# E12 + GEMM DMA sites reordered (m0 write before the address add) so the s_nop wait state is replaced by useful work: 97 s_nop removed
# baseline (speedup 1.0000x reference)
; #define PG8_STAGE(bufoff, gbase, voff) do { _Pragma("unroll") for (int _i = 0; _i < 2; ++_i) \
;         __builtin_amdgcn_global_load_lds((const unsigned*)((const char*)(gbase) + (voff)[_i]), (PG8_LAS unsigned*)(lds + (bufoff) + ldsw + _i * 8192), 16, 0, 0); } while (0)
; #define PG8_LDA(dst, b, h) do { _Pragma("unroll") for (int m = 0; m < 4; ++m) _Pragma("unroll") for (int k = 0; k < 2; ++k) dst[m][k] = *(const PG8_LAS bf16x8*)(lds + PG8_SA(b, h) + aoff + m * 2048 + k * 1024); } while (0)
; #define PG8_LDB(dst, b, h) do { _Pragma("unroll") for (int n = 0; n < 2; ++n) _Pragma("unroll") for (int k = 0; k < 2; ++k) dst[n][k] = *(const PG8_LAS bf16x8*)(lds + PG8_SB(b, h) + boff + n * 2048 + k * 1024); } while (0)
; #define PG8_MMA(ai, bj, At, Bt) do { __builtin_amdgcn_s_setprio(1); _Pragma("unroll") for (int m = 0; m < 4; ++m) _Pragma("unroll") for (int n = 0; n < 2; ++n) _Pragma("unroll") for (int k = 0; k < 2; ++k) \
;         acc[ai][bj][m][n] = __builtin_amdgcn_mfma_f32_16x16x32_bf16(Bt[n][k], At[m][k], acc[ai][bj][m][n], 0, 0, 0); __builtin_amdgcn_s_setprio(0); } while (0)
; #define PG8_WAIT_V(n) asm volatile("s_waitcnt vmcnt(" #n ")" ::: "memory")
; #define PG8_WAIT_L(n) asm volatile("s_waitcnt lgkmcnt(" #n ")" ::: "memory")
; #define PG8_BAR __builtin_amdgcn_s_barrier()
; #define PG8_SCHED __builtin_amdgcn_sched_barrier(0)
; template <class Epi, class Sched, bool ALIGN_EPI = false, bool SP2 = false>
; __device__ __forceinline__ void gemm_phase(PG8_LAS unsigned char* lds, const Gemm g, const Sched& S, const Epi& E) {
;     ...
;         for (int t = 0; t < nt; t += 2) {
;             const bool last = (t == nt - 2);
;             const char* a1 = cA + (size_t)(t + 1) * kstep;
;             const char* a2 = last ? nA : cA + (size_t)(t + 2) * kstep; const char* b2 = last ? nB : cB + (size_t)(t + 2) * kstep;
;             const char* a3 = a2 + kstep; const char* b3 = b2 + kstep;
;             if (last && has_next) S.a_ready(nxt);
;             if constexpr (SP2) {
;             PG8_LDB(B0, 0, 0); PG8_LDB(B1, 0, 1); PG8_SCHED; PG8_LDA(At, 0, 0); PG8_STAGE(PG8_SA(1, 1), a1 + hstep, voffA);
;             PG8_WAIT_V(8); PG8_WAIT_L(0); PG8_BAR; PG8_MMA(0, 0, At, B0); PG8_MMA(0, 1, At, B1); PG8_BAR; PG8_SCHED;
;             PG8_LDA(At, 0, 1); PG8_STAGE(PG8_SB(0, 0), b2, voffB); PG8_STAGE(PG8_SB(0, 1), b2 + hstep, voffB); PG8_STAGE(PG8_SA(0, 0), a2, voffA);
.LBB0_124:
	ds_read_b128 v[144:147], v151
	ds_read_b128 v[154:157], v151 offset:1024
	ds_read_b128 v[158:161], v151 offset:2048
	ds_read_b128 v[162:165], v151 offset:3072
	ds_read_b128 v[166:169], v152
	ds_read_b128 v[170:173], v152 offset:1024
	ds_read_b128 v[174:177], v152 offset:2048
	ds_read_b128 v[178:181], v152 offset:3072
	s_add_u32 s22, s20, 0xfffc0080
	s_addc_u32 s23, s21, -1
	s_cmp_eq_u32 s49, 12
	s_cselect_b32 s25, s13, s23
	s_cselect_b32 s24, s45, s22
	s_cselect_b32 s23, s11, s48
	s_cselect_b32 s22, s46, s47
	v_lshl_add_u64 v[182:183], s[20:21], 0, v[138:139]
	s_add_i32 m0, s19, 0xc000
	ds_read_b128 v[186:189], v153
	ds_read_b128 v[190:193], v153 offset:1024
	ds_read_b128 v[194:197], v153 offset:2048
	ds_read_b128 v[198:201], v153 offset:3072
	ds_read_b128 v[202:205], v153 offset:4096
	ds_read_b128 v[206:209], v153 offset:5120
	ds_read_b128 v[210:213], v153 offset:6144
	ds_read_b128 v[214:217], v153 offset:7168
	global_load_lds_dwordx4 v[182:183], off
	s_add_i32 m0, s19, 0xe000
	v_lshl_add_u64 v[182:183], s[20:21], 0, v[136:137]
	global_load_lds_dwordx4 v[182:183], off
	s_waitcnt vmcnt(8)
	s_waitcnt lgkmcnt(0)
	s_barrier
	s_setprio 1
	s_waitcnt lgkmcnt(0)
	v_mfma_f32_16x16x32_bf16 v[124:127], v[144:147], v[186:189], v[124:127]
	v_mfma_f32_16x16x32_bf16 v[116:119], v[158:161], v[186:189], v[116:119]
	v_mfma_f32_16x16x32_bf16 v[108:111], v[144:147], v[194:197], v[108:111]
	v_mfma_f32_16x16x32_bf16 v[100:103], v[158:161], v[194:197], v[100:103]
	v_mfma_f32_16x16x32_bf16 v[92:95], v[144:147], v[202:205], v[92:95]
	v_mfma_f32_16x16x32_bf16 v[84:87], v[158:161], v[202:205], v[84:87]
	v_mfma_f32_16x16x32_bf16 v[76:79], v[144:147], v[210:213], v[76:79]
	v_mfma_f32_16x16x32_bf16 v[68:71], v[158:161], v[210:213], v[68:71]
	v_mfma_f32_16x16x32_bf16 v[124:127], v[154:157], v[190:193], v[124:127]
	v_mfma_f32_16x16x32_bf16 v[116:119], v[162:165], v[190:193], v[116:119]
	v_mfma_f32_16x16x32_bf16 v[108:111], v[154:157], v[198:201], v[108:111]
	v_mfma_f32_16x16x32_bf16 v[100:103], v[162:165], v[198:201], v[100:103]
	v_mfma_f32_16x16x32_bf16 v[92:95], v[154:157], v[206:209], v[92:95]
	v_mfma_f32_16x16x32_bf16 v[84:87], v[162:165], v[206:209], v[84:87]
	v_mfma_f32_16x16x32_bf16 v[76:79], v[154:157], v[214:217], v[76:79]
	v_mfma_f32_16x16x32_bf16 v[68:71], v[162:165], v[214:217], v[68:71]
	s_setprio 0
	s_setprio 1
	v_mfma_f32_16x16x32_bf16 v[120:123], v[166:169], v[186:189], v[120:123]
	v_mfma_f32_16x16x32_bf16 v[112:115], v[174:177], v[186:189], v[112:115]
	v_mfma_f32_16x16x32_bf16 v[104:107], v[166:169], v[194:197], v[104:107]
	v_mfma_f32_16x16x32_bf16 v[96:99], v[174:177], v[194:197], v[96:99]
	v_mfma_f32_16x16x32_bf16 v[88:91], v[166:169], v[202:205], v[88:91]
	v_mfma_f32_16x16x32_bf16 v[80:83], v[174:177], v[202:205], v[80:83]
	v_mfma_f32_16x16x32_bf16 v[72:75], v[166:169], v[210:213], v[72:75]
	v_mfma_f32_16x16x32_bf16 v[64:67], v[174:177], v[210:213], v[64:67]
	v_mfma_f32_16x16x32_bf16 v[120:123], v[170:173], v[190:193], v[120:123]
	v_mfma_f32_16x16x32_bf16 v[112:115], v[178:181], v[190:193], v[112:115]
	v_mfma_f32_16x16x32_bf16 v[104:107], v[170:173], v[198:201], v[104:107]
	v_mfma_f32_16x16x32_bf16 v[96:99], v[178:181], v[198:201], v[96:99]
	v_mfma_f32_16x16x32_bf16 v[88:91], v[170:173], v[206:209], v[88:91]
	v_mfma_f32_16x16x32_bf16 v[80:83], v[178:181], v[206:209], v[80:83]
	v_mfma_f32_16x16x32_bf16 v[72:75], v[170:173], v[214:217], v[72:75]
	v_mfma_f32_16x16x32_bf16 v[64:67], v[178:181], v[214:217], v[64:67]
	s_setprio 0
	s_barrier
	s_add_i32 s50, s41, s31
	v_lshl_add_u64 v[182:183], s[22:23], 0, v[130:131]
	s_mov_b32 m0, s50
	ds_read_b128 v[186:189], v153 offset:16384
	ds_read_b128 v[190:193], v153 offset:17408
	ds_read_b128 v[194:197], v153 offset:18432
	ds_read_b128 v[198:201], v153 offset:19456
	ds_read_b128 v[202:205], v153 offset:20480
	ds_read_b128 v[206:209], v153 offset:21504
	ds_read_b128 v[210:213], v153 offset:22528
	ds_read_b128 v[214:217], v153 offset:23552
	global_load_lds_dwordx4 v[182:183], off
	s_add_i32 m0, s50, 0x2000
	s_add_u32 s50, s22, 0x40000
	v_lshl_add_u64 v[218:219], s[22:23], 0, v[134:135]
	s_addc_u32 s51, s23, 0
	s_add_i32 s52, s42, s31
	global_load_lds_dwordx4 v[218:219], off
	v_lshl_add_u64 v[220:221], s[50:51], 0, v[130:131]
	s_mov_b32 m0, s52
	v_lshl_add_u64 v[222:223], s[24:25], 0, v[132:133]
	global_load_lds_dwordx4 v[220:221], off
	s_add_i32 m0, s52, 0x2000
	v_lshl_add_u64 v[220:221], s[50:51], 0, v[134:135]
	global_load_lds_dwordx4 v[220:221], off
	s_mov_b32 m0, s19
	v_lshl_add_u64 v[220:221], s[24:25], 0, v[128:129]
	global_load_lds_dwordx4 v[220:221], off
	s_mov_b32 m0, s33
	s_nop 0
	global_load_lds_dwordx4 v[222:223], off
	s_waitcnt vmcnt(8)
	s_waitcnt lgkmcnt(0)
	s_barrier
; #define PG8_STAGE(bufoff, gbase, voff) do { _Pragma("unroll") for (int _i = 0; _i < 2; ++_i) \
;         __builtin_amdgcn_global_load_lds((const unsigned*)((const char*)(gbase) + (voff)[_i]), (PG8_LAS unsigned*)(lds + (bufoff) + ldsw + _i * 8192), 16, 0, 0); } while (0)
; #define PG8_LDA(dst, b, h) do { _Pragma("unroll") for (int m = 0; m < 4; ++m) _Pragma("unroll") for (int k = 0; k < 2; ++k) dst[m][k] = *(const PG8_LAS bf16x8*)(lds + PG8_SA(b, h) + aoff + m * 2048 + k * 1024); } while (0)
; #define PG8_LDB(dst, b, h) do { _Pragma("unroll") for (int n = 0; n < 2; ++n) _Pragma("unroll") for (int k = 0; k < 2; ++k) dst[n][k] = *(const PG8_LAS bf16x8*)(lds + PG8_SB(b, h) + boff + n * 2048 + k * 1024); } while (0)
; #define PG8_MMA(ai, bj, At, Bt) do { __builtin_amdgcn_s_setprio(1); _Pragma("unroll") for (int m = 0; m < 4; ++m) _Pragma("unroll") for (int n = 0; n < 2; ++n) _Pragma("unroll") for (int k = 0; k < 2; ++k) \
;         acc[ai][bj][m][n] = __builtin_amdgcn_mfma_f32_16x16x32_bf16(Bt[n][k], At[m][k], acc[ai][bj][m][n], 0, 0, 0); __builtin_amdgcn_s_setprio(0); } while (0)
; #define PG8_WAIT_V(n) asm volatile("s_waitcnt vmcnt(" #n ")" ::: "memory")
; #define PG8_WAIT_L(n) asm volatile("s_waitcnt lgkmcnt(" #n ")" ::: "memory")
; #define PG8_BAR __builtin_amdgcn_s_barrier()
; #define PG8_SCHED __builtin_amdgcn_sched_barrier(0)
; template <class Epi, class Sched, bool ALIGN_EPI = false, bool SP2 = false>
; __device__ __forceinline__ void gemm_phase(PG8_LAS unsigned char* lds, const Gemm g, const Sched& S, const Epi& E) {
;     ...
;             PG8_WAIT_V(8); PG8_WAIT_L(0); PG8_BAR; PG8_MMA(1, 0, At, B0); PG8_MMA(1, 1, At, B1); PG8_BAR; PG8_SCHED;
;             PG8_LDB(B0, 1, 0); PG8_LDB(B1, 1, 1); PG8_SCHED; PG8_LDA(At, 1, 0); PG8_STAGE(PG8_SA(0, 1), a2 + hstep, voffA);
;             PG8_WAIT_V(8); PG8_WAIT_L(0); PG8_BAR; PG8_MMA(0, 0, At, B0); PG8_MMA(0, 1, At, B1); PG8_BAR; PG8_SCHED;
	s_setprio 1
	s_waitcnt lgkmcnt(0)
	v_mfma_f32_16x16x32_bf16 v[60:63], v[144:147], v[186:189], v[60:63]
	v_mfma_f32_16x16x32_bf16 v[52:55], v[158:161], v[186:189], v[52:55]
	v_mfma_f32_16x16x32_bf16 v[44:47], v[144:147], v[194:197], v[44:47]
	v_mfma_f32_16x16x32_bf16 v[36:39], v[158:161], v[194:197], v[36:39]
	v_mfma_f32_16x16x32_bf16 v[28:31], v[144:147], v[202:205], v[28:31]
	v_mfma_f32_16x16x32_bf16 v[20:23], v[158:161], v[202:205], v[20:23]
	v_mfma_f32_16x16x32_bf16 v[12:15], v[144:147], v[210:213], v[12:15]
	v_mfma_f32_16x16x32_bf16 v[4:7], v[158:161], v[210:213], v[4:7]
	v_mfma_f32_16x16x32_bf16 v[60:63], v[154:157], v[190:193], v[60:63]
	v_mfma_f32_16x16x32_bf16 v[52:55], v[162:165], v[190:193], v[52:55]
	v_mfma_f32_16x16x32_bf16 v[44:47], v[154:157], v[198:201], v[44:47]
	v_mfma_f32_16x16x32_bf16 v[36:39], v[162:165], v[198:201], v[36:39]
	v_mfma_f32_16x16x32_bf16 v[28:31], v[154:157], v[206:209], v[28:31]
	v_mfma_f32_16x16x32_bf16 v[20:23], v[162:165], v[206:209], v[20:23]
	v_mfma_f32_16x16x32_bf16 v[12:15], v[154:157], v[214:217], v[12:15]
	v_mfma_f32_16x16x32_bf16 v[4:7], v[162:165], v[214:217], v[4:7]
	s_setprio 0
	s_setprio 1
	v_mfma_f32_16x16x32_bf16 v[56:59], v[166:169], v[186:189], v[56:59]
	v_mfma_f32_16x16x32_bf16 v[48:51], v[174:177], v[186:189], v[48:51]
	v_mfma_f32_16x16x32_bf16 v[40:43], v[166:169], v[194:197], v[40:43]
	v_mfma_f32_16x16x32_bf16 v[32:35], v[174:177], v[194:197], v[32:35]
	v_mfma_f32_16x16x32_bf16 v[24:27], v[166:169], v[202:205], v[24:27]
	v_mfma_f32_16x16x32_bf16 v[16:19], v[174:177], v[202:205], v[16:19]
	v_mfma_f32_16x16x32_bf16 v[8:11], v[166:169], v[210:213], v[8:11]
	v_mfma_f32_16x16x32_bf16 v[0:3], v[174:177], v[210:213], v[0:3]
	v_mfma_f32_16x16x32_bf16 v[56:59], v[170:173], v[190:193], v[56:59]
	v_mfma_f32_16x16x32_bf16 v[48:51], v[178:181], v[190:193], v[48:51]
	v_mfma_f32_16x16x32_bf16 v[40:43], v[170:173], v[198:201], v[40:43]
	v_mfma_f32_16x16x32_bf16 v[32:35], v[178:181], v[198:201], v[32:35]
	v_mfma_f32_16x16x32_bf16 v[24:27], v[170:173], v[206:209], v[24:27]
	v_mfma_f32_16x16x32_bf16 v[16:19], v[178:181], v[206:209], v[16:19]
	v_mfma_f32_16x16x32_bf16 v[8:11], v[170:173], v[214:217], v[8:11]
	v_mfma_f32_16x16x32_bf16 v[0:3], v[178:181], v[214:217], v[0:3]
	s_setprio 0
	s_barrier
	s_add_i32 s50, 0, 0x18000
	s_add_i32 s51, 0, 0x1c000
	v_add_u32_e32 v162, s50, v149
	v_add_u32_e32 v178, s51, v149
	ds_read_b128 v[144:147], v162
	ds_read_b128 v[154:157], v162 offset:1024
	ds_read_b128 v[158:161], v162 offset:2048
	ds_read_b128 v[162:165], v162 offset:3072
	ds_read_b128 v[166:169], v178
	ds_read_b128 v[170:173], v178 offset:1024
	ds_read_b128 v[174:177], v178 offset:2048
	ds_read_b128 v[178:181], v178 offset:3072
	s_add_u32 s24, s24, 0x40000
	s_addc_u32 s25, s25, 0
	s_mov_b32 m0, s34
	v_lshl_add_u64 v[224:225], s[24:25], 0, v[128:129]
	ds_read_b128 v[186:189], v153 offset:32768
	ds_read_b128 v[190:193], v153 offset:33792
	ds_read_b128 v[194:197], v153 offset:34816
	ds_read_b128 v[198:201], v153 offset:35840
	ds_read_b128 v[202:205], v153 offset:36864
	ds_read_b128 v[206:209], v153 offset:37888
	ds_read_b128 v[210:213], v153 offset:38912
	ds_read_b128 v[214:217], v153 offset:39936
	global_load_lds_dwordx4 v[224:225], off
	s_mov_b32 m0, s35
	v_lshl_add_u64 v[224:225], s[24:25], 0, v[132:133]
	global_load_lds_dwordx4 v[224:225], off
	s_waitcnt vmcnt(8)
	s_waitcnt lgkmcnt(0)
	s_barrier
	s_setprio 1
	s_waitcnt lgkmcnt(0)
	v_mfma_f32_16x16x32_bf16 v[124:127], v[144:147], v[186:189], v[124:127]
	v_mfma_f32_16x16x32_bf16 v[116:119], v[158:161], v[186:189], v[116:119]
	v_mfma_f32_16x16x32_bf16 v[108:111], v[144:147], v[194:197], v[108:111]
	v_mfma_f32_16x16x32_bf16 v[100:103], v[158:161], v[194:197], v[100:103]
	v_mfma_f32_16x16x32_bf16 v[92:95], v[144:147], v[202:205], v[92:95]
	v_mfma_f32_16x16x32_bf16 v[84:87], v[158:161], v[202:205], v[84:87]
	v_mfma_f32_16x16x32_bf16 v[76:79], v[144:147], v[210:213], v[76:79]
	v_mfma_f32_16x16x32_bf16 v[68:71], v[158:161], v[210:213], v[68:71]
	v_mfma_f32_16x16x32_bf16 v[124:127], v[154:157], v[190:193], v[124:127]
	v_mfma_f32_16x16x32_bf16 v[116:119], v[162:165], v[190:193], v[116:119]
	v_mfma_f32_16x16x32_bf16 v[108:111], v[154:157], v[198:201], v[108:111]
	v_mfma_f32_16x16x32_bf16 v[100:103], v[162:165], v[198:201], v[100:103]
	v_mfma_f32_16x16x32_bf16 v[92:95], v[154:157], v[206:209], v[92:95]
	v_mfma_f32_16x16x32_bf16 v[84:87], v[162:165], v[206:209], v[84:87]
	v_mfma_f32_16x16x32_bf16 v[76:79], v[154:157], v[214:217], v[76:79]
	v_mfma_f32_16x16x32_bf16 v[68:71], v[162:165], v[214:217], v[68:71]
	s_setprio 0
	s_setprio 1
	v_mfma_f32_16x16x32_bf16 v[120:123], v[166:169], v[186:189], v[120:123]
	v_mfma_f32_16x16x32_bf16 v[112:115], v[174:177], v[186:189], v[112:115]
	v_mfma_f32_16x16x32_bf16 v[104:107], v[166:169], v[194:197], v[104:107]
	v_mfma_f32_16x16x32_bf16 v[96:99], v[174:177], v[194:197], v[96:99]
	v_mfma_f32_16x16x32_bf16 v[88:91], v[166:169], v[202:205], v[88:91]
	v_mfma_f32_16x16x32_bf16 v[80:83], v[174:177], v[202:205], v[80:83]
	v_mfma_f32_16x16x32_bf16 v[72:75], v[166:169], v[210:213], v[72:75]
	v_mfma_f32_16x16x32_bf16 v[64:67], v[174:177], v[210:213], v[64:67]
	v_mfma_f32_16x16x32_bf16 v[120:123], v[170:173], v[190:193], v[120:123]
	v_mfma_f32_16x16x32_bf16 v[112:115], v[178:181], v[190:193], v[112:115]
	v_mfma_f32_16x16x32_bf16 v[104:107], v[170:173], v[198:201], v[104:107]
	v_mfma_f32_16x16x32_bf16 v[96:99], v[178:181], v[198:201], v[96:99]
	v_mfma_f32_16x16x32_bf16 v[88:91], v[170:173], v[206:209], v[88:91]
	v_mfma_f32_16x16x32_bf16 v[80:83], v[178:181], v[206:209], v[80:83]
	v_mfma_f32_16x16x32_bf16 v[72:75], v[170:173], v[214:217], v[72:75]
	v_mfma_f32_16x16x32_bf16 v[64:67], v[178:181], v[214:217], v[64:67]
	s_setprio 0
	s_barrier
; #define PG8_STAGE(bufoff, gbase, voff) do { _Pragma("unroll") for (int _i = 0; _i < 2; ++_i) \
;         __builtin_amdgcn_global_load_lds((const unsigned*)((const char*)(gbase) + (voff)[_i]), (PG8_LAS unsigned*)(lds + (bufoff) + ldsw + _i * 8192), 16, 0, 0); } while (0)
; #define PG8_LDA(dst, b, h) do { _Pragma("unroll") for (int m = 0; m < 4; ++m) _Pragma("unroll") for (int k = 0; k < 2; ++k) dst[m][k] = *(const PG8_LAS bf16x8*)(lds + PG8_SA(b, h) + aoff + m * 2048 + k * 1024); } while (0)
; #define PG8_MMA(ai, bj, At, Bt) do { __builtin_amdgcn_s_setprio(1); _Pragma("unroll") for (int m = 0; m < 4; ++m) _Pragma("unroll") for (int n = 0; n < 2; ++n) _Pragma("unroll") for (int k = 0; k < 2; ++k) \
;         acc[ai][bj][m][n] = __builtin_amdgcn_mfma_f32_16x16x32_bf16(Bt[n][k], At[m][k], acc[ai][bj][m][n], 0, 0, 0); __builtin_amdgcn_s_setprio(0); } while (0)
; #define PG8_WAIT_V(n) asm volatile("s_waitcnt vmcnt(" #n ")" ::: "memory")
; #define PG8_WAIT_L(n) asm volatile("s_waitcnt lgkmcnt(" #n ")" ::: "memory")
; #define PG8_BAR __builtin_amdgcn_s_barrier()
; #define PG8_SCHED __builtin_amdgcn_sched_barrier(0)
; template <class Epi, class Sched, bool ALIGN_EPI = false, bool SP2 = false>
; __device__ __forceinline__ void gemm_phase(PG8_LAS unsigned char* lds, const Gemm g, const Sched& S, const Epi& E) {
;     ...
;         for (int t = 0; t < nt; t += 2) {
;             const bool last = (t == nt - 2);
;             const char* a1 = cA + (size_t)(t + 1) * kstep;
;             const char* a2 = last ? nA : cA + (size_t)(t + 2) * kstep; const char* b2 = last ? nB : cB + (size_t)(t + 2) * kstep;
;             const char* a3 = a2 + kstep; const char* b3 = b2 + kstep;
;     ...
;             PG8_LDA(At, 1, 1); PG8_STAGE(PG8_SB(1, 0), b3, voffB); PG8_STAGE(PG8_SB(1, 1), b3 + hstep, voffB); PG8_STAGE(PG8_SA(1, 0), a3, voffA);
;             PG8_WAIT_V(8); PG8_WAIT_L(0); PG8_BAR; PG8_MMA(1, 0, At, B0); PG8_MMA(1, 1, At, B1); PG8_BAR; PG8_SCHED;
	s_add_i32 s24, s50, s31
	v_lshl_add_u64 v[182:183], v[182:183], 0, s[6:7]
	s_mov_b32 m0, s24
	ds_read_b128 v[186:189], v153 offset:49152
	ds_read_b128 v[190:193], v153 offset:50176
	ds_read_b128 v[194:197], v153 offset:51200
	ds_read_b128 v[198:201], v153 offset:52224
	ds_read_b128 v[202:205], v153 offset:53248
	ds_read_b128 v[206:209], v153 offset:54272
	ds_read_b128 v[210:213], v153 offset:55296
	ds_read_b128 v[214:217], v153 offset:56320
	global_load_lds_dwordx4 v[182:183], off
	s_add_i32 m0, s24, 0x2000
	s_add_u32 s22, s22, 0x40080
	v_lshl_add_u64 v[182:183], v[218:219], 0, s[6:7]
	s_addc_u32 s23, s23, 0
	s_add_i32 s24, s51, s31
	global_load_lds_dwordx4 v[182:183], off
	s_mov_b32 m0, s24
	v_lshl_add_u64 v[182:183], s[22:23], 0, v[130:131]
	global_load_lds_dwordx4 v[182:183], off
	s_add_i32 m0, s24, 0x2000
	v_lshl_add_u64 v[182:183], s[22:23], 0, v[134:135]
	global_load_lds_dwordx4 v[182:183], off
	s_mov_b32 m0, s37
	v_lshl_add_u64 v[182:183], v[220:221], 0, s[6:7]
	global_load_lds_dwordx4 v[182:183], off
	s_mov_b32 m0, s38
	v_lshl_add_u64 v[182:183], v[222:223], 0, s[6:7]
	global_load_lds_dwordx4 v[182:183], off
	s_waitcnt vmcnt(8)
	s_waitcnt lgkmcnt(0)
	s_barrier
	s_setprio 1
	s_waitcnt lgkmcnt(0)
	v_mfma_f32_16x16x32_bf16 v[60:63], v[144:147], v[186:189], v[60:63]
	v_mfma_f32_16x16x32_bf16 v[52:55], v[158:161], v[186:189], v[52:55]
	v_mfma_f32_16x16x32_bf16 v[44:47], v[144:147], v[194:197], v[44:47]
	v_mfma_f32_16x16x32_bf16 v[36:39], v[158:161], v[194:197], v[36:39]
	v_mfma_f32_16x16x32_bf16 v[28:31], v[144:147], v[202:205], v[28:31]
	v_mfma_f32_16x16x32_bf16 v[20:23], v[158:161], v[202:205], v[20:23]
	v_mfma_f32_16x16x32_bf16 v[12:15], v[144:147], v[210:213], v[12:15]
	v_mfma_f32_16x16x32_bf16 v[4:7], v[158:161], v[210:213], v[4:7]
	v_mfma_f32_16x16x32_bf16 v[60:63], v[154:157], v[190:193], v[60:63]
	v_mfma_f32_16x16x32_bf16 v[52:55], v[162:165], v[190:193], v[52:55]
	v_mfma_f32_16x16x32_bf16 v[44:47], v[154:157], v[198:201], v[44:47]
	v_mfma_f32_16x16x32_bf16 v[36:39], v[162:165], v[198:201], v[36:39]
	v_mfma_f32_16x16x32_bf16 v[28:31], v[154:157], v[206:209], v[28:31]
	v_mfma_f32_16x16x32_bf16 v[20:23], v[162:165], v[206:209], v[20:23]
	v_mfma_f32_16x16x32_bf16 v[12:15], v[154:157], v[214:217], v[12:15]
	v_mfma_f32_16x16x32_bf16 v[4:7], v[162:165], v[214:217], v[4:7]
	s_setprio 0
	s_setprio 1
	v_mfma_f32_16x16x32_bf16 v[56:59], v[166:169], v[186:189], v[56:59]
	v_mfma_f32_16x16x32_bf16 v[48:51], v[174:177], v[186:189], v[48:51]
	v_mfma_f32_16x16x32_bf16 v[40:43], v[166:169], v[194:197], v[40:43]
	v_mfma_f32_16x16x32_bf16 v[32:35], v[174:177], v[194:197], v[32:35]
	v_mfma_f32_16x16x32_bf16 v[24:27], v[166:169], v[202:205], v[24:27]
	v_mfma_f32_16x16x32_bf16 v[16:19], v[174:177], v[202:205], v[16:19]
	v_mfma_f32_16x16x32_bf16 v[8:11], v[166:169], v[210:213], v[8:11]
	v_mfma_f32_16x16x32_bf16 v[0:3], v[174:177], v[210:213], v[0:3]
	v_mfma_f32_16x16x32_bf16 v[56:59], v[170:173], v[190:193], v[56:59]
	v_mfma_f32_16x16x32_bf16 v[48:51], v[178:181], v[190:193], v[48:51]
	v_mfma_f32_16x16x32_bf16 v[40:43], v[170:173], v[198:201], v[40:43]
	v_mfma_f32_16x16x32_bf16 v[32:35], v[178:181], v[198:201], v[32:35]
	v_mfma_f32_16x16x32_bf16 v[24:27], v[170:173], v[206:209], v[24:27]
	v_mfma_f32_16x16x32_bf16 v[16:19], v[178:181], v[206:209], v[16:19]
	v_mfma_f32_16x16x32_bf16 v[8:11], v[170:173], v[214:217], v[8:11]
	v_mfma_f32_16x16x32_bf16 v[0:3], v[178:181], v[214:217], v[0:3]
	s_setprio 0
	s_barrier
	s_add_i32 s49, s49, 2
	s_add_u32 s47, s47, 0x100
	s_addc_u32 s48, s48, 0
	s_add_u32 s20, s20, 0x100
	s_addc_u32 s21, s21, 0
	s_cmp_gt_u32 s49, 13
	s_cbranch_scc0 .LBB0_124
	s_and_b64 vcc, exec, s[8:9]
	s_cbranch_vccz .LBB0_127
	s_barrier

; #define PG8_STAGE(bufoff, gbase, voff) do { _Pragma("unroll") for (int _i = 0; _i < 2; ++_i) \
;         __builtin_amdgcn_global_load_lds((const unsigned*)((const char*)(gbase) + (voff)[_i]), (PG8_LAS unsigned*)(lds + (bufoff) + ldsw + _i * 8192), 16, 0, 0); } while (0)
; #define PG8_LDA(dst, b, h) do { _Pragma("unroll") for (int m = 0; m < 4; ++m) _Pragma("unroll") for (int k = 0; k < 2; ++k) dst[m][k] = *(const PG8_LAS bf16x8*)(lds + PG8_SA(b, h) + aoff + m * 2048 + k * 1024); } while (0)
; #define PG8_LDB(dst, b, h) do { _Pragma("unroll") for (int n = 0; n < 2; ++n) _Pragma("unroll") for (int k = 0; k < 2; ++k) dst[n][k] = *(const PG8_LAS bf16x8*)(lds + PG8_SB(b, h) + boff + n * 2048 + k * 1024); } while (0)
; #define PG8_MMA(ai, bj, At, Bt) do { __builtin_amdgcn_s_setprio(1); _Pragma("unroll") for (int m = 0; m < 4; ++m) _Pragma("unroll") for (int n = 0; n < 2; ++n) _Pragma("unroll") for (int k = 0; k < 2; ++k) \
;         acc[ai][bj][m][n] = __builtin_amdgcn_mfma_f32_16x16x32_bf16(Bt[n][k], At[m][k], acc[ai][bj][m][n], 0, 0, 0); __builtin_amdgcn_s_setprio(0); } while (0)
; #define PG8_WAIT_V(n) asm volatile("s_waitcnt vmcnt(" #n ")" ::: "memory")
; #define PG8_WAIT_L(n) asm volatile("s_waitcnt lgkmcnt(" #n ")" ::: "memory")
; #define PG8_BAR __builtin_amdgcn_s_barrier()
; #define PG8_SCHED __builtin_amdgcn_sched_barrier(0)
; template <class Epi, class Sched, bool ALIGN_EPI = false, bool SP2 = false>
; __device__ __forceinline__ void gemm_phase(PG8_LAS unsigned char* lds, const Gemm g, const Sched& S, const Epi& E) {
;     ...
;         for (int t = 0; t < nt; t += 2) {
;             const bool last = (t == nt - 2);
;             const char* a1 = cA + (size_t)(t + 1) * kstep;
;             const char* a2 = last ? nA : cA + (size_t)(t + 2) * kstep; const char* b2 = last ? nB : cB + (size_t)(t + 2) * kstep;
;             const char* a3 = a2 + kstep; const char* b3 = b2 + kstep;
;             if (last && has_next) S.a_ready(nxt);
;             if constexpr (SP2) {
;             PG8_LDB(B0, 0, 0); PG8_LDB(B1, 0, 1); PG8_SCHED; PG8_LDA(At, 0, 0); PG8_STAGE(PG8_SA(1, 1), a1 + hstep, voffA);
;             PG8_WAIT_V(8); PG8_WAIT_L(0); PG8_BAR; PG8_MMA(0, 0, At, B0); PG8_MMA(0, 1, At, B1); PG8_BAR; PG8_SCHED;
;             PG8_LDA(At, 0, 1); PG8_STAGE(PG8_SB(0, 0), b2, voffB); PG8_STAGE(PG8_SB(0, 1), b2 + hstep, voffB); PG8_STAGE(PG8_SA(0, 0), a2, voffA);
.LBB0_196:
	ds_read_b128 v[152:155], v149
	ds_read_b128 v[156:159], v149 offset:1024
	ds_read_b128 v[160:163], v149 offset:2048
	ds_read_b128 v[164:167], v149 offset:3072
	ds_read_b128 v[168:171], v150
	ds_read_b128 v[172:175], v150 offset:1024
	ds_read_b128 v[176:179], v150 offset:2048
	ds_read_b128 v[180:183], v150 offset:3072
	s_add_u32 s24, s22, 0x100
	s_addc_u32 s25, s23, 0
	s_cmp_eq_u32 s58, 40
	s_cselect_b32 s29, s5, s25
	s_cselect_b32 s28, s4, s24
	s_cselect_b32 s27, s21, s57
	s_cselect_b32 s26, s20, s56
	v_lshl_add_u64 v[144:145], s[22:23], 0, v[138:139]
	s_add_i32 m0, s37, 0xc000
	ds_read_b128 v[186:189], v151
	ds_read_b128 v[190:193], v151 offset:1024
	ds_read_b128 v[194:197], v151 offset:2048
	ds_read_b128 v[198:201], v151 offset:3072
	ds_read_b128 v[202:205], v151 offset:4096
	ds_read_b128 v[206:209], v151 offset:5120
	ds_read_b128 v[210:213], v151 offset:6144
	ds_read_b128 v[214:217], v151 offset:7168
	global_load_lds_dwordx4 v[144:145], off
	s_add_i32 m0, s37, 0xe000
	v_lshl_add_u64 v[144:145], s[22:23], 0, v[136:137]
	global_load_lds_dwordx4 v[144:145], off
	s_waitcnt vmcnt(8)
	s_waitcnt lgkmcnt(0)
	s_barrier
	s_setprio 1
	s_waitcnt lgkmcnt(0)
	v_mfma_f32_16x16x32_bf16 v[124:127], v[152:155], v[186:189], v[124:127]
	v_mfma_f32_16x16x32_bf16 v[120:123], v[160:163], v[186:189], v[120:123]
	v_mfma_f32_16x16x32_bf16 v[116:119], v[152:155], v[194:197], v[116:119]
	v_mfma_f32_16x16x32_bf16 v[108:111], v[160:163], v[194:197], v[108:111]
	v_mfma_f32_16x16x32_bf16 v[100:103], v[152:155], v[202:205], v[100:103]
	v_mfma_f32_16x16x32_bf16 v[92:95], v[160:163], v[202:205], v[92:95]
	v_mfma_f32_16x16x32_bf16 v[84:87], v[152:155], v[210:213], v[84:87]
	v_mfma_f32_16x16x32_bf16 v[76:79], v[160:163], v[210:213], v[76:79]
	v_mfma_f32_16x16x32_bf16 v[124:127], v[156:159], v[190:193], v[124:127]
	v_mfma_f32_16x16x32_bf16 v[120:123], v[164:167], v[190:193], v[120:123]
	v_mfma_f32_16x16x32_bf16 v[116:119], v[156:159], v[198:201], v[116:119]
	v_mfma_f32_16x16x32_bf16 v[108:111], v[164:167], v[198:201], v[108:111]
	v_mfma_f32_16x16x32_bf16 v[100:103], v[156:159], v[206:209], v[100:103]
	v_mfma_f32_16x16x32_bf16 v[92:95], v[164:167], v[206:209], v[92:95]
	v_mfma_f32_16x16x32_bf16 v[84:87], v[156:159], v[214:217], v[84:87]
	v_mfma_f32_16x16x32_bf16 v[76:79], v[164:167], v[214:217], v[76:79]
	s_setprio 0
	s_setprio 1
	v_mfma_f32_16x16x32_bf16 v[112:115], v[168:171], v[186:189], v[112:115]
	v_mfma_f32_16x16x32_bf16 v[104:107], v[176:179], v[186:189], v[104:107]
	v_mfma_f32_16x16x32_bf16 v[96:99], v[168:171], v[194:197], v[96:99]
	v_mfma_f32_16x16x32_bf16 v[88:91], v[176:179], v[194:197], v[88:91]
	v_mfma_f32_16x16x32_bf16 v[80:83], v[168:171], v[202:205], v[80:83]
	v_mfma_f32_16x16x32_bf16 v[72:75], v[176:179], v[202:205], v[72:75]
	v_mfma_f32_16x16x32_bf16 v[68:71], v[168:171], v[210:213], v[68:71]
	v_mfma_f32_16x16x32_bf16 v[64:67], v[176:179], v[210:213], v[64:67]
	v_mfma_f32_16x16x32_bf16 v[112:115], v[172:175], v[190:193], v[112:115]
	v_mfma_f32_16x16x32_bf16 v[104:107], v[180:183], v[190:193], v[104:107]
	v_mfma_f32_16x16x32_bf16 v[96:99], v[172:175], v[198:201], v[96:99]
	v_mfma_f32_16x16x32_bf16 v[88:91], v[180:183], v[198:201], v[88:91]
	v_mfma_f32_16x16x32_bf16 v[80:83], v[172:175], v[206:209], v[80:83]
	v_mfma_f32_16x16x32_bf16 v[72:75], v[180:183], v[206:209], v[72:75]
	v_mfma_f32_16x16x32_bf16 v[68:71], v[172:175], v[214:217], v[68:71]
	v_mfma_f32_16x16x32_bf16 v[64:67], v[180:183], v[214:217], v[64:67]
	s_setprio 0
	s_barrier
	s_add_i32 s22, s46, s36
	v_lshl_add_u64 v[144:145], s[26:27], 0, v[130:131]
	s_mov_b32 m0, s22
	ds_read_b128 v[186:189], v151 offset:16384
	ds_read_b128 v[190:193], v151 offset:17408
	ds_read_b128 v[194:197], v151 offset:18432
	ds_read_b128 v[198:201], v151 offset:19456
	ds_read_b128 v[202:205], v151 offset:20480
	ds_read_b128 v[206:209], v151 offset:21504
	ds_read_b128 v[210:213], v151 offset:22528
	ds_read_b128 v[214:217], v151 offset:23552
	global_load_lds_dwordx4 v[144:145], off
	s_add_i32 m0, s22, 0x2000
	s_add_u32 s22, s26, 0xb0000
	v_lshl_add_u64 v[218:219], s[26:27], 0, v[134:135]
	s_addc_u32 s23, s27, 0
	s_add_i32 s59, s47, s36
	global_load_lds_dwordx4 v[218:219], off
	v_lshl_add_u64 v[220:221], s[22:23], 0, v[130:131]
	s_mov_b32 m0, s59
	v_lshl_add_u64 v[222:223], s[28:29], 0, v[132:133]
	global_load_lds_dwordx4 v[220:221], off
	s_add_i32 m0, s59, 0x2000
	v_lshl_add_u64 v[220:221], s[22:23], 0, v[134:135]
	global_load_lds_dwordx4 v[220:221], off
	s_mov_b32 m0, s37
	v_lshl_add_u64 v[220:221], s[28:29], 0, v[128:129]
	global_load_lds_dwordx4 v[220:221], off
	s_mov_b32 m0, s38
	s_nop 0
	global_load_lds_dwordx4 v[222:223], off
	s_waitcnt vmcnt(8)
	s_waitcnt lgkmcnt(0)
	s_barrier
; #define PG8_STAGE(bufoff, gbase, voff) do { _Pragma("unroll") for (int _i = 0; _i < 2; ++_i) \
;         __builtin_amdgcn_global_load_lds((const unsigned*)((const char*)(gbase) + (voff)[_i]), (PG8_LAS unsigned*)(lds + (bufoff) + ldsw + _i * 8192), 16, 0, 0); } while (0)
; #define PG8_LDA(dst, b, h) do { _Pragma("unroll") for (int m = 0; m < 4; ++m) _Pragma("unroll") for (int k = 0; k < 2; ++k) dst[m][k] = *(const PG8_LAS bf16x8*)(lds + PG8_SA(b, h) + aoff + m * 2048 + k * 1024); } while (0)
; #define PG8_LDB(dst, b, h) do { _Pragma("unroll") for (int n = 0; n < 2; ++n) _Pragma("unroll") for (int k = 0; k < 2; ++k) dst[n][k] = *(const PG8_LAS bf16x8*)(lds + PG8_SB(b, h) + boff + n * 2048 + k * 1024); } while (0)
; #define PG8_MMA(ai, bj, At, Bt) do { __builtin_amdgcn_s_setprio(1); _Pragma("unroll") for (int m = 0; m < 4; ++m) _Pragma("unroll") for (int n = 0; n < 2; ++n) _Pragma("unroll") for (int k = 0; k < 2; ++k) \
;         acc[ai][bj][m][n] = __builtin_amdgcn_mfma_f32_16x16x32_bf16(Bt[n][k], At[m][k], acc[ai][bj][m][n], 0, 0, 0); __builtin_amdgcn_s_setprio(0); } while (0)
; #define PG8_WAIT_V(n) asm volatile("s_waitcnt vmcnt(" #n ")" ::: "memory")
; #define PG8_WAIT_L(n) asm volatile("s_waitcnt lgkmcnt(" #n ")" ::: "memory")
; #define PG8_BAR __builtin_amdgcn_s_barrier()
; #define PG8_SCHED __builtin_amdgcn_sched_barrier(0)
; template <class Epi, class Sched, bool ALIGN_EPI = false, bool SP2 = false>
; __device__ __forceinline__ void gemm_phase(PG8_LAS unsigned char* lds, const Gemm g, const Sched& S, const Epi& E) {
;     ...
;             PG8_WAIT_V(8); PG8_WAIT_L(0); PG8_BAR; PG8_MMA(1, 0, At, B0); PG8_MMA(1, 1, At, B1); PG8_BAR; PG8_SCHED;
;             PG8_LDB(B0, 1, 0); PG8_LDB(B1, 1, 1); PG8_SCHED; PG8_LDA(At, 1, 0); PG8_STAGE(PG8_SA(0, 1), a2 + hstep, voffA);
;             PG8_WAIT_V(8); PG8_WAIT_L(0); PG8_BAR; PG8_MMA(0, 0, At, B0); PG8_MMA(0, 1, At, B1); PG8_BAR; PG8_SCHED;
	s_setprio 1
	s_waitcnt lgkmcnt(0)
	v_mfma_f32_16x16x32_bf16 v[60:63], v[152:155], v[186:189], v[60:63]
	v_mfma_f32_16x16x32_bf16 v[56:59], v[160:163], v[186:189], v[56:59]
	v_mfma_f32_16x16x32_bf16 v[52:55], v[152:155], v[194:197], v[52:55]
	v_mfma_f32_16x16x32_bf16 v[44:47], v[160:163], v[194:197], v[44:47]
	v_mfma_f32_16x16x32_bf16 v[36:39], v[152:155], v[202:205], v[36:39]
	v_mfma_f32_16x16x32_bf16 v[28:31], v[160:163], v[202:205], v[28:31]
	v_mfma_f32_16x16x32_bf16 v[20:23], v[152:155], v[210:213], v[20:23]
	v_mfma_f32_16x16x32_bf16 v[12:15], v[160:163], v[210:213], v[12:15]
	v_mfma_f32_16x16x32_bf16 v[60:63], v[156:159], v[190:193], v[60:63]
	v_mfma_f32_16x16x32_bf16 v[56:59], v[164:167], v[190:193], v[56:59]
	v_mfma_f32_16x16x32_bf16 v[52:55], v[156:159], v[198:201], v[52:55]
	v_mfma_f32_16x16x32_bf16 v[44:47], v[164:167], v[198:201], v[44:47]
	v_mfma_f32_16x16x32_bf16 v[36:39], v[156:159], v[206:209], v[36:39]
	v_mfma_f32_16x16x32_bf16 v[28:31], v[164:167], v[206:209], v[28:31]
	v_mfma_f32_16x16x32_bf16 v[20:23], v[156:159], v[214:217], v[20:23]
	v_mfma_f32_16x16x32_bf16 v[12:15], v[164:167], v[214:217], v[12:15]
	s_setprio 0
	s_setprio 1
	v_mfma_f32_16x16x32_bf16 v[48:51], v[168:171], v[186:189], v[48:51]
	v_mfma_f32_16x16x32_bf16 v[40:43], v[176:179], v[186:189], v[40:43]
	v_mfma_f32_16x16x32_bf16 v[32:35], v[168:171], v[194:197], v[32:35]
	v_mfma_f32_16x16x32_bf16 v[24:27], v[176:179], v[194:197], v[24:27]
	v_mfma_f32_16x16x32_bf16 v[16:19], v[168:171], v[202:205], v[16:19]
	v_mfma_f32_16x16x32_bf16 v[8:11], v[176:179], v[202:205], v[8:11]
	v_mfma_f32_16x16x32_bf16 v[4:7], v[168:171], v[210:213], v[4:7]
	v_mfma_f32_16x16x32_bf16 v[0:3], v[176:179], v[210:213], v[0:3]
	v_mfma_f32_16x16x32_bf16 v[48:51], v[172:175], v[190:193], v[48:51]
	v_mfma_f32_16x16x32_bf16 v[40:43], v[180:183], v[190:193], v[40:43]
	v_mfma_f32_16x16x32_bf16 v[32:35], v[172:175], v[198:201], v[32:35]
	v_mfma_f32_16x16x32_bf16 v[24:27], v[180:183], v[198:201], v[24:27]
	v_mfma_f32_16x16x32_bf16 v[16:19], v[172:175], v[206:209], v[16:19]
	v_mfma_f32_16x16x32_bf16 v[8:11], v[180:183], v[206:209], v[8:11]
	v_mfma_f32_16x16x32_bf16 v[4:7], v[172:175], v[214:217], v[4:7]
	v_mfma_f32_16x16x32_bf16 v[0:3], v[180:183], v[214:217], v[0:3]
	s_setprio 0
	s_barrier
	s_add_i32 s59, 0, 0x18000
	s_add_i32 s60, 0, 0x1c000
	v_add_u32_e32 v164, s59, v147
	v_add_u32_e32 v180, s60, v147
	ds_read_b128 v[152:155], v164
	ds_read_b128 v[156:159], v164 offset:1024
	ds_read_b128 v[160:163], v164 offset:2048
	ds_read_b128 v[164:167], v164 offset:3072
	ds_read_b128 v[168:171], v180
	ds_read_b128 v[172:175], v180 offset:1024
	ds_read_b128 v[176:179], v180 offset:2048
	ds_read_b128 v[180:183], v180 offset:3072
	s_add_u32 s22, s28, 0xb0000
	s_addc_u32 s23, s29, 0
	s_mov_b32 m0, s39
	v_lshl_add_u64 v[224:225], s[22:23], 0, v[128:129]
	ds_read_b128 v[186:189], v151 offset:32768
	ds_read_b128 v[190:193], v151 offset:33792
	ds_read_b128 v[194:197], v151 offset:34816
	ds_read_b128 v[198:201], v151 offset:35840
	ds_read_b128 v[202:205], v151 offset:36864
	ds_read_b128 v[206:209], v151 offset:37888
	ds_read_b128 v[210:213], v151 offset:38912
	ds_read_b128 v[214:217], v151 offset:39936
	global_load_lds_dwordx4 v[224:225], off
	s_mov_b32 m0, s40
	v_lshl_add_u64 v[224:225], s[22:23], 0, v[132:133]
	global_load_lds_dwordx4 v[224:225], off
	s_waitcnt vmcnt(8)
	s_waitcnt lgkmcnt(0)
	s_barrier
	s_setprio 1
	s_waitcnt lgkmcnt(0)
	v_mfma_f32_16x16x32_bf16 v[124:127], v[152:155], v[186:189], v[124:127]
	v_mfma_f32_16x16x32_bf16 v[120:123], v[160:163], v[186:189], v[120:123]
	v_mfma_f32_16x16x32_bf16 v[116:119], v[152:155], v[194:197], v[116:119]
	v_mfma_f32_16x16x32_bf16 v[108:111], v[160:163], v[194:197], v[108:111]
	v_mfma_f32_16x16x32_bf16 v[100:103], v[152:155], v[202:205], v[100:103]
	v_mfma_f32_16x16x32_bf16 v[92:95], v[160:163], v[202:205], v[92:95]
	v_mfma_f32_16x16x32_bf16 v[84:87], v[152:155], v[210:213], v[84:87]
	v_mfma_f32_16x16x32_bf16 v[76:79], v[160:163], v[210:213], v[76:79]
	v_mfma_f32_16x16x32_bf16 v[124:127], v[156:159], v[190:193], v[124:127]
	v_mfma_f32_16x16x32_bf16 v[120:123], v[164:167], v[190:193], v[120:123]
	v_mfma_f32_16x16x32_bf16 v[116:119], v[156:159], v[198:201], v[116:119]
	v_mfma_f32_16x16x32_bf16 v[108:111], v[164:167], v[198:201], v[108:111]
	v_mfma_f32_16x16x32_bf16 v[100:103], v[156:159], v[206:209], v[100:103]
	v_mfma_f32_16x16x32_bf16 v[92:95], v[164:167], v[206:209], v[92:95]
	v_mfma_f32_16x16x32_bf16 v[84:87], v[156:159], v[214:217], v[84:87]
	v_mfma_f32_16x16x32_bf16 v[76:79], v[164:167], v[214:217], v[76:79]
	s_setprio 0
	s_setprio 1
	v_mfma_f32_16x16x32_bf16 v[112:115], v[168:171], v[186:189], v[112:115]
	v_mfma_f32_16x16x32_bf16 v[104:107], v[176:179], v[186:189], v[104:107]
	v_mfma_f32_16x16x32_bf16 v[96:99], v[168:171], v[194:197], v[96:99]
	v_mfma_f32_16x16x32_bf16 v[88:91], v[176:179], v[194:197], v[88:91]
	v_mfma_f32_16x16x32_bf16 v[80:83], v[168:171], v[202:205], v[80:83]
	v_mfma_f32_16x16x32_bf16 v[72:75], v[176:179], v[202:205], v[72:75]
	v_mfma_f32_16x16x32_bf16 v[68:71], v[168:171], v[210:213], v[68:71]
	v_mfma_f32_16x16x32_bf16 v[64:67], v[176:179], v[210:213], v[64:67]
	v_mfma_f32_16x16x32_bf16 v[112:115], v[172:175], v[190:193], v[112:115]
	v_mfma_f32_16x16x32_bf16 v[104:107], v[180:183], v[190:193], v[104:107]
	v_mfma_f32_16x16x32_bf16 v[96:99], v[172:175], v[198:201], v[96:99]
	v_mfma_f32_16x16x32_bf16 v[88:91], v[180:183], v[198:201], v[88:91]
	v_mfma_f32_16x16x32_bf16 v[80:83], v[172:175], v[206:209], v[80:83]
	v_mfma_f32_16x16x32_bf16 v[72:75], v[180:183], v[206:209], v[72:75]
	v_mfma_f32_16x16x32_bf16 v[68:71], v[172:175], v[214:217], v[68:71]
	v_mfma_f32_16x16x32_bf16 v[64:67], v[180:183], v[214:217], v[64:67]
	s_setprio 0
	s_barrier
; #define PG8_STAGE(bufoff, gbase, voff) do { _Pragma("unroll") for (int _i = 0; _i < 2; ++_i) \
;         __builtin_amdgcn_global_load_lds((const unsigned*)((const char*)(gbase) + (voff)[_i]), (PG8_LAS unsigned*)(lds + (bufoff) + ldsw + _i * 8192), 16, 0, 0); } while (0)
; #define PG8_LDA(dst, b, h) do { _Pragma("unroll") for (int m = 0; m < 4; ++m) _Pragma("unroll") for (int k = 0; k < 2; ++k) dst[m][k] = *(const PG8_LAS bf16x8*)(lds + PG8_SA(b, h) + aoff + m * 2048 + k * 1024); } while (0)
; #define PG8_MMA(ai, bj, At, Bt) do { __builtin_amdgcn_s_setprio(1); _Pragma("unroll") for (int m = 0; m < 4; ++m) _Pragma("unroll") for (int n = 0; n < 2; ++n) _Pragma("unroll") for (int k = 0; k < 2; ++k) \
;         acc[ai][bj][m][n] = __builtin_amdgcn_mfma_f32_16x16x32_bf16(Bt[n][k], At[m][k], acc[ai][bj][m][n], 0, 0, 0); __builtin_amdgcn_s_setprio(0); } while (0)
; #define PG8_WAIT_V(n) asm volatile("s_waitcnt vmcnt(" #n ")" ::: "memory")
; #define PG8_WAIT_L(n) asm volatile("s_waitcnt lgkmcnt(" #n ")" ::: "memory")
; #define PG8_BAR __builtin_amdgcn_s_barrier()
; #define PG8_SCHED __builtin_amdgcn_sched_barrier(0)
; template <class Epi, class Sched, bool ALIGN_EPI = false, bool SP2 = false>
; __device__ __forceinline__ void gemm_phase(PG8_LAS unsigned char* lds, const Gemm g, const Sched& S, const Epi& E) {
;     ...
;         for (int t = 0; t < nt; t += 2) {
;             const bool last = (t == nt - 2);
;             const char* a1 = cA + (size_t)(t + 1) * kstep;
;             const char* a2 = last ? nA : cA + (size_t)(t + 2) * kstep; const char* b2 = last ? nB : cB + (size_t)(t + 2) * kstep;
;             const char* a3 = a2 + kstep; const char* b3 = b2 + kstep;
;     ...
;             PG8_LDA(At, 1, 1); PG8_STAGE(PG8_SB(1, 0), b3, voffB); PG8_STAGE(PG8_SB(1, 1), b3 + hstep, voffB); PG8_STAGE(PG8_SA(1, 0), a3, voffA);
;             PG8_WAIT_V(8); PG8_WAIT_L(0); PG8_BAR; PG8_MMA(1, 0, At, B0); PG8_MMA(1, 1, At, B1); PG8_BAR; PG8_SCHED;
	s_add_i32 s22, s59, s36
	v_lshl_add_u64 v[144:145], v[144:145], 0, s[8:9]
	s_mov_b32 m0, s22
	ds_read_b128 v[186:189], v151 offset:49152
	ds_read_b128 v[190:193], v151 offset:50176
	ds_read_b128 v[194:197], v151 offset:51200
	ds_read_b128 v[198:201], v151 offset:52224
	ds_read_b128 v[202:205], v151 offset:53248
	ds_read_b128 v[206:209], v151 offset:54272
	ds_read_b128 v[210:213], v151 offset:55296
	ds_read_b128 v[214:217], v151 offset:56320
	global_load_lds_dwordx4 v[144:145], off
	s_add_i32 m0, s22, 0x2000
	s_add_u32 s22, s26, 0xb0080
	v_lshl_add_u64 v[144:145], v[218:219], 0, s[8:9]
	s_addc_u32 s23, s27, 0
	s_add_i32 s26, s60, s36
	global_load_lds_dwordx4 v[144:145], off
	s_mov_b32 m0, s26
	v_lshl_add_u64 v[144:145], s[22:23], 0, v[130:131]
	global_load_lds_dwordx4 v[144:145], off
	s_add_i32 m0, s26, 0x2000
	v_lshl_add_u64 v[144:145], s[22:23], 0, v[134:135]
	global_load_lds_dwordx4 v[144:145], off
	s_mov_b32 m0, s42
	v_lshl_add_u64 v[144:145], v[220:221], 0, s[8:9]
	global_load_lds_dwordx4 v[144:145], off
	s_mov_b32 m0, s43
	v_lshl_add_u64 v[144:145], v[222:223], 0, s[8:9]
	global_load_lds_dwordx4 v[144:145], off
	s_waitcnt vmcnt(8)
	s_waitcnt lgkmcnt(0)
	s_barrier
	s_setprio 1
	s_waitcnt lgkmcnt(0)
	v_mfma_f32_16x16x32_bf16 v[60:63], v[152:155], v[186:189], v[60:63]
	v_mfma_f32_16x16x32_bf16 v[56:59], v[160:163], v[186:189], v[56:59]
	v_mfma_f32_16x16x32_bf16 v[52:55], v[152:155], v[194:197], v[52:55]
	v_mfma_f32_16x16x32_bf16 v[44:47], v[160:163], v[194:197], v[44:47]
	v_mfma_f32_16x16x32_bf16 v[36:39], v[152:155], v[202:205], v[36:39]
	v_mfma_f32_16x16x32_bf16 v[28:31], v[160:163], v[202:205], v[28:31]
	v_mfma_f32_16x16x32_bf16 v[20:23], v[152:155], v[210:213], v[20:23]
	v_mfma_f32_16x16x32_bf16 v[12:15], v[160:163], v[210:213], v[12:15]
	v_mfma_f32_16x16x32_bf16 v[60:63], v[156:159], v[190:193], v[60:63]
	v_mfma_f32_16x16x32_bf16 v[56:59], v[164:167], v[190:193], v[56:59]
	v_mfma_f32_16x16x32_bf16 v[52:55], v[156:159], v[198:201], v[52:55]
	v_mfma_f32_16x16x32_bf16 v[44:47], v[164:167], v[198:201], v[44:47]
	v_mfma_f32_16x16x32_bf16 v[36:39], v[156:159], v[206:209], v[36:39]
	v_mfma_f32_16x16x32_bf16 v[28:31], v[164:167], v[206:209], v[28:31]
	v_mfma_f32_16x16x32_bf16 v[20:23], v[156:159], v[214:217], v[20:23]
	v_mfma_f32_16x16x32_bf16 v[12:15], v[164:167], v[214:217], v[12:15]
	s_setprio 0
	s_setprio 1
	v_mfma_f32_16x16x32_bf16 v[48:51], v[168:171], v[186:189], v[48:51]
	v_mfma_f32_16x16x32_bf16 v[40:43], v[176:179], v[186:189], v[40:43]
	v_mfma_f32_16x16x32_bf16 v[32:35], v[168:171], v[194:197], v[32:35]
	v_mfma_f32_16x16x32_bf16 v[24:27], v[176:179], v[194:197], v[24:27]
	v_mfma_f32_16x16x32_bf16 v[16:19], v[168:171], v[202:205], v[16:19]
	v_mfma_f32_16x16x32_bf16 v[8:11], v[176:179], v[202:205], v[8:11]
	v_mfma_f32_16x16x32_bf16 v[4:7], v[168:171], v[210:213], v[4:7]
	v_mfma_f32_16x16x32_bf16 v[0:3], v[176:179], v[210:213], v[0:3]
	v_mfma_f32_16x16x32_bf16 v[48:51], v[172:175], v[190:193], v[48:51]
	v_mfma_f32_16x16x32_bf16 v[40:43], v[180:183], v[190:193], v[40:43]
	v_mfma_f32_16x16x32_bf16 v[32:35], v[172:175], v[198:201], v[32:35]
	v_mfma_f32_16x16x32_bf16 v[24:27], v[180:183], v[198:201], v[24:27]
	v_mfma_f32_16x16x32_bf16 v[16:19], v[172:175], v[206:209], v[16:19]
	v_mfma_f32_16x16x32_bf16 v[8:11], v[180:183], v[206:209], v[8:11]
	v_mfma_f32_16x16x32_bf16 v[4:7], v[172:175], v[214:217], v[4:7]
	v_mfma_f32_16x16x32_bf16 v[0:3], v[180:183], v[214:217], v[0:3]
	s_setprio 0
	s_barrier
	s_add_i32 s58, s58, 2
	s_add_u32 s56, s56, 0x100
	s_addc_u32 s57, s57, 0
	s_cmp_gt_u32 s58, 41
	s_mov_b64 s[22:23], s[24:25]
	s_cbranch_scc0 .LBB0_196
	s_and_b64 vcc, exec, s[10:11]
	s_cbranch_vccz .LBB0_199
	s_barrier

; #define PG8_STAGE(bufoff, gbase, voff) do { _Pragma("unroll") for (int _i = 0; _i < 2; ++_i) \
;         __builtin_amdgcn_global_load_lds((const unsigned*)((const char*)(gbase) + (voff)[_i]), (PG8_LAS unsigned*)(lds + (bufoff) + ldsw + _i * 8192), 16, 0, 0); } while (0)
; #define PG8_LDA(dst, b, h) do { _Pragma("unroll") for (int m = 0; m < 4; ++m) _Pragma("unroll") for (int k = 0; k < 2; ++k) dst[m][k] = *(const PG8_LAS bf16x8*)(lds + PG8_SA(b, h) + aoff + m * 2048 + k * 1024); } while (0)
; #define PG8_LDB(dst, b, h) do { _Pragma("unroll") for (int n = 0; n < 2; ++n) _Pragma("unroll") for (int k = 0; k < 2; ++k) dst[n][k] = *(const PG8_LAS bf16x8*)(lds + PG8_SB(b, h) + boff + n * 2048 + k * 1024); } while (0)
; #define PG8_MMA(ai, bj, At, Bt) do { __builtin_amdgcn_s_setprio(1); _Pragma("unroll") for (int m = 0; m < 4; ++m) _Pragma("unroll") for (int n = 0; n < 2; ++n) _Pragma("unroll") for (int k = 0; k < 2; ++k) \
;         acc[ai][bj][m][n] = __builtin_amdgcn_mfma_f32_16x16x32_bf16(Bt[n][k], At[m][k], acc[ai][bj][m][n], 0, 0, 0); __builtin_amdgcn_s_setprio(0); } while (0)
; #define PG8_WAIT_V(n) asm volatile("s_waitcnt vmcnt(" #n ")" ::: "memory")
; #define PG8_WAIT_L(n) asm volatile("s_waitcnt lgkmcnt(" #n ")" ::: "memory")
; #define PG8_BAR __builtin_amdgcn_s_barrier()
; #define PG8_SCHED __builtin_amdgcn_sched_barrier(0)
; template <class Epi, class Sched, bool ALIGN_EPI = false, bool SP2 = false>
; __device__ __forceinline__ void gemm_phase(PG8_LAS unsigned char* lds, const Gemm g, const Sched& S, const Epi& E) {
;     ...
;         for (int t = 0; t < nt; t += 2) {
;             const bool last = (t == nt - 2);
;             const char* a1 = cA + (size_t)(t + 1) * kstep;
;             const char* a2 = last ? nA : cA + (size_t)(t + 2) * kstep; const char* b2 = last ? nB : cB + (size_t)(t + 2) * kstep;
;             const char* a3 = a2 + kstep; const char* b3 = b2 + kstep;
;             if (last && has_next) S.a_ready(nxt);
;             if constexpr (SP2) {
;             PG8_LDB(B0, 0, 0); PG8_LDB(B1, 0, 1); PG8_SCHED; PG8_LDA(At, 0, 0); PG8_STAGE(PG8_SA(1, 1), a1 + hstep, voffA);
;             PG8_WAIT_V(8); PG8_WAIT_L(0); PG8_BAR; PG8_MMA(0, 0, At, B0); PG8_MMA(0, 1, At, B1); PG8_BAR; PG8_SCHED;
;             PG8_LDA(At, 0, 1); PG8_STAGE(PG8_SB(0, 0), b2, voffB); PG8_STAGE(PG8_SB(0, 1), b2 + hstep, voffB); PG8_STAGE(PG8_SA(0, 0), a2, voffA);
.LBB0_269:
	ds_read_b128 v[148:151], v145
	ds_read_b128 v[152:155], v145 offset:1024
	ds_read_b128 v[156:159], v145 offset:2048
	ds_read_b128 v[160:163], v145 offset:3072
	ds_read_b128 v[164:167], v146
	ds_read_b128 v[168:171], v146 offset:1024
	ds_read_b128 v[172:175], v146 offset:2048
	ds_read_b128 v[176:179], v146 offset:3072
	s_add_u32 s26, s24, 0x100
	s_addc_u32 s27, s25, 0
	s_cmp_eq_u32 s57, 40
	s_cselect_b32 s31, s21, s27
	s_cselect_b32 s30, s20, s26
	s_cselect_b32 s29, s23, s56
	s_cselect_b32 s28, s22, s55
	v_lshl_add_u64 v[140:141], s[24:25], 0, v[138:139]
	s_add_i32 m0, s36, 0xc000
	ds_read_b128 v[180:183], v147
	ds_read_b128 v[186:189], v147 offset:1024
	ds_read_b128 v[190:193], v147 offset:2048
	ds_read_b128 v[194:197], v147 offset:3072
	ds_read_b128 v[198:201], v147 offset:4096
	ds_read_b128 v[202:205], v147 offset:5120
	ds_read_b128 v[206:209], v147 offset:6144
	ds_read_b128 v[210:213], v147 offset:7168
	global_load_lds_dwordx4 v[140:141], off
	s_add_i32 m0, s36, 0xe000
	v_lshl_add_u64 v[140:141], s[24:25], 0, v[136:137]
	global_load_lds_dwordx4 v[140:141], off
	s_waitcnt vmcnt(8)
	s_waitcnt lgkmcnt(0)
	s_barrier
	s_setprio 1
	s_waitcnt lgkmcnt(0)
	v_mfma_f32_16x16x32_bf16 v[124:127], v[148:151], v[180:183], v[124:127]
	v_mfma_f32_16x16x32_bf16 v[120:123], v[156:159], v[180:183], v[120:123]
	v_mfma_f32_16x16x32_bf16 v[116:119], v[148:151], v[190:193], v[116:119]
	v_mfma_f32_16x16x32_bf16 v[108:111], v[156:159], v[190:193], v[108:111]
	v_mfma_f32_16x16x32_bf16 v[100:103], v[148:151], v[198:201], v[100:103]
	v_mfma_f32_16x16x32_bf16 v[92:95], v[156:159], v[198:201], v[92:95]
	v_mfma_f32_16x16x32_bf16 v[84:87], v[148:151], v[206:209], v[84:87]
	v_mfma_f32_16x16x32_bf16 v[76:79], v[156:159], v[206:209], v[76:79]
	v_mfma_f32_16x16x32_bf16 v[124:127], v[152:155], v[186:189], v[124:127]
	v_mfma_f32_16x16x32_bf16 v[120:123], v[160:163], v[186:189], v[120:123]
	v_mfma_f32_16x16x32_bf16 v[116:119], v[152:155], v[194:197], v[116:119]
	v_mfma_f32_16x16x32_bf16 v[108:111], v[160:163], v[194:197], v[108:111]
	v_mfma_f32_16x16x32_bf16 v[100:103], v[152:155], v[202:205], v[100:103]
	v_mfma_f32_16x16x32_bf16 v[92:95], v[160:163], v[202:205], v[92:95]
	v_mfma_f32_16x16x32_bf16 v[84:87], v[152:155], v[210:213], v[84:87]
	v_mfma_f32_16x16x32_bf16 v[76:79], v[160:163], v[210:213], v[76:79]
	s_setprio 0
	s_setprio 1
	v_mfma_f32_16x16x32_bf16 v[112:115], v[164:167], v[180:183], v[112:115]
	v_mfma_f32_16x16x32_bf16 v[104:107], v[172:175], v[180:183], v[104:107]
	v_mfma_f32_16x16x32_bf16 v[96:99], v[164:167], v[190:193], v[96:99]
	v_mfma_f32_16x16x32_bf16 v[88:91], v[172:175], v[190:193], v[88:91]
	v_mfma_f32_16x16x32_bf16 v[80:83], v[164:167], v[198:201], v[80:83]
	v_mfma_f32_16x16x32_bf16 v[72:75], v[172:175], v[198:201], v[72:75]
	v_mfma_f32_16x16x32_bf16 v[68:71], v[164:167], v[206:209], v[68:71]
	v_mfma_f32_16x16x32_bf16 v[64:67], v[172:175], v[206:209], v[64:67]
	v_mfma_f32_16x16x32_bf16 v[112:115], v[168:171], v[186:189], v[112:115]
	v_mfma_f32_16x16x32_bf16 v[104:107], v[176:179], v[186:189], v[104:107]
	v_mfma_f32_16x16x32_bf16 v[96:99], v[168:171], v[194:197], v[96:99]
	v_mfma_f32_16x16x32_bf16 v[88:91], v[176:179], v[194:197], v[88:91]
	v_mfma_f32_16x16x32_bf16 v[80:83], v[168:171], v[202:205], v[80:83]
	v_mfma_f32_16x16x32_bf16 v[72:75], v[176:179], v[202:205], v[72:75]
	v_mfma_f32_16x16x32_bf16 v[68:71], v[168:171], v[210:213], v[68:71]
	v_mfma_f32_16x16x32_bf16 v[64:67], v[176:179], v[210:213], v[64:67]
	s_setprio 0
	s_barrier
	s_add_i32 s24, s44, s35
	v_lshl_add_u64 v[140:141], s[28:29], 0, v[130:131]
	s_mov_b32 m0, s24
	ds_read_b128 v[180:183], v147 offset:16384
	ds_read_b128 v[186:189], v147 offset:17408
	ds_read_b128 v[190:193], v147 offset:18432
	ds_read_b128 v[194:197], v147 offset:19456
	ds_read_b128 v[198:201], v147 offset:20480
	ds_read_b128 v[202:205], v147 offset:21504
	ds_read_b128 v[206:209], v147 offset:22528
	ds_read_b128 v[210:213], v147 offset:23552
	global_load_lds_dwordx4 v[140:141], off
	s_add_i32 m0, s24, 0x2000
	s_add_u32 s24, s28, 0xb0000
	v_lshl_add_u64 v[214:215], s[28:29], 0, v[134:135]
	s_addc_u32 s25, s29, 0
	s_add_i32 s58, s45, s35
	global_load_lds_dwordx4 v[214:215], off
	v_lshl_add_u64 v[216:217], s[24:25], 0, v[130:131]
	s_mov_b32 m0, s58
	v_lshl_add_u64 v[218:219], s[30:31], 0, v[132:133]
	global_load_lds_dwordx4 v[216:217], off
	s_add_i32 m0, s58, 0x2000
	v_lshl_add_u64 v[216:217], s[24:25], 0, v[134:135]
	global_load_lds_dwordx4 v[216:217], off
	s_mov_b32 m0, s36
	v_lshl_add_u64 v[216:217], s[30:31], 0, v[128:129]
	global_load_lds_dwordx4 v[216:217], off
	s_mov_b32 m0, s37
	s_nop 0
	global_load_lds_dwordx4 v[218:219], off
	s_waitcnt vmcnt(8)
	s_waitcnt lgkmcnt(0)
	s_barrier
; #define PG8_STAGE(bufoff, gbase, voff) do { _Pragma("unroll") for (int _i = 0; _i < 2; ++_i) \
;         __builtin_amdgcn_global_load_lds((const unsigned*)((const char*)(gbase) + (voff)[_i]), (PG8_LAS unsigned*)(lds + (bufoff) + ldsw + _i * 8192), 16, 0, 0); } while (0)
; #define PG8_LDA(dst, b, h) do { _Pragma("unroll") for (int m = 0; m < 4; ++m) _Pragma("unroll") for (int k = 0; k < 2; ++k) dst[m][k] = *(const PG8_LAS bf16x8*)(lds + PG8_SA(b, h) + aoff + m * 2048 + k * 1024); } while (0)
; #define PG8_LDB(dst, b, h) do { _Pragma("unroll") for (int n = 0; n < 2; ++n) _Pragma("unroll") for (int k = 0; k < 2; ++k) dst[n][k] = *(const PG8_LAS bf16x8*)(lds + PG8_SB(b, h) + boff + n * 2048 + k * 1024); } while (0)
; #define PG8_MMA(ai, bj, At, Bt) do { __builtin_amdgcn_s_setprio(1); _Pragma("unroll") for (int m = 0; m < 4; ++m) _Pragma("unroll") for (int n = 0; n < 2; ++n) _Pragma("unroll") for (int k = 0; k < 2; ++k) \
;         acc[ai][bj][m][n] = __builtin_amdgcn_mfma_f32_16x16x32_bf16(Bt[n][k], At[m][k], acc[ai][bj][m][n], 0, 0, 0); __builtin_amdgcn_s_setprio(0); } while (0)
; #define PG8_WAIT_V(n) asm volatile("s_waitcnt vmcnt(" #n ")" ::: "memory")
; #define PG8_WAIT_L(n) asm volatile("s_waitcnt lgkmcnt(" #n ")" ::: "memory")
; #define PG8_BAR __builtin_amdgcn_s_barrier()
; #define PG8_SCHED __builtin_amdgcn_sched_barrier(0)
; template <class Epi, class Sched, bool ALIGN_EPI = false, bool SP2 = false>
; __device__ __forceinline__ void gemm_phase(PG8_LAS unsigned char* lds, const Gemm g, const Sched& S, const Epi& E) {
;     ...
;             PG8_WAIT_V(8); PG8_WAIT_L(0); PG8_BAR; PG8_MMA(1, 0, At, B0); PG8_MMA(1, 1, At, B1); PG8_BAR; PG8_SCHED;
;             PG8_LDB(B0, 1, 0); PG8_LDB(B1, 1, 1); PG8_SCHED; PG8_LDA(At, 1, 0); PG8_STAGE(PG8_SA(0, 1), a2 + hstep, voffA);
;             PG8_WAIT_V(8); PG8_WAIT_L(0); PG8_BAR; PG8_MMA(0, 0, At, B0); PG8_MMA(0, 1, At, B1); PG8_BAR; PG8_SCHED;
	s_setprio 1
	s_waitcnt lgkmcnt(0)
	v_mfma_f32_16x16x32_bf16 v[60:63], v[148:151], v[180:183], v[60:63]
	v_mfma_f32_16x16x32_bf16 v[56:59], v[156:159], v[180:183], v[56:59]
	v_mfma_f32_16x16x32_bf16 v[52:55], v[148:151], v[190:193], v[52:55]
	v_mfma_f32_16x16x32_bf16 v[44:47], v[156:159], v[190:193], v[44:47]
	v_mfma_f32_16x16x32_bf16 v[36:39], v[148:151], v[198:201], v[36:39]
	v_mfma_f32_16x16x32_bf16 v[28:31], v[156:159], v[198:201], v[28:31]
	v_mfma_f32_16x16x32_bf16 v[20:23], v[148:151], v[206:209], v[20:23]
	v_mfma_f32_16x16x32_bf16 v[12:15], v[156:159], v[206:209], v[12:15]
	v_mfma_f32_16x16x32_bf16 v[60:63], v[152:155], v[186:189], v[60:63]
	v_mfma_f32_16x16x32_bf16 v[56:59], v[160:163], v[186:189], v[56:59]
	v_mfma_f32_16x16x32_bf16 v[52:55], v[152:155], v[194:197], v[52:55]
	v_mfma_f32_16x16x32_bf16 v[44:47], v[160:163], v[194:197], v[44:47]
	v_mfma_f32_16x16x32_bf16 v[36:39], v[152:155], v[202:205], v[36:39]
	v_mfma_f32_16x16x32_bf16 v[28:31], v[160:163], v[202:205], v[28:31]
	v_mfma_f32_16x16x32_bf16 v[20:23], v[152:155], v[210:213], v[20:23]
	v_mfma_f32_16x16x32_bf16 v[12:15], v[160:163], v[210:213], v[12:15]
	s_setprio 0
	s_setprio 1
	v_mfma_f32_16x16x32_bf16 v[48:51], v[164:167], v[180:183], v[48:51]
	v_mfma_f32_16x16x32_bf16 v[40:43], v[172:175], v[180:183], v[40:43]
	v_mfma_f32_16x16x32_bf16 v[32:35], v[164:167], v[190:193], v[32:35]
	v_mfma_f32_16x16x32_bf16 v[24:27], v[172:175], v[190:193], v[24:27]
	v_mfma_f32_16x16x32_bf16 v[16:19], v[164:167], v[198:201], v[16:19]
	v_mfma_f32_16x16x32_bf16 v[8:11], v[172:175], v[198:201], v[8:11]
	v_mfma_f32_16x16x32_bf16 v[4:7], v[164:167], v[206:209], v[4:7]
	v_mfma_f32_16x16x32_bf16 v[0:3], v[172:175], v[206:209], v[0:3]
	v_mfma_f32_16x16x32_bf16 v[48:51], v[168:171], v[186:189], v[48:51]
	v_mfma_f32_16x16x32_bf16 v[40:43], v[176:179], v[186:189], v[40:43]
	v_mfma_f32_16x16x32_bf16 v[32:35], v[168:171], v[194:197], v[32:35]
	v_mfma_f32_16x16x32_bf16 v[24:27], v[176:179], v[194:197], v[24:27]
	v_mfma_f32_16x16x32_bf16 v[16:19], v[168:171], v[202:205], v[16:19]
	v_mfma_f32_16x16x32_bf16 v[8:11], v[176:179], v[202:205], v[8:11]
	v_mfma_f32_16x16x32_bf16 v[4:7], v[168:171], v[210:213], v[4:7]
	v_mfma_f32_16x16x32_bf16 v[0:3], v[176:179], v[210:213], v[0:3]
	s_setprio 0
	s_barrier
	s_add_i32 s58, 0, 0x18000
	s_add_i32 s59, 0, 0x1c000
	v_add_u32_e32 v160, s58, v143
	v_add_u32_e32 v176, s59, v143
	ds_read_b128 v[148:151], v160
	ds_read_b128 v[152:155], v160 offset:1024
	ds_read_b128 v[156:159], v160 offset:2048
	ds_read_b128 v[160:163], v160 offset:3072
	ds_read_b128 v[164:167], v176
	ds_read_b128 v[168:171], v176 offset:1024
	ds_read_b128 v[172:175], v176 offset:2048
	ds_read_b128 v[176:179], v176 offset:3072
	s_add_u32 s24, s30, 0xb0000
	s_addc_u32 s25, s31, 0
	s_mov_b32 m0, s38
	v_lshl_add_u64 v[220:221], s[24:25], 0, v[128:129]
	ds_read_b128 v[180:183], v147 offset:32768
	ds_read_b128 v[186:189], v147 offset:33792
	ds_read_b128 v[190:193], v147 offset:34816
	ds_read_b128 v[194:197], v147 offset:35840
	ds_read_b128 v[198:201], v147 offset:36864
	ds_read_b128 v[202:205], v147 offset:37888
	ds_read_b128 v[206:209], v147 offset:38912
	ds_read_b128 v[210:213], v147 offset:39936
	global_load_lds_dwordx4 v[220:221], off
	s_mov_b32 m0, s39
	v_lshl_add_u64 v[220:221], s[24:25], 0, v[132:133]
	global_load_lds_dwordx4 v[220:221], off
	s_waitcnt vmcnt(8)
	s_waitcnt lgkmcnt(0)
	s_barrier
	s_setprio 1
	s_waitcnt lgkmcnt(0)
	v_mfma_f32_16x16x32_bf16 v[124:127], v[148:151], v[180:183], v[124:127]
	v_mfma_f32_16x16x32_bf16 v[120:123], v[156:159], v[180:183], v[120:123]
	v_mfma_f32_16x16x32_bf16 v[116:119], v[148:151], v[190:193], v[116:119]
	v_mfma_f32_16x16x32_bf16 v[108:111], v[156:159], v[190:193], v[108:111]
	v_mfma_f32_16x16x32_bf16 v[100:103], v[148:151], v[198:201], v[100:103]
	v_mfma_f32_16x16x32_bf16 v[92:95], v[156:159], v[198:201], v[92:95]
	v_mfma_f32_16x16x32_bf16 v[84:87], v[148:151], v[206:209], v[84:87]
	v_mfma_f32_16x16x32_bf16 v[76:79], v[156:159], v[206:209], v[76:79]
	v_mfma_f32_16x16x32_bf16 v[124:127], v[152:155], v[186:189], v[124:127]
	v_mfma_f32_16x16x32_bf16 v[120:123], v[160:163], v[186:189], v[120:123]
	v_mfma_f32_16x16x32_bf16 v[116:119], v[152:155], v[194:197], v[116:119]
	v_mfma_f32_16x16x32_bf16 v[108:111], v[160:163], v[194:197], v[108:111]
	v_mfma_f32_16x16x32_bf16 v[100:103], v[152:155], v[202:205], v[100:103]
	v_mfma_f32_16x16x32_bf16 v[92:95], v[160:163], v[202:205], v[92:95]
	v_mfma_f32_16x16x32_bf16 v[84:87], v[152:155], v[210:213], v[84:87]
	v_mfma_f32_16x16x32_bf16 v[76:79], v[160:163], v[210:213], v[76:79]
	s_setprio 0
	s_setprio 1
	v_mfma_f32_16x16x32_bf16 v[112:115], v[164:167], v[180:183], v[112:115]
	v_mfma_f32_16x16x32_bf16 v[104:107], v[172:175], v[180:183], v[104:107]
	v_mfma_f32_16x16x32_bf16 v[96:99], v[164:167], v[190:193], v[96:99]
	v_mfma_f32_16x16x32_bf16 v[88:91], v[172:175], v[190:193], v[88:91]
	v_mfma_f32_16x16x32_bf16 v[80:83], v[164:167], v[198:201], v[80:83]
	v_mfma_f32_16x16x32_bf16 v[72:75], v[172:175], v[198:201], v[72:75]
	v_mfma_f32_16x16x32_bf16 v[68:71], v[164:167], v[206:209], v[68:71]
	v_mfma_f32_16x16x32_bf16 v[64:67], v[172:175], v[206:209], v[64:67]
	v_mfma_f32_16x16x32_bf16 v[112:115], v[168:171], v[186:189], v[112:115]
	v_mfma_f32_16x16x32_bf16 v[104:107], v[176:179], v[186:189], v[104:107]
	v_mfma_f32_16x16x32_bf16 v[96:99], v[168:171], v[194:197], v[96:99]
	v_mfma_f32_16x16x32_bf16 v[88:91], v[176:179], v[194:197], v[88:91]
	v_mfma_f32_16x16x32_bf16 v[80:83], v[168:171], v[202:205], v[80:83]
	v_mfma_f32_16x16x32_bf16 v[72:75], v[176:179], v[202:205], v[72:75]
	v_mfma_f32_16x16x32_bf16 v[68:71], v[168:171], v[210:213], v[68:71]
	v_mfma_f32_16x16x32_bf16 v[64:67], v[176:179], v[210:213], v[64:67]
	s_setprio 0
	s_barrier
; #define PG8_STAGE(bufoff, gbase, voff) do { _Pragma("unroll") for (int _i = 0; _i < 2; ++_i) \
;         __builtin_amdgcn_global_load_lds((const unsigned*)((const char*)(gbase) + (voff)[_i]), (PG8_LAS unsigned*)(lds + (bufoff) + ldsw + _i * 8192), 16, 0, 0); } while (0)
; #define PG8_LDA(dst, b, h) do { _Pragma("unroll") for (int m = 0; m < 4; ++m) _Pragma("unroll") for (int k = 0; k < 2; ++k) dst[m][k] = *(const PG8_LAS bf16x8*)(lds + PG8_SA(b, h) + aoff + m * 2048 + k * 1024); } while (0)
; #define PG8_MMA(ai, bj, At, Bt) do { __builtin_amdgcn_s_setprio(1); _Pragma("unroll") for (int m = 0; m < 4; ++m) _Pragma("unroll") for (int n = 0; n < 2; ++n) _Pragma("unroll") for (int k = 0; k < 2; ++k) \
;         acc[ai][bj][m][n] = __builtin_amdgcn_mfma_f32_16x16x32_bf16(Bt[n][k], At[m][k], acc[ai][bj][m][n], 0, 0, 0); __builtin_amdgcn_s_setprio(0); } while (0)
; #define PG8_WAIT_V(n) asm volatile("s_waitcnt vmcnt(" #n ")" ::: "memory")
; #define PG8_WAIT_L(n) asm volatile("s_waitcnt lgkmcnt(" #n ")" ::: "memory")
; #define PG8_BAR __builtin_amdgcn_s_barrier()
; #define PG8_SCHED __builtin_amdgcn_sched_barrier(0)
; template <class Epi, class Sched, bool ALIGN_EPI = false, bool SP2 = false>
; __device__ __forceinline__ void gemm_phase(PG8_LAS unsigned char* lds, const Gemm g, const Sched& S, const Epi& E) {
;     ...
;         for (int t = 0; t < nt; t += 2) {
;             const bool last = (t == nt - 2);
;             const char* a1 = cA + (size_t)(t + 1) * kstep;
;             const char* a2 = last ? nA : cA + (size_t)(t + 2) * kstep; const char* b2 = last ? nB : cB + (size_t)(t + 2) * kstep;
;             const char* a3 = a2 + kstep; const char* b3 = b2 + kstep;
;     ...
;             PG8_LDA(At, 1, 1); PG8_STAGE(PG8_SB(1, 0), b3, voffB); PG8_STAGE(PG8_SB(1, 1), b3 + hstep, voffB); PG8_STAGE(PG8_SA(1, 0), a3, voffA);
;             PG8_WAIT_V(8); PG8_WAIT_L(0); PG8_BAR; PG8_MMA(1, 0, At, B0); PG8_MMA(1, 1, At, B1); PG8_BAR; PG8_SCHED;
	s_add_i32 s24, s58, s35
	v_lshl_add_u64 v[140:141], v[140:141], 0, s[8:9]
	s_mov_b32 m0, s24
	ds_read_b128 v[180:183], v147 offset:49152
	ds_read_b128 v[186:189], v147 offset:50176
	ds_read_b128 v[190:193], v147 offset:51200
	ds_read_b128 v[194:197], v147 offset:52224
	ds_read_b128 v[198:201], v147 offset:53248
	ds_read_b128 v[202:205], v147 offset:54272
	ds_read_b128 v[206:209], v147 offset:55296
	ds_read_b128 v[210:213], v147 offset:56320
	global_load_lds_dwordx4 v[140:141], off
	s_add_i32 m0, s24, 0x2000
	s_add_u32 s24, s28, 0xb0080
	v_lshl_add_u64 v[140:141], v[214:215], 0, s[8:9]
	s_addc_u32 s25, s29, 0
	s_add_i32 s28, s59, s35
	global_load_lds_dwordx4 v[140:141], off
	s_mov_b32 m0, s28
	v_lshl_add_u64 v[140:141], s[24:25], 0, v[130:131]
	global_load_lds_dwordx4 v[140:141], off
	s_add_i32 m0, s28, 0x2000
	v_lshl_add_u64 v[140:141], s[24:25], 0, v[134:135]
	global_load_lds_dwordx4 v[140:141], off
	s_mov_b32 m0, s40
	v_lshl_add_u64 v[140:141], v[216:217], 0, s[8:9]
	global_load_lds_dwordx4 v[140:141], off
	s_mov_b32 m0, s41
	v_lshl_add_u64 v[140:141], v[218:219], 0, s[8:9]
	global_load_lds_dwordx4 v[140:141], off
	s_waitcnt vmcnt(8)
	s_waitcnt lgkmcnt(0)
	s_barrier
	s_setprio 1
	s_waitcnt lgkmcnt(0)
	v_mfma_f32_16x16x32_bf16 v[60:63], v[148:151], v[180:183], v[60:63]
	v_mfma_f32_16x16x32_bf16 v[56:59], v[156:159], v[180:183], v[56:59]
	v_mfma_f32_16x16x32_bf16 v[52:55], v[148:151], v[190:193], v[52:55]
	v_mfma_f32_16x16x32_bf16 v[44:47], v[156:159], v[190:193], v[44:47]
	v_mfma_f32_16x16x32_bf16 v[36:39], v[148:151], v[198:201], v[36:39]
	v_mfma_f32_16x16x32_bf16 v[28:31], v[156:159], v[198:201], v[28:31]
	v_mfma_f32_16x16x32_bf16 v[20:23], v[148:151], v[206:209], v[20:23]
	v_mfma_f32_16x16x32_bf16 v[12:15], v[156:159], v[206:209], v[12:15]
	v_mfma_f32_16x16x32_bf16 v[60:63], v[152:155], v[186:189], v[60:63]
	v_mfma_f32_16x16x32_bf16 v[56:59], v[160:163], v[186:189], v[56:59]
	v_mfma_f32_16x16x32_bf16 v[52:55], v[152:155], v[194:197], v[52:55]
	v_mfma_f32_16x16x32_bf16 v[44:47], v[160:163], v[194:197], v[44:47]
	v_mfma_f32_16x16x32_bf16 v[36:39], v[152:155], v[202:205], v[36:39]
	v_mfma_f32_16x16x32_bf16 v[28:31], v[160:163], v[202:205], v[28:31]
	v_mfma_f32_16x16x32_bf16 v[20:23], v[152:155], v[210:213], v[20:23]
	v_mfma_f32_16x16x32_bf16 v[12:15], v[160:163], v[210:213], v[12:15]
	s_setprio 0
	s_setprio 1
	v_mfma_f32_16x16x32_bf16 v[48:51], v[164:167], v[180:183], v[48:51]
	v_mfma_f32_16x16x32_bf16 v[40:43], v[172:175], v[180:183], v[40:43]
	v_mfma_f32_16x16x32_bf16 v[32:35], v[164:167], v[190:193], v[32:35]
	v_mfma_f32_16x16x32_bf16 v[24:27], v[172:175], v[190:193], v[24:27]
	v_mfma_f32_16x16x32_bf16 v[16:19], v[164:167], v[198:201], v[16:19]
	v_mfma_f32_16x16x32_bf16 v[8:11], v[172:175], v[198:201], v[8:11]
	v_mfma_f32_16x16x32_bf16 v[4:7], v[164:167], v[206:209], v[4:7]
	v_mfma_f32_16x16x32_bf16 v[0:3], v[172:175], v[206:209], v[0:3]
	v_mfma_f32_16x16x32_bf16 v[48:51], v[168:171], v[186:189], v[48:51]
	v_mfma_f32_16x16x32_bf16 v[40:43], v[176:179], v[186:189], v[40:43]
	v_mfma_f32_16x16x32_bf16 v[32:35], v[168:171], v[194:197], v[32:35]
	v_mfma_f32_16x16x32_bf16 v[24:27], v[176:179], v[194:197], v[24:27]
	v_mfma_f32_16x16x32_bf16 v[16:19], v[168:171], v[202:205], v[16:19]
	v_mfma_f32_16x16x32_bf16 v[8:11], v[176:179], v[202:205], v[8:11]
	v_mfma_f32_16x16x32_bf16 v[4:7], v[168:171], v[210:213], v[4:7]
	v_mfma_f32_16x16x32_bf16 v[0:3], v[176:179], v[210:213], v[0:3]
	s_setprio 0
	s_barrier
	s_add_i32 s57, s57, 2
	s_add_u32 s55, s55, 0x100
	s_addc_u32 s56, s56, 0
	s_cmp_gt_u32 s57, 41
	s_mov_b64 s[24:25], s[26:27]
	s_cbranch_scc0 .LBB0_269
	s_and_b64 vcc, exec, s[10:11]
	s_cbranch_vccz .LBB0_272
	s_barrier

; #define PG8_STAGE(bufoff, gbase, voff) do { _Pragma("unroll") for (int _i = 0; _i < 2; ++_i) \
;         __builtin_amdgcn_global_load_lds((const unsigned*)((const char*)(gbase) + (voff)[_i]), (PG8_LAS unsigned*)(lds + (bufoff) + ldsw + _i * 8192), 16, 0, 0); } while (0)
; #define PG8_LDA(dst, b, h) do { _Pragma("unroll") for (int m = 0; m < 4; ++m) _Pragma("unroll") for (int k = 0; k < 2; ++k) dst[m][k] = *(const PG8_LAS bf16x8*)(lds + PG8_SA(b, h) + aoff + m * 2048 + k * 1024); } while (0)
; #define PG8_LDB(dst, b, h) do { _Pragma("unroll") for (int n = 0; n < 2; ++n) _Pragma("unroll") for (int k = 0; k < 2; ++k) dst[n][k] = *(const PG8_LAS bf16x8*)(lds + PG8_SB(b, h) + boff + n * 2048 + k * 1024); } while (0)
; #define PG8_MMA(ai, bj, At, Bt) do { __builtin_amdgcn_s_setprio(1); _Pragma("unroll") for (int m = 0; m < 4; ++m) _Pragma("unroll") for (int n = 0; n < 2; ++n) _Pragma("unroll") for (int k = 0; k < 2; ++k) \
;         acc[ai][bj][m][n] = __builtin_amdgcn_mfma_f32_16x16x32_bf16(Bt[n][k], At[m][k], acc[ai][bj][m][n], 0, 0, 0); __builtin_amdgcn_s_setprio(0); } while (0)
; #define PG8_WAIT_V(n) asm volatile("s_waitcnt vmcnt(" #n ")" ::: "memory")
; #define PG8_WAIT_L(n) asm volatile("s_waitcnt lgkmcnt(" #n ")" ::: "memory")
; #define PG8_BAR __builtin_amdgcn_s_barrier()
; #define PG8_SCHED __builtin_amdgcn_sched_barrier(0)
; template <class Epi, class Sched, bool ALIGN_EPI = false, bool SP2 = false>
; __device__ __forceinline__ void gemm_phase(PG8_LAS unsigned char* lds, const Gemm g, const Sched& S, const Epi& E) {
;     ...
;         for (int t = 0; t < nt; t += 2) {
;             const bool last = (t == nt - 2);
;             const char* a1 = cA + (size_t)(t + 1) * kstep;
;             const char* a2 = last ? nA : cA + (size_t)(t + 2) * kstep; const char* b2 = last ? nB : cB + (size_t)(t + 2) * kstep;
;             const char* a3 = a2 + kstep; const char* b3 = b2 + kstep;
;             if (last && has_next) S.a_ready(nxt);
;             if constexpr (SP2) {
;             PG8_LDB(B0, 0, 0); PG8_LDB(B1, 0, 1); PG8_SCHED; PG8_LDA(At, 0, 0); PG8_STAGE(PG8_SA(1, 1), a1 + hstep, voffA);
;             PG8_WAIT_V(8); PG8_WAIT_L(0); PG8_BAR; PG8_MMA(0, 0, At, B0); PG8_MMA(0, 1, At, B1); PG8_BAR; PG8_SCHED;
;             PG8_LDA(At, 0, 1); PG8_STAGE(PG8_SB(0, 0), b2, voffB); PG8_STAGE(PG8_SB(0, 1), b2 + hstep, voffB); PG8_STAGE(PG8_SA(0, 0), a2, voffA);
.LBB0_343:
	ds_read_b128 v[144:147], v151
	ds_read_b128 v[154:157], v151 offset:1024
	ds_read_b128 v[158:161], v151 offset:2048
	ds_read_b128 v[162:165], v151 offset:3072
	ds_read_b128 v[166:169], v152
	ds_read_b128 v[170:173], v152 offset:1024
	ds_read_b128 v[174:177], v152 offset:2048
	ds_read_b128 v[178:181], v152 offset:3072
	s_add_u32 s22, s20, 0xfffc0080
	s_addc_u32 s23, s21, -1
	s_cmp_eq_u32 s50, 12
	s_cselect_b32 s25, s13, s23
	s_cselect_b32 s24, s46, s22
	s_cselect_b32 s23, s11, s49
	s_cselect_b32 s22, s47, s48
	v_lshl_add_u64 v[182:183], s[20:21], 0, v[138:139]
	s_add_i32 m0, s19, 0xc000
	ds_read_b128 v[186:189], v153
	ds_read_b128 v[190:193], v153 offset:1024
	ds_read_b128 v[194:197], v153 offset:2048
	ds_read_b128 v[198:201], v153 offset:3072
	ds_read_b128 v[202:205], v153 offset:4096
	ds_read_b128 v[206:209], v153 offset:5120
	ds_read_b128 v[210:213], v153 offset:6144
	ds_read_b128 v[214:217], v153 offset:7168
	global_load_lds_dwordx4 v[182:183], off
	s_add_i32 m0, s19, 0xe000
	v_lshl_add_u64 v[182:183], s[20:21], 0, v[136:137]
	global_load_lds_dwordx4 v[182:183], off
	s_waitcnt vmcnt(8)
	s_waitcnt lgkmcnt(0)
	s_barrier
	s_setprio 1
	s_waitcnt lgkmcnt(0)
	v_mfma_f32_16x16x32_bf16 v[124:127], v[144:147], v[186:189], v[124:127]
	v_mfma_f32_16x16x32_bf16 v[120:123], v[158:161], v[186:189], v[120:123]
	v_mfma_f32_16x16x32_bf16 v[116:119], v[144:147], v[194:197], v[116:119]
	v_mfma_f32_16x16x32_bf16 v[108:111], v[158:161], v[194:197], v[108:111]
	v_mfma_f32_16x16x32_bf16 v[100:103], v[144:147], v[202:205], v[100:103]
	v_mfma_f32_16x16x32_bf16 v[92:95], v[158:161], v[202:205], v[92:95]
	v_mfma_f32_16x16x32_bf16 v[84:87], v[144:147], v[210:213], v[84:87]
	v_mfma_f32_16x16x32_bf16 v[76:79], v[158:161], v[210:213], v[76:79]
	v_mfma_f32_16x16x32_bf16 v[124:127], v[154:157], v[190:193], v[124:127]
	v_mfma_f32_16x16x32_bf16 v[120:123], v[162:165], v[190:193], v[120:123]
	v_mfma_f32_16x16x32_bf16 v[116:119], v[154:157], v[198:201], v[116:119]
	v_mfma_f32_16x16x32_bf16 v[108:111], v[162:165], v[198:201], v[108:111]
	v_mfma_f32_16x16x32_bf16 v[100:103], v[154:157], v[206:209], v[100:103]
	v_mfma_f32_16x16x32_bf16 v[92:95], v[162:165], v[206:209], v[92:95]
	v_mfma_f32_16x16x32_bf16 v[84:87], v[154:157], v[214:217], v[84:87]
	v_mfma_f32_16x16x32_bf16 v[76:79], v[162:165], v[214:217], v[76:79]
	s_setprio 0
	s_setprio 1
	v_mfma_f32_16x16x32_bf16 v[112:115], v[166:169], v[186:189], v[112:115]
	v_mfma_f32_16x16x32_bf16 v[104:107], v[174:177], v[186:189], v[104:107]
	v_mfma_f32_16x16x32_bf16 v[96:99], v[166:169], v[194:197], v[96:99]
	v_mfma_f32_16x16x32_bf16 v[88:91], v[174:177], v[194:197], v[88:91]
	v_mfma_f32_16x16x32_bf16 v[80:83], v[166:169], v[202:205], v[80:83]
	v_mfma_f32_16x16x32_bf16 v[72:75], v[174:177], v[202:205], v[72:75]
	v_mfma_f32_16x16x32_bf16 v[68:71], v[166:169], v[210:213], v[68:71]
	v_mfma_f32_16x16x32_bf16 v[64:67], v[174:177], v[210:213], v[64:67]
	v_mfma_f32_16x16x32_bf16 v[112:115], v[170:173], v[190:193], v[112:115]
	v_mfma_f32_16x16x32_bf16 v[104:107], v[178:181], v[190:193], v[104:107]
	v_mfma_f32_16x16x32_bf16 v[96:99], v[170:173], v[198:201], v[96:99]
	v_mfma_f32_16x16x32_bf16 v[88:91], v[178:181], v[198:201], v[88:91]
	v_mfma_f32_16x16x32_bf16 v[80:83], v[170:173], v[206:209], v[80:83]
	v_mfma_f32_16x16x32_bf16 v[72:75], v[178:181], v[206:209], v[72:75]
	v_mfma_f32_16x16x32_bf16 v[68:71], v[170:173], v[214:217], v[68:71]
	v_mfma_f32_16x16x32_bf16 v[64:67], v[178:181], v[214:217], v[64:67]
	s_setprio 0
	s_barrier
	s_add_i32 s51, s42, s30
	v_lshl_add_u64 v[182:183], s[22:23], 0, v[132:133]
	s_mov_b32 m0, s51
	ds_read_b128 v[186:189], v153 offset:16384
	ds_read_b128 v[190:193], v153 offset:17408
	ds_read_b128 v[194:197], v153 offset:18432
	ds_read_b128 v[198:201], v153 offset:19456
	ds_read_b128 v[202:205], v153 offset:20480
	ds_read_b128 v[206:209], v153 offset:21504
	ds_read_b128 v[210:213], v153 offset:22528
	ds_read_b128 v[214:217], v153 offset:23552
	global_load_lds_dwordx4 v[182:183], off
	s_add_i32 m0, s51, 0x2000
	s_add_u32 s52, s22, 0x40000
	v_lshl_add_u64 v[218:219], s[22:23], 0, v[128:129]
	s_addc_u32 s53, s23, 0
	s_add_i32 s51, s43, s30
	global_load_lds_dwordx4 v[218:219], off
	v_lshl_add_u64 v[220:221], s[52:53], 0, v[132:133]
	s_mov_b32 m0, s51
	v_lshl_add_u64 v[222:223], s[24:25], 0, v[130:131]
	global_load_lds_dwordx4 v[220:221], off
	s_add_i32 m0, s51, 0x2000
	v_lshl_add_u64 v[220:221], s[52:53], 0, v[128:129]
	global_load_lds_dwordx4 v[220:221], off
	s_mov_b32 m0, s19
	v_lshl_add_u64 v[220:221], s[24:25], 0, v[134:135]
	global_load_lds_dwordx4 v[220:221], off
	s_mov_b32 m0, s34
	s_nop 0
	global_load_lds_dwordx4 v[222:223], off
	s_waitcnt vmcnt(8)
	s_waitcnt lgkmcnt(0)
	s_barrier
; #define PG8_STAGE(bufoff, gbase, voff) do { _Pragma("unroll") for (int _i = 0; _i < 2; ++_i) \
;         __builtin_amdgcn_global_load_lds((const unsigned*)((const char*)(gbase) + (voff)[_i]), (PG8_LAS unsigned*)(lds + (bufoff) + ldsw + _i * 8192), 16, 0, 0); } while (0)
; #define PG8_LDA(dst, b, h) do { _Pragma("unroll") for (int m = 0; m < 4; ++m) _Pragma("unroll") for (int k = 0; k < 2; ++k) dst[m][k] = *(const PG8_LAS bf16x8*)(lds + PG8_SA(b, h) + aoff + m * 2048 + k * 1024); } while (0)
; #define PG8_LDB(dst, b, h) do { _Pragma("unroll") for (int n = 0; n < 2; ++n) _Pragma("unroll") for (int k = 0; k < 2; ++k) dst[n][k] = *(const PG8_LAS bf16x8*)(lds + PG8_SB(b, h) + boff + n * 2048 + k * 1024); } while (0)
; #define PG8_MMA(ai, bj, At, Bt) do { __builtin_amdgcn_s_setprio(1); _Pragma("unroll") for (int m = 0; m < 4; ++m) _Pragma("unroll") for (int n = 0; n < 2; ++n) _Pragma("unroll") for (int k = 0; k < 2; ++k) \
;         acc[ai][bj][m][n] = __builtin_amdgcn_mfma_f32_16x16x32_bf16(Bt[n][k], At[m][k], acc[ai][bj][m][n], 0, 0, 0); __builtin_amdgcn_s_setprio(0); } while (0)
; #define PG8_WAIT_V(n) asm volatile("s_waitcnt vmcnt(" #n ")" ::: "memory")
; #define PG8_WAIT_L(n) asm volatile("s_waitcnt lgkmcnt(" #n ")" ::: "memory")
; #define PG8_BAR __builtin_amdgcn_s_barrier()
; #define PG8_SCHED __builtin_amdgcn_sched_barrier(0)
; template <class Epi, class Sched, bool ALIGN_EPI = false, bool SP2 = false>
; __device__ __forceinline__ void gemm_phase(PG8_LAS unsigned char* lds, const Gemm g, const Sched& S, const Epi& E) {
;     ...
;             PG8_WAIT_V(8); PG8_WAIT_L(0); PG8_BAR; PG8_MMA(1, 0, At, B0); PG8_MMA(1, 1, At, B1); PG8_BAR; PG8_SCHED;
;             PG8_LDB(B0, 1, 0); PG8_LDB(B1, 1, 1); PG8_SCHED; PG8_LDA(At, 1, 0); PG8_STAGE(PG8_SA(0, 1), a2 + hstep, voffA);
;             PG8_WAIT_V(8); PG8_WAIT_L(0); PG8_BAR; PG8_MMA(0, 0, At, B0); PG8_MMA(0, 1, At, B1); PG8_BAR; PG8_SCHED;
	s_setprio 1
	s_waitcnt lgkmcnt(0)
	v_mfma_f32_16x16x32_bf16 v[60:63], v[144:147], v[186:189], v[60:63]
	v_mfma_f32_16x16x32_bf16 v[56:59], v[158:161], v[186:189], v[56:59]
	v_mfma_f32_16x16x32_bf16 v[52:55], v[144:147], v[194:197], v[52:55]
	v_mfma_f32_16x16x32_bf16 v[44:47], v[158:161], v[194:197], v[44:47]
	v_mfma_f32_16x16x32_bf16 v[36:39], v[144:147], v[202:205], v[36:39]
	v_mfma_f32_16x16x32_bf16 v[28:31], v[158:161], v[202:205], v[28:31]
	v_mfma_f32_16x16x32_bf16 v[20:23], v[144:147], v[210:213], v[20:23]
	v_mfma_f32_16x16x32_bf16 v[12:15], v[158:161], v[210:213], v[12:15]
	v_mfma_f32_16x16x32_bf16 v[60:63], v[154:157], v[190:193], v[60:63]
	v_mfma_f32_16x16x32_bf16 v[56:59], v[162:165], v[190:193], v[56:59]
	v_mfma_f32_16x16x32_bf16 v[52:55], v[154:157], v[198:201], v[52:55]
	v_mfma_f32_16x16x32_bf16 v[44:47], v[162:165], v[198:201], v[44:47]
	v_mfma_f32_16x16x32_bf16 v[36:39], v[154:157], v[206:209], v[36:39]
	v_mfma_f32_16x16x32_bf16 v[28:31], v[162:165], v[206:209], v[28:31]
	v_mfma_f32_16x16x32_bf16 v[20:23], v[154:157], v[214:217], v[20:23]
	v_mfma_f32_16x16x32_bf16 v[12:15], v[162:165], v[214:217], v[12:15]
	s_setprio 0
	s_setprio 1
	v_mfma_f32_16x16x32_bf16 v[48:51], v[166:169], v[186:189], v[48:51]
	v_mfma_f32_16x16x32_bf16 v[40:43], v[174:177], v[186:189], v[40:43]
	v_mfma_f32_16x16x32_bf16 v[32:35], v[166:169], v[194:197], v[32:35]
	v_mfma_f32_16x16x32_bf16 v[24:27], v[174:177], v[194:197], v[24:27]
	v_mfma_f32_16x16x32_bf16 v[16:19], v[166:169], v[202:205], v[16:19]
	v_mfma_f32_16x16x32_bf16 v[8:11], v[174:177], v[202:205], v[8:11]
	v_mfma_f32_16x16x32_bf16 v[4:7], v[166:169], v[210:213], v[4:7]
	v_mfma_f32_16x16x32_bf16 v[0:3], v[174:177], v[210:213], v[0:3]
	v_mfma_f32_16x16x32_bf16 v[48:51], v[170:173], v[190:193], v[48:51]
	v_mfma_f32_16x16x32_bf16 v[40:43], v[178:181], v[190:193], v[40:43]
	v_mfma_f32_16x16x32_bf16 v[32:35], v[170:173], v[198:201], v[32:35]
	v_mfma_f32_16x16x32_bf16 v[24:27], v[178:181], v[198:201], v[24:27]
	v_mfma_f32_16x16x32_bf16 v[16:19], v[170:173], v[206:209], v[16:19]
	v_mfma_f32_16x16x32_bf16 v[8:11], v[178:181], v[206:209], v[8:11]
	v_mfma_f32_16x16x32_bf16 v[4:7], v[170:173], v[214:217], v[4:7]
	v_mfma_f32_16x16x32_bf16 v[0:3], v[178:181], v[214:217], v[0:3]
	s_setprio 0
	s_barrier
	s_add_i32 s51, 0, 0x18000
	s_add_i32 s52, 0, 0x1c000
	v_add_u32_e32 v162, s51, v149
	v_add_u32_e32 v178, s52, v149
	ds_read_b128 v[144:147], v162
	ds_read_b128 v[154:157], v162 offset:1024
	ds_read_b128 v[158:161], v162 offset:2048
	ds_read_b128 v[162:165], v162 offset:3072
	ds_read_b128 v[166:169], v178
	ds_read_b128 v[170:173], v178 offset:1024
	ds_read_b128 v[174:177], v178 offset:2048
	ds_read_b128 v[178:181], v178 offset:3072
	s_add_u32 s24, s24, 0x40000
	s_addc_u32 s25, s25, 0
	s_mov_b32 m0, s35
	v_lshl_add_u64 v[224:225], s[24:25], 0, v[134:135]
	ds_read_b128 v[186:189], v153 offset:32768
	ds_read_b128 v[190:193], v153 offset:33792
	ds_read_b128 v[194:197], v153 offset:34816
	ds_read_b128 v[198:201], v153 offset:35840
	ds_read_b128 v[202:205], v153 offset:36864
	ds_read_b128 v[206:209], v153 offset:37888
	ds_read_b128 v[210:213], v153 offset:38912
	ds_read_b128 v[214:217], v153 offset:39936
	global_load_lds_dwordx4 v[224:225], off
	s_mov_b32 m0, s36
	v_lshl_add_u64 v[224:225], s[24:25], 0, v[130:131]
	global_load_lds_dwordx4 v[224:225], off
	s_waitcnt vmcnt(8)
	s_waitcnt lgkmcnt(0)
	s_barrier
	s_setprio 1
	s_waitcnt lgkmcnt(0)
	v_mfma_f32_16x16x32_bf16 v[124:127], v[144:147], v[186:189], v[124:127]
	v_mfma_f32_16x16x32_bf16 v[120:123], v[158:161], v[186:189], v[120:123]
	v_mfma_f32_16x16x32_bf16 v[116:119], v[144:147], v[194:197], v[116:119]
	v_mfma_f32_16x16x32_bf16 v[108:111], v[158:161], v[194:197], v[108:111]
	v_mfma_f32_16x16x32_bf16 v[100:103], v[144:147], v[202:205], v[100:103]
	v_mfma_f32_16x16x32_bf16 v[92:95], v[158:161], v[202:205], v[92:95]
	v_mfma_f32_16x16x32_bf16 v[84:87], v[144:147], v[210:213], v[84:87]
	v_mfma_f32_16x16x32_bf16 v[76:79], v[158:161], v[210:213], v[76:79]
	v_mfma_f32_16x16x32_bf16 v[124:127], v[154:157], v[190:193], v[124:127]
	v_mfma_f32_16x16x32_bf16 v[120:123], v[162:165], v[190:193], v[120:123]
	v_mfma_f32_16x16x32_bf16 v[116:119], v[154:157], v[198:201], v[116:119]
	v_mfma_f32_16x16x32_bf16 v[108:111], v[162:165], v[198:201], v[108:111]
	v_mfma_f32_16x16x32_bf16 v[100:103], v[154:157], v[206:209], v[100:103]
	v_mfma_f32_16x16x32_bf16 v[92:95], v[162:165], v[206:209], v[92:95]
	v_mfma_f32_16x16x32_bf16 v[84:87], v[154:157], v[214:217], v[84:87]
	v_mfma_f32_16x16x32_bf16 v[76:79], v[162:165], v[214:217], v[76:79]
	s_setprio 0
	s_setprio 1
	v_mfma_f32_16x16x32_bf16 v[112:115], v[166:169], v[186:189], v[112:115]
	v_mfma_f32_16x16x32_bf16 v[104:107], v[174:177], v[186:189], v[104:107]
	v_mfma_f32_16x16x32_bf16 v[96:99], v[166:169], v[194:197], v[96:99]
	v_mfma_f32_16x16x32_bf16 v[88:91], v[174:177], v[194:197], v[88:91]
	v_mfma_f32_16x16x32_bf16 v[80:83], v[166:169], v[202:205], v[80:83]
	v_mfma_f32_16x16x32_bf16 v[72:75], v[174:177], v[202:205], v[72:75]
	v_mfma_f32_16x16x32_bf16 v[68:71], v[166:169], v[210:213], v[68:71]
	v_mfma_f32_16x16x32_bf16 v[64:67], v[174:177], v[210:213], v[64:67]
	v_mfma_f32_16x16x32_bf16 v[112:115], v[170:173], v[190:193], v[112:115]
	v_mfma_f32_16x16x32_bf16 v[104:107], v[178:181], v[190:193], v[104:107]
	v_mfma_f32_16x16x32_bf16 v[96:99], v[170:173], v[198:201], v[96:99]
	v_mfma_f32_16x16x32_bf16 v[88:91], v[178:181], v[198:201], v[88:91]
	v_mfma_f32_16x16x32_bf16 v[80:83], v[170:173], v[206:209], v[80:83]
	v_mfma_f32_16x16x32_bf16 v[72:75], v[178:181], v[206:209], v[72:75]
	v_mfma_f32_16x16x32_bf16 v[68:71], v[170:173], v[214:217], v[68:71]
	v_mfma_f32_16x16x32_bf16 v[64:67], v[178:181], v[214:217], v[64:67]
	s_setprio 0
	s_barrier
; #define PG8_STAGE(bufoff, gbase, voff) do { _Pragma("unroll") for (int _i = 0; _i < 2; ++_i) \
;         __builtin_amdgcn_global_load_lds((const unsigned*)((const char*)(gbase) + (voff)[_i]), (PG8_LAS unsigned*)(lds + (bufoff) + ldsw + _i * 8192), 16, 0, 0); } while (0)
; #define PG8_LDA(dst, b, h) do { _Pragma("unroll") for (int m = 0; m < 4; ++m) _Pragma("unroll") for (int k = 0; k < 2; ++k) dst[m][k] = *(const PG8_LAS bf16x8*)(lds + PG8_SA(b, h) + aoff + m * 2048 + k * 1024); } while (0)
; #define PG8_MMA(ai, bj, At, Bt) do { __builtin_amdgcn_s_setprio(1); _Pragma("unroll") for (int m = 0; m < 4; ++m) _Pragma("unroll") for (int n = 0; n < 2; ++n) _Pragma("unroll") for (int k = 0; k < 2; ++k) \
;         acc[ai][bj][m][n] = __builtin_amdgcn_mfma_f32_16x16x32_bf16(Bt[n][k], At[m][k], acc[ai][bj][m][n], 0, 0, 0); __builtin_amdgcn_s_setprio(0); } while (0)
; #define PG8_WAIT_V(n) asm volatile("s_waitcnt vmcnt(" #n ")" ::: "memory")
; #define PG8_WAIT_L(n) asm volatile("s_waitcnt lgkmcnt(" #n ")" ::: "memory")
; #define PG8_BAR __builtin_amdgcn_s_barrier()
; #define PG8_SCHED __builtin_amdgcn_sched_barrier(0)
; template <class Epi, class Sched, bool ALIGN_EPI = false, bool SP2 = false>
; __device__ __forceinline__ void gemm_phase(PG8_LAS unsigned char* lds, const Gemm g, const Sched& S, const Epi& E) {
;     ...
;         for (int t = 0; t < nt; t += 2) {
;             const bool last = (t == nt - 2);
;             const char* a1 = cA + (size_t)(t + 1) * kstep;
;             const char* a2 = last ? nA : cA + (size_t)(t + 2) * kstep; const char* b2 = last ? nB : cB + (size_t)(t + 2) * kstep;
;             const char* a3 = a2 + kstep; const char* b3 = b2 + kstep;
;     ...
;             PG8_LDA(At, 1, 1); PG8_STAGE(PG8_SB(1, 0), b3, voffB); PG8_STAGE(PG8_SB(1, 1), b3 + hstep, voffB); PG8_STAGE(PG8_SA(1, 0), a3, voffA);
;             PG8_WAIT_V(8); PG8_WAIT_L(0); PG8_BAR; PG8_MMA(1, 0, At, B0); PG8_MMA(1, 1, At, B1); PG8_BAR; PG8_SCHED;
	s_add_i32 s24, s51, s30
	v_lshl_add_u64 v[182:183], v[182:183], 0, s[6:7]
	s_mov_b32 m0, s24
	ds_read_b128 v[186:189], v153 offset:49152
	ds_read_b128 v[190:193], v153 offset:50176
	ds_read_b128 v[194:197], v153 offset:51200
	ds_read_b128 v[198:201], v153 offset:52224
	ds_read_b128 v[202:205], v153 offset:53248
	ds_read_b128 v[206:209], v153 offset:54272
	ds_read_b128 v[210:213], v153 offset:55296
	ds_read_b128 v[214:217], v153 offset:56320
	global_load_lds_dwordx4 v[182:183], off
	s_add_i32 m0, s24, 0x2000
	s_add_u32 s22, s22, 0x40080
	v_lshl_add_u64 v[182:183], v[218:219], 0, s[6:7]
	s_addc_u32 s23, s23, 0
	s_add_i32 s24, s52, s30
	global_load_lds_dwordx4 v[182:183], off
	s_mov_b32 m0, s24
	v_lshl_add_u64 v[182:183], s[22:23], 0, v[132:133]
	global_load_lds_dwordx4 v[182:183], off
	s_add_i32 m0, s24, 0x2000
	v_lshl_add_u64 v[182:183], s[22:23], 0, v[128:129]
	global_load_lds_dwordx4 v[182:183], off
	s_mov_b32 m0, s37
	v_lshl_add_u64 v[182:183], v[220:221], 0, s[6:7]
	global_load_lds_dwordx4 v[182:183], off
	s_mov_b32 m0, s38
	v_lshl_add_u64 v[182:183], v[222:223], 0, s[6:7]
	global_load_lds_dwordx4 v[182:183], off
	s_waitcnt vmcnt(8)
	s_waitcnt lgkmcnt(0)
	s_barrier
	s_setprio 1
	s_waitcnt lgkmcnt(0)
	v_mfma_f32_16x16x32_bf16 v[60:63], v[144:147], v[186:189], v[60:63]
	v_mfma_f32_16x16x32_bf16 v[56:59], v[158:161], v[186:189], v[56:59]
	v_mfma_f32_16x16x32_bf16 v[52:55], v[144:147], v[194:197], v[52:55]
	v_mfma_f32_16x16x32_bf16 v[44:47], v[158:161], v[194:197], v[44:47]
	v_mfma_f32_16x16x32_bf16 v[36:39], v[144:147], v[202:205], v[36:39]
	v_mfma_f32_16x16x32_bf16 v[28:31], v[158:161], v[202:205], v[28:31]
	v_mfma_f32_16x16x32_bf16 v[20:23], v[144:147], v[210:213], v[20:23]
	v_mfma_f32_16x16x32_bf16 v[12:15], v[158:161], v[210:213], v[12:15]
	v_mfma_f32_16x16x32_bf16 v[60:63], v[154:157], v[190:193], v[60:63]
	v_mfma_f32_16x16x32_bf16 v[56:59], v[162:165], v[190:193], v[56:59]
	v_mfma_f32_16x16x32_bf16 v[52:55], v[154:157], v[198:201], v[52:55]
	v_mfma_f32_16x16x32_bf16 v[44:47], v[162:165], v[198:201], v[44:47]
	v_mfma_f32_16x16x32_bf16 v[36:39], v[154:157], v[206:209], v[36:39]
	v_mfma_f32_16x16x32_bf16 v[28:31], v[162:165], v[206:209], v[28:31]
	v_mfma_f32_16x16x32_bf16 v[20:23], v[154:157], v[214:217], v[20:23]
	v_mfma_f32_16x16x32_bf16 v[12:15], v[162:165], v[214:217], v[12:15]
	s_setprio 0
	s_setprio 1
	v_mfma_f32_16x16x32_bf16 v[48:51], v[166:169], v[186:189], v[48:51]
	v_mfma_f32_16x16x32_bf16 v[40:43], v[174:177], v[186:189], v[40:43]
	v_mfma_f32_16x16x32_bf16 v[32:35], v[166:169], v[194:197], v[32:35]
	v_mfma_f32_16x16x32_bf16 v[24:27], v[174:177], v[194:197], v[24:27]
	v_mfma_f32_16x16x32_bf16 v[16:19], v[166:169], v[202:205], v[16:19]
	v_mfma_f32_16x16x32_bf16 v[8:11], v[174:177], v[202:205], v[8:11]
	v_mfma_f32_16x16x32_bf16 v[4:7], v[166:169], v[210:213], v[4:7]
	v_mfma_f32_16x16x32_bf16 v[0:3], v[174:177], v[210:213], v[0:3]
	v_mfma_f32_16x16x32_bf16 v[48:51], v[170:173], v[190:193], v[48:51]
	v_mfma_f32_16x16x32_bf16 v[40:43], v[178:181], v[190:193], v[40:43]
	v_mfma_f32_16x16x32_bf16 v[32:35], v[170:173], v[198:201], v[32:35]
	v_mfma_f32_16x16x32_bf16 v[24:27], v[178:181], v[198:201], v[24:27]
	v_mfma_f32_16x16x32_bf16 v[16:19], v[170:173], v[206:209], v[16:19]
	v_mfma_f32_16x16x32_bf16 v[8:11], v[178:181], v[206:209], v[8:11]
	v_mfma_f32_16x16x32_bf16 v[4:7], v[170:173], v[214:217], v[4:7]
	v_mfma_f32_16x16x32_bf16 v[0:3], v[178:181], v[214:217], v[0:3]
	s_setprio 0
	s_barrier
	s_add_i32 s50, s50, 2
	s_add_u32 s48, s48, 0x100
	s_addc_u32 s49, s49, 0
	s_add_u32 s20, s20, 0x100
	s_addc_u32 s21, s21, 0
	s_cmp_gt_u32 s50, 13
	s_cbranch_scc0 .LBB0_343
	s_and_b64 vcc, exec, s[8:9]
	s_cbranch_vccz .LBB0_346
	s_barrier

; #define PG8_STAGE(bufoff, gbase, voff) do { _Pragma("unroll") for (int _i = 0; _i < 2; ++_i) \
;         __builtin_amdgcn_global_load_lds((const unsigned*)((const char*)(gbase) + (voff)[_i]), (PG8_LAS unsigned*)(lds + (bufoff) + ldsw + _i * 8192), 16, 0, 0); } while (0)
; #define PG8_LDA(dst, b, h) do { _Pragma("unroll") for (int m = 0; m < 4; ++m) _Pragma("unroll") for (int k = 0; k < 2; ++k) dst[m][k] = *(const PG8_LAS bf16x8*)(lds + PG8_SA(b, h) + aoff + m * 2048 + k * 1024); } while (0)
; #define PG8_LDB(dst, b, h) do { _Pragma("unroll") for (int n = 0; n < 2; ++n) _Pragma("unroll") for (int k = 0; k < 2; ++k) dst[n][k] = *(const PG8_LAS bf16x8*)(lds + PG8_SB(b, h) + boff + n * 2048 + k * 1024); } while (0)
; #define PG8_MMA(ai, bj, At, Bt) do { __builtin_amdgcn_s_setprio(1); _Pragma("unroll") for (int m = 0; m < 4; ++m) _Pragma("unroll") for (int n = 0; n < 2; ++n) _Pragma("unroll") for (int k = 0; k < 2; ++k) \
;         acc[ai][bj][m][n] = __builtin_amdgcn_mfma_f32_16x16x32_bf16(Bt[n][k], At[m][k], acc[ai][bj][m][n], 0, 0, 0); __builtin_amdgcn_s_setprio(0); } while (0)
; #define PG8_WAIT_V(n) asm volatile("s_waitcnt vmcnt(" #n ")" ::: "memory")
; #define PG8_WAIT_L(n) asm volatile("s_waitcnt lgkmcnt(" #n ")" ::: "memory")
; #define PG8_BAR __builtin_amdgcn_s_barrier()
; #define PG8_SCHED __builtin_amdgcn_sched_barrier(0)
; template <class Epi, class Sched, bool ALIGN_EPI = false, bool SP2 = false>
; __device__ __forceinline__ void gemm_phase(PG8_LAS unsigned char* lds, const Gemm g, const Sched& S, const Epi& E) {
;     ...
;         for (int t = 0; t < nt; t += 2) {
;             const bool last = (t == nt - 2);
;             const char* a1 = cA + (size_t)(t + 1) * kstep;
;             const char* a2 = last ? nA : cA + (size_t)(t + 2) * kstep; const char* b2 = last ? nB : cB + (size_t)(t + 2) * kstep;
;             const char* a3 = a2 + kstep; const char* b3 = b2 + kstep;
;             if (last && has_next) S.a_ready(nxt);
;             if constexpr (SP2) {
;             PG8_LDB(B0, 0, 0); PG8_LDB(B1, 0, 1); PG8_SCHED; PG8_LDA(At, 0, 0); PG8_STAGE(PG8_SA(1, 1), a1 + hstep, voffA);
;             PG8_WAIT_V(8); PG8_WAIT_L(0); PG8_BAR; PG8_MMA(0, 0, At, B0); PG8_MMA(0, 1, At, B1); PG8_BAR; PG8_SCHED;
;             PG8_LDA(At, 0, 1); PG8_STAGE(PG8_SB(0, 0), b2, voffB); PG8_STAGE(PG8_SB(0, 1), b2 + hstep, voffB); PG8_STAGE(PG8_SA(0, 0), a2, voffA);
.LBB0_424:
	ds_read_b128 v[140:143], v147
	ds_read_b128 v[150:153], v147 offset:1024
	ds_read_b128 v[154:157], v147 offset:2048
	ds_read_b128 v[158:161], v147 offset:3072
	ds_read_b128 v[162:165], v148
	ds_read_b128 v[166:169], v148 offset:1024
	ds_read_b128 v[170:173], v148 offset:2048
	ds_read_b128 v[174:177], v148 offset:3072
	s_add_u32 s22, s20, 0xfffc0080
	s_addc_u32 s23, s21, -1
	s_cmp_eq_u32 s48, 12
	s_cselect_b32 s25, s15, s23
	s_cselect_b32 s24, s44, s22
	s_cselect_b32 s23, s11, s47
	s_cselect_b32 s22, s45, s46
	v_lshl_add_u64 v[182:183], s[20:21], 0, v[138:139]
	s_add_i32 m0, s29, 0xc000
	ds_read_b128 v[178:181], v149
	ds_read_b128 v[186:189], v149 offset:1024
	ds_read_b128 v[190:193], v149 offset:2048
	ds_read_b128 v[194:197], v149 offset:3072
	ds_read_b128 v[198:201], v149 offset:4096
	ds_read_b128 v[202:205], v149 offset:5120
	ds_read_b128 v[206:209], v149 offset:6144
	ds_read_b128 v[210:213], v149 offset:7168
	global_load_lds_dwordx4 v[182:183], off
	s_add_i32 m0, s29, 0xe000
	v_lshl_add_u64 v[182:183], s[20:21], 0, v[136:137]
	global_load_lds_dwordx4 v[182:183], off
	s_waitcnt vmcnt(8)
	s_waitcnt lgkmcnt(0)
	s_barrier
	s_setprio 1
	s_waitcnt lgkmcnt(0)
	v_mfma_f32_16x16x32_bf16 v[124:127], v[140:143], v[178:181], v[124:127]
	v_mfma_f32_16x16x32_bf16 v[120:123], v[154:157], v[178:181], v[120:123]
	v_mfma_f32_16x16x32_bf16 v[116:119], v[140:143], v[190:193], v[116:119]
	v_mfma_f32_16x16x32_bf16 v[108:111], v[154:157], v[190:193], v[108:111]
	v_mfma_f32_16x16x32_bf16 v[100:103], v[140:143], v[198:201], v[100:103]
	v_mfma_f32_16x16x32_bf16 v[92:95], v[154:157], v[198:201], v[92:95]
	v_mfma_f32_16x16x32_bf16 v[84:87], v[140:143], v[206:209], v[84:87]
	v_mfma_f32_16x16x32_bf16 v[76:79], v[154:157], v[206:209], v[76:79]
	v_mfma_f32_16x16x32_bf16 v[124:127], v[150:153], v[186:189], v[124:127]
	v_mfma_f32_16x16x32_bf16 v[120:123], v[158:161], v[186:189], v[120:123]
	v_mfma_f32_16x16x32_bf16 v[116:119], v[150:153], v[194:197], v[116:119]
	v_mfma_f32_16x16x32_bf16 v[108:111], v[158:161], v[194:197], v[108:111]
	v_mfma_f32_16x16x32_bf16 v[100:103], v[150:153], v[202:205], v[100:103]
	v_mfma_f32_16x16x32_bf16 v[92:95], v[158:161], v[202:205], v[92:95]
	v_mfma_f32_16x16x32_bf16 v[84:87], v[150:153], v[210:213], v[84:87]
	v_mfma_f32_16x16x32_bf16 v[76:79], v[158:161], v[210:213], v[76:79]
	s_setprio 0
	s_setprio 1
	v_mfma_f32_16x16x32_bf16 v[112:115], v[162:165], v[178:181], v[112:115]
	v_mfma_f32_16x16x32_bf16 v[104:107], v[170:173], v[178:181], v[104:107]
	v_mfma_f32_16x16x32_bf16 v[96:99], v[162:165], v[190:193], v[96:99]
	v_mfma_f32_16x16x32_bf16 v[88:91], v[170:173], v[190:193], v[88:91]
	v_mfma_f32_16x16x32_bf16 v[80:83], v[162:165], v[198:201], v[80:83]
	v_mfma_f32_16x16x32_bf16 v[72:75], v[170:173], v[198:201], v[72:75]
	v_mfma_f32_16x16x32_bf16 v[68:71], v[162:165], v[206:209], v[68:71]
	v_mfma_f32_16x16x32_bf16 v[64:67], v[170:173], v[206:209], v[64:67]
	v_mfma_f32_16x16x32_bf16 v[112:115], v[166:169], v[186:189], v[112:115]
	v_mfma_f32_16x16x32_bf16 v[104:107], v[174:177], v[186:189], v[104:107]
	v_mfma_f32_16x16x32_bf16 v[96:99], v[166:169], v[194:197], v[96:99]
	v_mfma_f32_16x16x32_bf16 v[88:91], v[174:177], v[194:197], v[88:91]
	v_mfma_f32_16x16x32_bf16 v[80:83], v[166:169], v[202:205], v[80:83]
	v_mfma_f32_16x16x32_bf16 v[72:75], v[174:177], v[202:205], v[72:75]
	v_mfma_f32_16x16x32_bf16 v[68:71], v[166:169], v[210:213], v[68:71]
	v_mfma_f32_16x16x32_bf16 v[64:67], v[174:177], v[210:213], v[64:67]
	s_setprio 0
	s_barrier
	s_add_i32 s49, s38, s28
	v_lshl_add_u64 v[182:183], s[22:23], 0, v[130:131]
	s_mov_b32 m0, s49
	ds_read_b128 v[178:181], v149 offset:16384
	ds_read_b128 v[186:189], v149 offset:17408
	ds_read_b128 v[190:193], v149 offset:18432
	ds_read_b128 v[194:197], v149 offset:19456
	ds_read_b128 v[198:201], v149 offset:20480
	ds_read_b128 v[202:205], v149 offset:21504
	ds_read_b128 v[206:209], v149 offset:22528
	ds_read_b128 v[210:213], v149 offset:23552
	global_load_lds_dwordx4 v[182:183], off
	s_add_i32 m0, s49, 0x2000
	s_add_u32 s50, s22, 0x40000
	v_lshl_add_u64 v[214:215], s[22:23], 0, v[134:135]
	s_addc_u32 s51, s23, 0
	s_add_i32 s49, s39, s28
	global_load_lds_dwordx4 v[214:215], off
	v_lshl_add_u64 v[216:217], s[50:51], 0, v[130:131]
	s_mov_b32 m0, s49
	v_lshl_add_u64 v[218:219], s[24:25], 0, v[132:133]
	global_load_lds_dwordx4 v[216:217], off
	s_add_i32 m0, s49, 0x2000
	v_lshl_add_u64 v[216:217], s[50:51], 0, v[134:135]
	global_load_lds_dwordx4 v[216:217], off
	s_mov_b32 m0, s29
	v_lshl_add_u64 v[216:217], s[24:25], 0, v[128:129]
	global_load_lds_dwordx4 v[216:217], off
	s_mov_b32 m0, s30
	s_nop 0
	global_load_lds_dwordx4 v[218:219], off
	s_waitcnt vmcnt(8)
	s_waitcnt lgkmcnt(0)
	s_barrier
; #define PG8_STAGE(bufoff, gbase, voff) do { _Pragma("unroll") for (int _i = 0; _i < 2; ++_i) \
;         __builtin_amdgcn_global_load_lds((const unsigned*)((const char*)(gbase) + (voff)[_i]), (PG8_LAS unsigned*)(lds + (bufoff) + ldsw + _i * 8192), 16, 0, 0); } while (0)
; #define PG8_LDA(dst, b, h) do { _Pragma("unroll") for (int m = 0; m < 4; ++m) _Pragma("unroll") for (int k = 0; k < 2; ++k) dst[m][k] = *(const PG8_LAS bf16x8*)(lds + PG8_SA(b, h) + aoff + m * 2048 + k * 1024); } while (0)
; #define PG8_LDB(dst, b, h) do { _Pragma("unroll") for (int n = 0; n < 2; ++n) _Pragma("unroll") for (int k = 0; k < 2; ++k) dst[n][k] = *(const PG8_LAS bf16x8*)(lds + PG8_SB(b, h) + boff + n * 2048 + k * 1024); } while (0)
; #define PG8_MMA(ai, bj, At, Bt) do { __builtin_amdgcn_s_setprio(1); _Pragma("unroll") for (int m = 0; m < 4; ++m) _Pragma("unroll") for (int n = 0; n < 2; ++n) _Pragma("unroll") for (int k = 0; k < 2; ++k) \
;         acc[ai][bj][m][n] = __builtin_amdgcn_mfma_f32_16x16x32_bf16(Bt[n][k], At[m][k], acc[ai][bj][m][n], 0, 0, 0); __builtin_amdgcn_s_setprio(0); } while (0)
; #define PG8_WAIT_V(n) asm volatile("s_waitcnt vmcnt(" #n ")" ::: "memory")
; #define PG8_WAIT_L(n) asm volatile("s_waitcnt lgkmcnt(" #n ")" ::: "memory")
; #define PG8_BAR __builtin_amdgcn_s_barrier()
; #define PG8_SCHED __builtin_amdgcn_sched_barrier(0)
; template <class Epi, class Sched, bool ALIGN_EPI = false, bool SP2 = false>
; __device__ __forceinline__ void gemm_phase(PG8_LAS unsigned char* lds, const Gemm g, const Sched& S, const Epi& E) {
;     ...
;             PG8_WAIT_V(8); PG8_WAIT_L(0); PG8_BAR; PG8_MMA(1, 0, At, B0); PG8_MMA(1, 1, At, B1); PG8_BAR; PG8_SCHED;
;             PG8_LDB(B0, 1, 0); PG8_LDB(B1, 1, 1); PG8_SCHED; PG8_LDA(At, 1, 0); PG8_STAGE(PG8_SA(0, 1), a2 + hstep, voffA);
;             PG8_WAIT_V(8); PG8_WAIT_L(0); PG8_BAR; PG8_MMA(0, 0, At, B0); PG8_MMA(0, 1, At, B1); PG8_BAR; PG8_SCHED;
	s_setprio 1
	s_waitcnt lgkmcnt(0)
	v_mfma_f32_16x16x32_bf16 v[60:63], v[140:143], v[178:181], v[60:63]
	v_mfma_f32_16x16x32_bf16 v[56:59], v[154:157], v[178:181], v[56:59]
	v_mfma_f32_16x16x32_bf16 v[52:55], v[140:143], v[190:193], v[52:55]
	v_mfma_f32_16x16x32_bf16 v[44:47], v[154:157], v[190:193], v[44:47]
	v_mfma_f32_16x16x32_bf16 v[36:39], v[140:143], v[198:201], v[36:39]
	v_mfma_f32_16x16x32_bf16 v[28:31], v[154:157], v[198:201], v[28:31]
	v_mfma_f32_16x16x32_bf16 v[20:23], v[140:143], v[206:209], v[20:23]
	v_mfma_f32_16x16x32_bf16 v[12:15], v[154:157], v[206:209], v[12:15]
	v_mfma_f32_16x16x32_bf16 v[60:63], v[150:153], v[186:189], v[60:63]
	v_mfma_f32_16x16x32_bf16 v[56:59], v[158:161], v[186:189], v[56:59]
	v_mfma_f32_16x16x32_bf16 v[52:55], v[150:153], v[194:197], v[52:55]
	v_mfma_f32_16x16x32_bf16 v[44:47], v[158:161], v[194:197], v[44:47]
	v_mfma_f32_16x16x32_bf16 v[36:39], v[150:153], v[202:205], v[36:39]
	v_mfma_f32_16x16x32_bf16 v[28:31], v[158:161], v[202:205], v[28:31]
	v_mfma_f32_16x16x32_bf16 v[20:23], v[150:153], v[210:213], v[20:23]
	v_mfma_f32_16x16x32_bf16 v[12:15], v[158:161], v[210:213], v[12:15]
	s_setprio 0
	s_setprio 1
	v_mfma_f32_16x16x32_bf16 v[48:51], v[162:165], v[178:181], v[48:51]
	v_mfma_f32_16x16x32_bf16 v[40:43], v[170:173], v[178:181], v[40:43]
	v_mfma_f32_16x16x32_bf16 v[32:35], v[162:165], v[190:193], v[32:35]
	v_mfma_f32_16x16x32_bf16 v[24:27], v[170:173], v[190:193], v[24:27]
	v_mfma_f32_16x16x32_bf16 v[16:19], v[162:165], v[198:201], v[16:19]
	v_mfma_f32_16x16x32_bf16 v[8:11], v[170:173], v[198:201], v[8:11]
	v_mfma_f32_16x16x32_bf16 v[4:7], v[162:165], v[206:209], v[4:7]
	v_mfma_f32_16x16x32_bf16 v[0:3], v[170:173], v[206:209], v[0:3]
	v_mfma_f32_16x16x32_bf16 v[48:51], v[166:169], v[186:189], v[48:51]
	v_mfma_f32_16x16x32_bf16 v[40:43], v[174:177], v[186:189], v[40:43]
	v_mfma_f32_16x16x32_bf16 v[32:35], v[166:169], v[194:197], v[32:35]
	v_mfma_f32_16x16x32_bf16 v[24:27], v[174:177], v[194:197], v[24:27]
	v_mfma_f32_16x16x32_bf16 v[16:19], v[166:169], v[202:205], v[16:19]
	v_mfma_f32_16x16x32_bf16 v[8:11], v[174:177], v[202:205], v[8:11]
	v_mfma_f32_16x16x32_bf16 v[4:7], v[166:169], v[210:213], v[4:7]
	v_mfma_f32_16x16x32_bf16 v[0:3], v[174:177], v[210:213], v[0:3]
	s_setprio 0
	s_barrier
	s_add_i32 s49, 0, 0x18000
	s_add_i32 s50, 0, 0x1c000
	v_add_u32_e32 v158, s49, v145
	v_add_u32_e32 v174, s50, v145
	ds_read_b128 v[140:143], v158
	ds_read_b128 v[150:153], v158 offset:1024
	ds_read_b128 v[154:157], v158 offset:2048
	ds_read_b128 v[158:161], v158 offset:3072
	ds_read_b128 v[162:165], v174
	ds_read_b128 v[166:169], v174 offset:1024
	ds_read_b128 v[170:173], v174 offset:2048
	ds_read_b128 v[174:177], v174 offset:3072
	s_add_u32 s24, s24, 0x40000
	s_addc_u32 s25, s25, 0
	s_mov_b32 m0, s31
	v_lshl_add_u64 v[220:221], s[24:25], 0, v[128:129]
	ds_read_b128 v[178:181], v149 offset:32768
	ds_read_b128 v[186:189], v149 offset:33792
	ds_read_b128 v[190:193], v149 offset:34816
	ds_read_b128 v[194:197], v149 offset:35840
	ds_read_b128 v[198:201], v149 offset:36864
	ds_read_b128 v[202:205], v149 offset:37888
	ds_read_b128 v[206:209], v149 offset:38912
	ds_read_b128 v[210:213], v149 offset:39936
	global_load_lds_dwordx4 v[220:221], off
	s_mov_b32 m0, s33
	v_lshl_add_u64 v[220:221], s[24:25], 0, v[132:133]
	global_load_lds_dwordx4 v[220:221], off
	s_waitcnt vmcnt(8)
	s_waitcnt lgkmcnt(0)
	s_barrier
	s_setprio 1
	s_waitcnt lgkmcnt(0)
	v_mfma_f32_16x16x32_bf16 v[124:127], v[140:143], v[178:181], v[124:127]
	v_mfma_f32_16x16x32_bf16 v[120:123], v[154:157], v[178:181], v[120:123]
	v_mfma_f32_16x16x32_bf16 v[116:119], v[140:143], v[190:193], v[116:119]
	v_mfma_f32_16x16x32_bf16 v[108:111], v[154:157], v[190:193], v[108:111]
	v_mfma_f32_16x16x32_bf16 v[100:103], v[140:143], v[198:201], v[100:103]
	v_mfma_f32_16x16x32_bf16 v[92:95], v[154:157], v[198:201], v[92:95]
	v_mfma_f32_16x16x32_bf16 v[84:87], v[140:143], v[206:209], v[84:87]
	v_mfma_f32_16x16x32_bf16 v[76:79], v[154:157], v[206:209], v[76:79]
	v_mfma_f32_16x16x32_bf16 v[124:127], v[150:153], v[186:189], v[124:127]
	v_mfma_f32_16x16x32_bf16 v[120:123], v[158:161], v[186:189], v[120:123]
	v_mfma_f32_16x16x32_bf16 v[116:119], v[150:153], v[194:197], v[116:119]
	v_mfma_f32_16x16x32_bf16 v[108:111], v[158:161], v[194:197], v[108:111]
	v_mfma_f32_16x16x32_bf16 v[100:103], v[150:153], v[202:205], v[100:103]
	v_mfma_f32_16x16x32_bf16 v[92:95], v[158:161], v[202:205], v[92:95]
	v_mfma_f32_16x16x32_bf16 v[84:87], v[150:153], v[210:213], v[84:87]
	v_mfma_f32_16x16x32_bf16 v[76:79], v[158:161], v[210:213], v[76:79]
	s_setprio 0
	s_setprio 1
	v_mfma_f32_16x16x32_bf16 v[112:115], v[162:165], v[178:181], v[112:115]
	v_mfma_f32_16x16x32_bf16 v[104:107], v[170:173], v[178:181], v[104:107]
	v_mfma_f32_16x16x32_bf16 v[96:99], v[162:165], v[190:193], v[96:99]
	v_mfma_f32_16x16x32_bf16 v[88:91], v[170:173], v[190:193], v[88:91]
	v_mfma_f32_16x16x32_bf16 v[80:83], v[162:165], v[198:201], v[80:83]
	v_mfma_f32_16x16x32_bf16 v[72:75], v[170:173], v[198:201], v[72:75]
	v_mfma_f32_16x16x32_bf16 v[68:71], v[162:165], v[206:209], v[68:71]
	v_mfma_f32_16x16x32_bf16 v[64:67], v[170:173], v[206:209], v[64:67]
	v_mfma_f32_16x16x32_bf16 v[112:115], v[166:169], v[186:189], v[112:115]
	v_mfma_f32_16x16x32_bf16 v[104:107], v[174:177], v[186:189], v[104:107]
	v_mfma_f32_16x16x32_bf16 v[96:99], v[166:169], v[194:197], v[96:99]
	v_mfma_f32_16x16x32_bf16 v[88:91], v[174:177], v[194:197], v[88:91]
	v_mfma_f32_16x16x32_bf16 v[80:83], v[166:169], v[202:205], v[80:83]
	v_mfma_f32_16x16x32_bf16 v[72:75], v[174:177], v[202:205], v[72:75]
	v_mfma_f32_16x16x32_bf16 v[68:71], v[166:169], v[210:213], v[68:71]
	v_mfma_f32_16x16x32_bf16 v[64:67], v[174:177], v[210:213], v[64:67]
	s_setprio 0
	s_barrier
; #define PG8_STAGE(bufoff, gbase, voff) do { _Pragma("unroll") for (int _i = 0; _i < 2; ++_i) \
;         __builtin_amdgcn_global_load_lds((const unsigned*)((const char*)(gbase) + (voff)[_i]), (PG8_LAS unsigned*)(lds + (bufoff) + ldsw + _i * 8192), 16, 0, 0); } while (0)
; #define PG8_LDA(dst, b, h) do { _Pragma("unroll") for (int m = 0; m < 4; ++m) _Pragma("unroll") for (int k = 0; k < 2; ++k) dst[m][k] = *(const PG8_LAS bf16x8*)(lds + PG8_SA(b, h) + aoff + m * 2048 + k * 1024); } while (0)
; #define PG8_MMA(ai, bj, At, Bt) do { __builtin_amdgcn_s_setprio(1); _Pragma("unroll") for (int m = 0; m < 4; ++m) _Pragma("unroll") for (int n = 0; n < 2; ++n) _Pragma("unroll") for (int k = 0; k < 2; ++k) \
;         acc[ai][bj][m][n] = __builtin_amdgcn_mfma_f32_16x16x32_bf16(Bt[n][k], At[m][k], acc[ai][bj][m][n], 0, 0, 0); __builtin_amdgcn_s_setprio(0); } while (0)
; #define PG8_WAIT_V(n) asm volatile("s_waitcnt vmcnt(" #n ")" ::: "memory")
; #define PG8_WAIT_L(n) asm volatile("s_waitcnt lgkmcnt(" #n ")" ::: "memory")
; #define PG8_BAR __builtin_amdgcn_s_barrier()
; #define PG8_SCHED __builtin_amdgcn_sched_barrier(0)
; template <class Epi, class Sched, bool ALIGN_EPI = false, bool SP2 = false>
; __device__ __forceinline__ void gemm_phase(PG8_LAS unsigned char* lds, const Gemm g, const Sched& S, const Epi& E) {
;     ...
;         for (int t = 0; t < nt; t += 2) {
;             const bool last = (t == nt - 2);
;             const char* a1 = cA + (size_t)(t + 1) * kstep;
;             const char* a2 = last ? nA : cA + (size_t)(t + 2) * kstep; const char* b2 = last ? nB : cB + (size_t)(t + 2) * kstep;
;             const char* a3 = a2 + kstep; const char* b3 = b2 + kstep;
;     ...
;             PG8_LDA(At, 1, 1); PG8_STAGE(PG8_SB(1, 0), b3, voffB); PG8_STAGE(PG8_SB(1, 1), b3 + hstep, voffB); PG8_STAGE(PG8_SA(1, 0), a3, voffA);
;             PG8_WAIT_V(8); PG8_WAIT_L(0); PG8_BAR; PG8_MMA(1, 0, At, B0); PG8_MMA(1, 1, At, B1); PG8_BAR; PG8_SCHED;
	s_add_i32 s24, s49, s28
	v_lshl_add_u64 v[182:183], v[182:183], 0, s[6:7]
	s_mov_b32 m0, s24
	ds_read_b128 v[178:181], v149 offset:49152
	ds_read_b128 v[186:189], v149 offset:50176
	ds_read_b128 v[190:193], v149 offset:51200
	ds_read_b128 v[194:197], v149 offset:52224
	ds_read_b128 v[198:201], v149 offset:53248
	ds_read_b128 v[202:205], v149 offset:54272
	ds_read_b128 v[206:209], v149 offset:55296
	ds_read_b128 v[210:213], v149 offset:56320
	global_load_lds_dwordx4 v[182:183], off
	s_add_i32 m0, s24, 0x2000
	s_add_u32 s22, s22, 0x40080
	v_lshl_add_u64 v[182:183], v[214:215], 0, s[6:7]
	s_addc_u32 s23, s23, 0
	s_add_i32 s24, s50, s28
	global_load_lds_dwordx4 v[182:183], off
	s_mov_b32 m0, s24
	v_lshl_add_u64 v[182:183], s[22:23], 0, v[130:131]
	global_load_lds_dwordx4 v[182:183], off
	s_add_i32 m0, s24, 0x2000
	v_lshl_add_u64 v[182:183], s[22:23], 0, v[134:135]
	global_load_lds_dwordx4 v[182:183], off
	s_mov_b32 m0, s34
	v_lshl_add_u64 v[182:183], v[216:217], 0, s[6:7]
	global_load_lds_dwordx4 v[182:183], off
	s_mov_b32 m0, s35
	v_lshl_add_u64 v[182:183], v[218:219], 0, s[6:7]
	global_load_lds_dwordx4 v[182:183], off
	s_waitcnt vmcnt(8)
	s_waitcnt lgkmcnt(0)
	s_barrier
	s_setprio 1
	s_waitcnt lgkmcnt(0)
	v_mfma_f32_16x16x32_bf16 v[60:63], v[140:143], v[178:181], v[60:63]
	v_mfma_f32_16x16x32_bf16 v[56:59], v[154:157], v[178:181], v[56:59]
	v_mfma_f32_16x16x32_bf16 v[52:55], v[140:143], v[190:193], v[52:55]
	v_mfma_f32_16x16x32_bf16 v[44:47], v[154:157], v[190:193], v[44:47]
	v_mfma_f32_16x16x32_bf16 v[36:39], v[140:143], v[198:201], v[36:39]
	v_mfma_f32_16x16x32_bf16 v[28:31], v[154:157], v[198:201], v[28:31]
	v_mfma_f32_16x16x32_bf16 v[20:23], v[140:143], v[206:209], v[20:23]
	v_mfma_f32_16x16x32_bf16 v[12:15], v[154:157], v[206:209], v[12:15]
	v_mfma_f32_16x16x32_bf16 v[60:63], v[150:153], v[186:189], v[60:63]
	v_mfma_f32_16x16x32_bf16 v[56:59], v[158:161], v[186:189], v[56:59]
	v_mfma_f32_16x16x32_bf16 v[52:55], v[150:153], v[194:197], v[52:55]
	v_mfma_f32_16x16x32_bf16 v[44:47], v[158:161], v[194:197], v[44:47]
	v_mfma_f32_16x16x32_bf16 v[36:39], v[150:153], v[202:205], v[36:39]
	v_mfma_f32_16x16x32_bf16 v[28:31], v[158:161], v[202:205], v[28:31]
	v_mfma_f32_16x16x32_bf16 v[20:23], v[150:153], v[210:213], v[20:23]
	v_mfma_f32_16x16x32_bf16 v[12:15], v[158:161], v[210:213], v[12:15]
	s_setprio 0
	s_setprio 1
	v_mfma_f32_16x16x32_bf16 v[48:51], v[162:165], v[178:181], v[48:51]
	v_mfma_f32_16x16x32_bf16 v[40:43], v[170:173], v[178:181], v[40:43]
	v_mfma_f32_16x16x32_bf16 v[32:35], v[162:165], v[190:193], v[32:35]
	v_mfma_f32_16x16x32_bf16 v[24:27], v[170:173], v[190:193], v[24:27]
	v_mfma_f32_16x16x32_bf16 v[16:19], v[162:165], v[198:201], v[16:19]
	v_mfma_f32_16x16x32_bf16 v[8:11], v[170:173], v[198:201], v[8:11]
	v_mfma_f32_16x16x32_bf16 v[4:7], v[162:165], v[206:209], v[4:7]
	v_mfma_f32_16x16x32_bf16 v[0:3], v[170:173], v[206:209], v[0:3]
	v_mfma_f32_16x16x32_bf16 v[48:51], v[166:169], v[186:189], v[48:51]
	v_mfma_f32_16x16x32_bf16 v[40:43], v[174:177], v[186:189], v[40:43]
	v_mfma_f32_16x16x32_bf16 v[32:35], v[166:169], v[194:197], v[32:35]
	v_mfma_f32_16x16x32_bf16 v[24:27], v[174:177], v[194:197], v[24:27]
	v_mfma_f32_16x16x32_bf16 v[16:19], v[166:169], v[202:205], v[16:19]
	v_mfma_f32_16x16x32_bf16 v[8:11], v[174:177], v[202:205], v[8:11]
	v_mfma_f32_16x16x32_bf16 v[4:7], v[166:169], v[210:213], v[4:7]
	v_mfma_f32_16x16x32_bf16 v[0:3], v[174:177], v[210:213], v[0:3]
	s_setprio 0
	s_barrier
	s_add_i32 s48, s48, 2
	s_add_u32 s46, s46, 0x100
	s_addc_u32 s47, s47, 0
	s_add_u32 s20, s20, 0x100
	s_addc_u32 s21, s21, 0
	s_cmp_gt_u32 s48, 13
	s_cbranch_scc0 .LBB0_424
	s_and_b64 vcc, exec, s[8:9]
	s_cbranch_vccz .LBB0_427
	s_barrier

; #define PG8_STAGE(bufoff, gbase, voff) do { _Pragma("unroll") for (int _i = 0; _i < 2; ++_i) \
;         __builtin_amdgcn_global_load_lds((const unsigned*)((const char*)(gbase) + (voff)[_i]), (PG8_LAS unsigned*)(lds + (bufoff) + ldsw + _i * 8192), 16, 0, 0); } while (0)
; #define PG8_LDA(dst, b, h) do { _Pragma("unroll") for (int m = 0; m < 4; ++m) _Pragma("unroll") for (int k = 0; k < 2; ++k) dst[m][k] = *(const PG8_LAS bf16x8*)(lds + PG8_SA(b, h) + aoff + m * 2048 + k * 1024); } while (0)
; #define PG8_LDB(dst, b, h) do { _Pragma("unroll") for (int n = 0; n < 2; ++n) _Pragma("unroll") for (int k = 0; k < 2; ++k) dst[n][k] = *(const PG8_LAS bf16x8*)(lds + PG8_SB(b, h) + boff + n * 2048 + k * 1024); } while (0)
; #define PG8_MMA(ai, bj, At, Bt) do { __builtin_amdgcn_s_setprio(1); _Pragma("unroll") for (int m = 0; m < 4; ++m) _Pragma("unroll") for (int n = 0; n < 2; ++n) _Pragma("unroll") for (int k = 0; k < 2; ++k) \
;         acc[ai][bj][m][n] = __builtin_amdgcn_mfma_f32_16x16x32_bf16(Bt[n][k], At[m][k], acc[ai][bj][m][n], 0, 0, 0); __builtin_amdgcn_s_setprio(0); } while (0)
; #define PG8_WAIT_V(n) asm volatile("s_waitcnt vmcnt(" #n ")" ::: "memory")
; #define PG8_WAIT_L(n) asm volatile("s_waitcnt lgkmcnt(" #n ")" ::: "memory")
; #define PG8_BAR __builtin_amdgcn_s_barrier()
; #define PG8_SCHED __builtin_amdgcn_sched_barrier(0)
; template <class Epi, class Sched, bool ALIGN_EPI = false, bool SP2 = false>
; __device__ __forceinline__ void gemm_phase(PG8_LAS unsigned char* lds, const Gemm g, const Sched& S, const Epi& E) {
;     ...
;         for (int t = 0; t < nt; t += 2) {
;             const bool last = (t == nt - 2);
;             const char* a1 = cA + (size_t)(t + 1) * kstep;
;             const char* a2 = last ? nA : cA + (size_t)(t + 2) * kstep; const char* b2 = last ? nB : cB + (size_t)(t + 2) * kstep;
;             const char* a3 = a2 + kstep; const char* b3 = b2 + kstep;
;             if (last && has_next) S.a_ready(nxt);
;             if constexpr (SP2) {
;             PG8_LDB(B0, 0, 0); PG8_LDB(B1, 0, 1); PG8_SCHED; PG8_LDA(At, 0, 0); PG8_STAGE(PG8_SA(1, 1), a1 + hstep, voffA);
;             PG8_WAIT_V(8); PG8_WAIT_L(0); PG8_BAR; PG8_MMA(0, 0, At, B0); PG8_MMA(0, 1, At, B1); PG8_BAR; PG8_SCHED;
;             PG8_LDA(At, 0, 1); PG8_STAGE(PG8_SB(0, 0), b2, voffB); PG8_STAGE(PG8_SB(0, 1), b2 + hstep, voffB); PG8_STAGE(PG8_SA(0, 0), a2, voffA);
.LBB0_515:
	ds_read_b128 v[144:147], v151
	ds_read_b128 v[154:157], v151 offset:1024
	ds_read_b128 v[158:161], v151 offset:2048
	ds_read_b128 v[162:165], v151 offset:3072
	ds_read_b128 v[166:169], v152
	ds_read_b128 v[170:173], v152 offset:1024
	ds_read_b128 v[174:177], v152 offset:2048
	ds_read_b128 v[178:181], v152 offset:3072
	s_add_u32 s16, s14, 0x100
	s_addc_u32 s17, s15, 0
	s_cmp_eq_u32 s48, 2
	s_cselect_b32 s21, s5, s17
	s_cselect_b32 s20, s4, s16
	s_cselect_b32 s19, s13, s47
	s_cselect_b32 s18, s12, s46
	v_lshl_add_u64 v[182:183], s[14:15], 0, v[138:139]
	s_add_i32 m0, s29, 0xc000
	ds_read_b128 v[186:189], v153
	ds_read_b128 v[190:193], v153 offset:1024
	ds_read_b128 v[194:197], v153 offset:2048
	ds_read_b128 v[198:201], v153 offset:3072
	ds_read_b128 v[202:205], v153 offset:4096
	ds_read_b128 v[206:209], v153 offset:5120
	ds_read_b128 v[210:213], v153 offset:6144
	ds_read_b128 v[214:217], v153 offset:7168
	global_load_lds_dwordx4 v[182:183], off
	s_add_i32 m0, s29, 0xe000
	v_lshl_add_u64 v[182:183], s[14:15], 0, v[136:137]
	global_load_lds_dwordx4 v[182:183], off
	s_waitcnt vmcnt(8)
	s_waitcnt lgkmcnt(0)
	s_barrier
	s_setprio 1
	s_waitcnt lgkmcnt(0)
	v_mfma_f32_16x16x32_bf16 v[124:127], v[144:147], v[186:189], v[124:127]
	v_mfma_f32_16x16x32_bf16 v[120:123], v[158:161], v[186:189], v[120:123]
	v_mfma_f32_16x16x32_bf16 v[116:119], v[144:147], v[194:197], v[116:119]
	v_mfma_f32_16x16x32_bf16 v[108:111], v[158:161], v[194:197], v[108:111]
	v_mfma_f32_16x16x32_bf16 v[100:103], v[144:147], v[202:205], v[100:103]
	v_mfma_f32_16x16x32_bf16 v[92:95], v[158:161], v[202:205], v[92:95]
	v_mfma_f32_16x16x32_bf16 v[84:87], v[144:147], v[210:213], v[84:87]
	v_mfma_f32_16x16x32_bf16 v[76:79], v[158:161], v[210:213], v[76:79]
	v_mfma_f32_16x16x32_bf16 v[124:127], v[154:157], v[190:193], v[124:127]
	v_mfma_f32_16x16x32_bf16 v[120:123], v[162:165], v[190:193], v[120:123]
	v_mfma_f32_16x16x32_bf16 v[116:119], v[154:157], v[198:201], v[116:119]
	v_mfma_f32_16x16x32_bf16 v[108:111], v[162:165], v[198:201], v[108:111]
	v_mfma_f32_16x16x32_bf16 v[100:103], v[154:157], v[206:209], v[100:103]
	v_mfma_f32_16x16x32_bf16 v[92:95], v[162:165], v[206:209], v[92:95]
	v_mfma_f32_16x16x32_bf16 v[84:87], v[154:157], v[214:217], v[84:87]
	v_mfma_f32_16x16x32_bf16 v[76:79], v[162:165], v[214:217], v[76:79]
	s_setprio 0
	s_setprio 1
	v_mfma_f32_16x16x32_bf16 v[112:115], v[166:169], v[186:189], v[112:115]
	v_mfma_f32_16x16x32_bf16 v[104:107], v[174:177], v[186:189], v[104:107]
	v_mfma_f32_16x16x32_bf16 v[96:99], v[166:169], v[194:197], v[96:99]
	v_mfma_f32_16x16x32_bf16 v[88:91], v[174:177], v[194:197], v[88:91]
	v_mfma_f32_16x16x32_bf16 v[80:83], v[166:169], v[202:205], v[80:83]
	v_mfma_f32_16x16x32_bf16 v[72:75], v[174:177], v[202:205], v[72:75]
	v_mfma_f32_16x16x32_bf16 v[68:71], v[166:169], v[210:213], v[68:71]
	v_mfma_f32_16x16x32_bf16 v[64:67], v[174:177], v[210:213], v[64:67]
	v_mfma_f32_16x16x32_bf16 v[112:115], v[170:173], v[190:193], v[112:115]
	v_mfma_f32_16x16x32_bf16 v[104:107], v[178:181], v[190:193], v[104:107]
	v_mfma_f32_16x16x32_bf16 v[96:99], v[170:173], v[198:201], v[96:99]
	v_mfma_f32_16x16x32_bf16 v[88:91], v[178:181], v[198:201], v[88:91]
	v_mfma_f32_16x16x32_bf16 v[80:83], v[170:173], v[206:209], v[80:83]
	v_mfma_f32_16x16x32_bf16 v[72:75], v[178:181], v[206:209], v[72:75]
	v_mfma_f32_16x16x32_bf16 v[68:71], v[170:173], v[214:217], v[68:71]
	v_mfma_f32_16x16x32_bf16 v[64:67], v[178:181], v[214:217], v[64:67]
	s_setprio 0
	s_barrier
	s_add_i32 s14, s39, s28
	v_lshl_add_u64 v[182:183], s[18:19], 0, v[130:131]
	s_mov_b32 m0, s14
	ds_read_b128 v[186:189], v153 offset:16384
	ds_read_b128 v[190:193], v153 offset:17408
	ds_read_b128 v[194:197], v153 offset:18432
	ds_read_b128 v[198:201], v153 offset:19456
	ds_read_b128 v[202:205], v153 offset:20480
	ds_read_b128 v[206:209], v153 offset:21504
	ds_read_b128 v[210:213], v153 offset:22528
	ds_read_b128 v[214:217], v153 offset:23552
	global_load_lds_dwordx4 v[182:183], off
	s_add_i32 m0, s14, 0x2000
	s_add_u32 s14, s18, 0x18000
	v_lshl_add_u64 v[218:219], s[18:19], 0, v[134:135]
	s_addc_u32 s15, s19, 0
	s_add_i32 s49, s40, s28
	global_load_lds_dwordx4 v[218:219], off
	v_lshl_add_u64 v[220:221], s[14:15], 0, v[130:131]
	s_mov_b32 m0, s49
	v_lshl_add_u64 v[222:223], s[20:21], 0, v[132:133]
	global_load_lds_dwordx4 v[220:221], off
	s_add_i32 m0, s49, 0x2000
	v_lshl_add_u64 v[220:221], s[14:15], 0, v[134:135]
	global_load_lds_dwordx4 v[220:221], off
	s_mov_b32 m0, s29
	v_lshl_add_u64 v[220:221], s[20:21], 0, v[128:129]
	global_load_lds_dwordx4 v[220:221], off
	s_mov_b32 m0, s30
	s_nop 0
	global_load_lds_dwordx4 v[222:223], off
	s_waitcnt vmcnt(8)
	s_waitcnt lgkmcnt(0)
	s_barrier
; #define PG8_STAGE(bufoff, gbase, voff) do { _Pragma("unroll") for (int _i = 0; _i < 2; ++_i) \
;         __builtin_amdgcn_global_load_lds((const unsigned*)((const char*)(gbase) + (voff)[_i]), (PG8_LAS unsigned*)(lds + (bufoff) + ldsw + _i * 8192), 16, 0, 0); } while (0)
; #define PG8_LDA(dst, b, h) do { _Pragma("unroll") for (int m = 0; m < 4; ++m) _Pragma("unroll") for (int k = 0; k < 2; ++k) dst[m][k] = *(const PG8_LAS bf16x8*)(lds + PG8_SA(b, h) + aoff + m * 2048 + k * 1024); } while (0)
; #define PG8_LDB(dst, b, h) do { _Pragma("unroll") for (int n = 0; n < 2; ++n) _Pragma("unroll") for (int k = 0; k < 2; ++k) dst[n][k] = *(const PG8_LAS bf16x8*)(lds + PG8_SB(b, h) + boff + n * 2048 + k * 1024); } while (0)
; #define PG8_MMA(ai, bj, At, Bt) do { __builtin_amdgcn_s_setprio(1); _Pragma("unroll") for (int m = 0; m < 4; ++m) _Pragma("unroll") for (int n = 0; n < 2; ++n) _Pragma("unroll") for (int k = 0; k < 2; ++k) \
;         acc[ai][bj][m][n] = __builtin_amdgcn_mfma_f32_16x16x32_bf16(Bt[n][k], At[m][k], acc[ai][bj][m][n], 0, 0, 0); __builtin_amdgcn_s_setprio(0); } while (0)
; #define PG8_WAIT_V(n) asm volatile("s_waitcnt vmcnt(" #n ")" ::: "memory")
; #define PG8_WAIT_L(n) asm volatile("s_waitcnt lgkmcnt(" #n ")" ::: "memory")
; #define PG8_BAR __builtin_amdgcn_s_barrier()
; #define PG8_SCHED __builtin_amdgcn_sched_barrier(0)
; template <class Epi, class Sched, bool ALIGN_EPI = false, bool SP2 = false>
; __device__ __forceinline__ void gemm_phase(PG8_LAS unsigned char* lds, const Gemm g, const Sched& S, const Epi& E) {
;     ...
;             PG8_WAIT_V(8); PG8_WAIT_L(0); PG8_BAR; PG8_MMA(1, 0, At, B0); PG8_MMA(1, 1, At, B1); PG8_BAR; PG8_SCHED;
;             PG8_LDB(B0, 1, 0); PG8_LDB(B1, 1, 1); PG8_SCHED; PG8_LDA(At, 1, 0); PG8_STAGE(PG8_SA(0, 1), a2 + hstep, voffA);
;             PG8_WAIT_V(8); PG8_WAIT_L(0); PG8_BAR; PG8_MMA(0, 0, At, B0); PG8_MMA(0, 1, At, B1); PG8_BAR; PG8_SCHED;
	s_setprio 1
	s_waitcnt lgkmcnt(0)
	v_mfma_f32_16x16x32_bf16 v[60:63], v[144:147], v[186:189], v[60:63]
	v_mfma_f32_16x16x32_bf16 v[56:59], v[158:161], v[186:189], v[56:59]
	v_mfma_f32_16x16x32_bf16 v[52:55], v[144:147], v[194:197], v[52:55]
	v_mfma_f32_16x16x32_bf16 v[44:47], v[158:161], v[194:197], v[44:47]
	v_mfma_f32_16x16x32_bf16 v[36:39], v[144:147], v[202:205], v[36:39]
	v_mfma_f32_16x16x32_bf16 v[28:31], v[158:161], v[202:205], v[28:31]
	v_mfma_f32_16x16x32_bf16 v[20:23], v[144:147], v[210:213], v[20:23]
	v_mfma_f32_16x16x32_bf16 v[12:15], v[158:161], v[210:213], v[12:15]
	v_mfma_f32_16x16x32_bf16 v[60:63], v[154:157], v[190:193], v[60:63]
	v_mfma_f32_16x16x32_bf16 v[56:59], v[162:165], v[190:193], v[56:59]
	v_mfma_f32_16x16x32_bf16 v[52:55], v[154:157], v[198:201], v[52:55]
	v_mfma_f32_16x16x32_bf16 v[44:47], v[162:165], v[198:201], v[44:47]
	v_mfma_f32_16x16x32_bf16 v[36:39], v[154:157], v[206:209], v[36:39]
	v_mfma_f32_16x16x32_bf16 v[28:31], v[162:165], v[206:209], v[28:31]
	v_mfma_f32_16x16x32_bf16 v[20:23], v[154:157], v[214:217], v[20:23]
	v_mfma_f32_16x16x32_bf16 v[12:15], v[162:165], v[214:217], v[12:15]
	s_setprio 0
	s_setprio 1
	v_mfma_f32_16x16x32_bf16 v[48:51], v[166:169], v[186:189], v[48:51]
	v_mfma_f32_16x16x32_bf16 v[40:43], v[174:177], v[186:189], v[40:43]
	v_mfma_f32_16x16x32_bf16 v[32:35], v[166:169], v[194:197], v[32:35]
	v_mfma_f32_16x16x32_bf16 v[24:27], v[174:177], v[194:197], v[24:27]
	v_mfma_f32_16x16x32_bf16 v[16:19], v[166:169], v[202:205], v[16:19]
	v_mfma_f32_16x16x32_bf16 v[8:11], v[174:177], v[202:205], v[8:11]
	v_mfma_f32_16x16x32_bf16 v[4:7], v[166:169], v[210:213], v[4:7]
	v_mfma_f32_16x16x32_bf16 v[0:3], v[174:177], v[210:213], v[0:3]
	v_mfma_f32_16x16x32_bf16 v[48:51], v[170:173], v[190:193], v[48:51]
	v_mfma_f32_16x16x32_bf16 v[40:43], v[178:181], v[190:193], v[40:43]
	v_mfma_f32_16x16x32_bf16 v[32:35], v[170:173], v[198:201], v[32:35]
	v_mfma_f32_16x16x32_bf16 v[24:27], v[178:181], v[198:201], v[24:27]
	v_mfma_f32_16x16x32_bf16 v[16:19], v[170:173], v[206:209], v[16:19]
	v_mfma_f32_16x16x32_bf16 v[8:11], v[178:181], v[206:209], v[8:11]
	v_mfma_f32_16x16x32_bf16 v[4:7], v[170:173], v[214:217], v[4:7]
	v_mfma_f32_16x16x32_bf16 v[0:3], v[178:181], v[214:217], v[0:3]
	s_setprio 0
	s_barrier
	s_add_i32 s49, 0, 0x18000
	s_add_i32 s50, 0, 0x1c000
	v_add_u32_e32 v162, s49, v149
	v_add_u32_e32 v178, s50, v149
	ds_read_b128 v[144:147], v162
	ds_read_b128 v[154:157], v162 offset:1024
	ds_read_b128 v[158:161], v162 offset:2048
	ds_read_b128 v[162:165], v162 offset:3072
	ds_read_b128 v[166:169], v178
	ds_read_b128 v[170:173], v178 offset:1024
	ds_read_b128 v[174:177], v178 offset:2048
	ds_read_b128 v[178:181], v178 offset:3072
	s_add_u32 s14, s20, 0x18000
	s_addc_u32 s15, s21, 0
	s_mov_b32 m0, s31
	v_lshl_add_u64 v[224:225], s[14:15], 0, v[128:129]
	ds_read_b128 v[186:189], v153 offset:32768
	ds_read_b128 v[190:193], v153 offset:33792
	ds_read_b128 v[194:197], v153 offset:34816
	ds_read_b128 v[198:201], v153 offset:35840
	ds_read_b128 v[202:205], v153 offset:36864
	ds_read_b128 v[206:209], v153 offset:37888
	ds_read_b128 v[210:213], v153 offset:38912
	ds_read_b128 v[214:217], v153 offset:39936
	global_load_lds_dwordx4 v[224:225], off
	s_mov_b32 m0, s33
	v_lshl_add_u64 v[224:225], s[14:15], 0, v[132:133]
	global_load_lds_dwordx4 v[224:225], off
	s_waitcnt vmcnt(8)
	s_waitcnt lgkmcnt(0)
	s_barrier
	s_setprio 1
	s_waitcnt lgkmcnt(0)
	v_mfma_f32_16x16x32_bf16 v[124:127], v[144:147], v[186:189], v[124:127]
	v_mfma_f32_16x16x32_bf16 v[120:123], v[158:161], v[186:189], v[120:123]
	v_mfma_f32_16x16x32_bf16 v[116:119], v[144:147], v[194:197], v[116:119]
	v_mfma_f32_16x16x32_bf16 v[108:111], v[158:161], v[194:197], v[108:111]
	v_mfma_f32_16x16x32_bf16 v[100:103], v[144:147], v[202:205], v[100:103]
	v_mfma_f32_16x16x32_bf16 v[92:95], v[158:161], v[202:205], v[92:95]
	v_mfma_f32_16x16x32_bf16 v[84:87], v[144:147], v[210:213], v[84:87]
	v_mfma_f32_16x16x32_bf16 v[76:79], v[158:161], v[210:213], v[76:79]
	v_mfma_f32_16x16x32_bf16 v[124:127], v[154:157], v[190:193], v[124:127]
	v_mfma_f32_16x16x32_bf16 v[120:123], v[162:165], v[190:193], v[120:123]
	v_mfma_f32_16x16x32_bf16 v[116:119], v[154:157], v[198:201], v[116:119]
	v_mfma_f32_16x16x32_bf16 v[108:111], v[162:165], v[198:201], v[108:111]
	v_mfma_f32_16x16x32_bf16 v[100:103], v[154:157], v[206:209], v[100:103]
	v_mfma_f32_16x16x32_bf16 v[92:95], v[162:165], v[206:209], v[92:95]
	v_mfma_f32_16x16x32_bf16 v[84:87], v[154:157], v[214:217], v[84:87]
	v_mfma_f32_16x16x32_bf16 v[76:79], v[162:165], v[214:217], v[76:79]
	s_setprio 0
	s_setprio 1
	v_mfma_f32_16x16x32_bf16 v[112:115], v[166:169], v[186:189], v[112:115]
	v_mfma_f32_16x16x32_bf16 v[104:107], v[174:177], v[186:189], v[104:107]
	v_mfma_f32_16x16x32_bf16 v[96:99], v[166:169], v[194:197], v[96:99]
	v_mfma_f32_16x16x32_bf16 v[88:91], v[174:177], v[194:197], v[88:91]
	v_mfma_f32_16x16x32_bf16 v[80:83], v[166:169], v[202:205], v[80:83]
	v_mfma_f32_16x16x32_bf16 v[72:75], v[174:177], v[202:205], v[72:75]
	v_mfma_f32_16x16x32_bf16 v[68:71], v[166:169], v[210:213], v[68:71]
	v_mfma_f32_16x16x32_bf16 v[64:67], v[174:177], v[210:213], v[64:67]
	v_mfma_f32_16x16x32_bf16 v[112:115], v[170:173], v[190:193], v[112:115]
	v_mfma_f32_16x16x32_bf16 v[104:107], v[178:181], v[190:193], v[104:107]
	v_mfma_f32_16x16x32_bf16 v[96:99], v[170:173], v[198:201], v[96:99]
	v_mfma_f32_16x16x32_bf16 v[88:91], v[178:181], v[198:201], v[88:91]
	v_mfma_f32_16x16x32_bf16 v[80:83], v[170:173], v[206:209], v[80:83]
	v_mfma_f32_16x16x32_bf16 v[72:75], v[178:181], v[206:209], v[72:75]
	v_mfma_f32_16x16x32_bf16 v[68:71], v[170:173], v[214:217], v[68:71]
	v_mfma_f32_16x16x32_bf16 v[64:67], v[178:181], v[214:217], v[64:67]
	s_setprio 0
	s_barrier
; #define PG8_STAGE(bufoff, gbase, voff) do { _Pragma("unroll") for (int _i = 0; _i < 2; ++_i) \
;         __builtin_amdgcn_global_load_lds((const unsigned*)((const char*)(gbase) + (voff)[_i]), (PG8_LAS unsigned*)(lds + (bufoff) + ldsw + _i * 8192), 16, 0, 0); } while (0)
; #define PG8_LDA(dst, b, h) do { _Pragma("unroll") for (int m = 0; m < 4; ++m) _Pragma("unroll") for (int k = 0; k < 2; ++k) dst[m][k] = *(const PG8_LAS bf16x8*)(lds + PG8_SA(b, h) + aoff + m * 2048 + k * 1024); } while (0)
; #define PG8_MMA(ai, bj, At, Bt) do { __builtin_amdgcn_s_setprio(1); _Pragma("unroll") for (int m = 0; m < 4; ++m) _Pragma("unroll") for (int n = 0; n < 2; ++n) _Pragma("unroll") for (int k = 0; k < 2; ++k) \
;         acc[ai][bj][m][n] = __builtin_amdgcn_mfma_f32_16x16x32_bf16(Bt[n][k], At[m][k], acc[ai][bj][m][n], 0, 0, 0); __builtin_amdgcn_s_setprio(0); } while (0)
; #define PG8_WAIT_V(n) asm volatile("s_waitcnt vmcnt(" #n ")" ::: "memory")
; #define PG8_WAIT_L(n) asm volatile("s_waitcnt lgkmcnt(" #n ")" ::: "memory")
; #define PG8_BAR __builtin_amdgcn_s_barrier()
; #define PG8_SCHED __builtin_amdgcn_sched_barrier(0)
; template <class Epi, class Sched, bool ALIGN_EPI = false, bool SP2 = false>
; __device__ __forceinline__ void gemm_phase(PG8_LAS unsigned char* lds, const Gemm g, const Sched& S, const Epi& E) {
;     ...
;         for (int t = 0; t < nt; t += 2) {
;             const bool last = (t == nt - 2);
;             const char* a1 = cA + (size_t)(t + 1) * kstep;
;             const char* a2 = last ? nA : cA + (size_t)(t + 2) * kstep; const char* b2 = last ? nB : cB + (size_t)(t + 2) * kstep;
;             const char* a3 = a2 + kstep; const char* b3 = b2 + kstep;
;     ...
;             PG8_LDA(At, 1, 1); PG8_STAGE(PG8_SB(1, 0), b3, voffB); PG8_STAGE(PG8_SB(1, 1), b3 + hstep, voffB); PG8_STAGE(PG8_SA(1, 0), a3, voffA);
;             PG8_WAIT_V(8); PG8_WAIT_L(0); PG8_BAR; PG8_MMA(1, 0, At, B0); PG8_MMA(1, 1, At, B1); PG8_BAR; PG8_SCHED;
	s_add_i32 s14, s49, s28
	v_lshl_add_u64 v[182:183], v[182:183], 0, s[8:9]
	s_mov_b32 m0, s14
	ds_read_b128 v[186:189], v153 offset:49152
	ds_read_b128 v[190:193], v153 offset:50176
	ds_read_b128 v[194:197], v153 offset:51200
	ds_read_b128 v[198:201], v153 offset:52224
	ds_read_b128 v[202:205], v153 offset:53248
	ds_read_b128 v[206:209], v153 offset:54272
	ds_read_b128 v[210:213], v153 offset:55296
	ds_read_b128 v[214:217], v153 offset:56320
	global_load_lds_dwordx4 v[182:183], off
	s_add_i32 m0, s14, 0x2000
	s_add_u32 s14, s18, 0x18080
	v_lshl_add_u64 v[182:183], v[218:219], 0, s[8:9]
	s_addc_u32 s15, s19, 0
	s_add_i32 s18, s50, s28
	global_load_lds_dwordx4 v[182:183], off
	s_mov_b32 m0, s18
	v_lshl_add_u64 v[182:183], s[14:15], 0, v[130:131]
	global_load_lds_dwordx4 v[182:183], off
	s_add_i32 m0, s18, 0x2000
	v_lshl_add_u64 v[182:183], s[14:15], 0, v[134:135]
	global_load_lds_dwordx4 v[182:183], off
	s_mov_b32 m0, s35
	v_lshl_add_u64 v[182:183], v[220:221], 0, s[8:9]
	global_load_lds_dwordx4 v[182:183], off
	s_mov_b32 m0, s36
	v_lshl_add_u64 v[182:183], v[222:223], 0, s[8:9]
	global_load_lds_dwordx4 v[182:183], off
	s_waitcnt vmcnt(8)
	s_waitcnt lgkmcnt(0)
	s_barrier
	s_setprio 1
	s_waitcnt lgkmcnt(0)
	v_mfma_f32_16x16x32_bf16 v[60:63], v[144:147], v[186:189], v[60:63]
	v_mfma_f32_16x16x32_bf16 v[56:59], v[158:161], v[186:189], v[56:59]
	v_mfma_f32_16x16x32_bf16 v[52:55], v[144:147], v[194:197], v[52:55]
	v_mfma_f32_16x16x32_bf16 v[44:47], v[158:161], v[194:197], v[44:47]
	v_mfma_f32_16x16x32_bf16 v[36:39], v[144:147], v[202:205], v[36:39]
	v_mfma_f32_16x16x32_bf16 v[28:31], v[158:161], v[202:205], v[28:31]
	v_mfma_f32_16x16x32_bf16 v[20:23], v[144:147], v[210:213], v[20:23]
	v_mfma_f32_16x16x32_bf16 v[12:15], v[158:161], v[210:213], v[12:15]
	v_mfma_f32_16x16x32_bf16 v[60:63], v[154:157], v[190:193], v[60:63]
	v_mfma_f32_16x16x32_bf16 v[56:59], v[162:165], v[190:193], v[56:59]
	v_mfma_f32_16x16x32_bf16 v[52:55], v[154:157], v[198:201], v[52:55]
	v_mfma_f32_16x16x32_bf16 v[44:47], v[162:165], v[198:201], v[44:47]
	v_mfma_f32_16x16x32_bf16 v[36:39], v[154:157], v[206:209], v[36:39]
	v_mfma_f32_16x16x32_bf16 v[28:31], v[162:165], v[206:209], v[28:31]
	v_mfma_f32_16x16x32_bf16 v[20:23], v[154:157], v[214:217], v[20:23]
	v_mfma_f32_16x16x32_bf16 v[12:15], v[162:165], v[214:217], v[12:15]
	s_setprio 0
	s_setprio 1
	v_mfma_f32_16x16x32_bf16 v[48:51], v[166:169], v[186:189], v[48:51]
	v_mfma_f32_16x16x32_bf16 v[40:43], v[174:177], v[186:189], v[40:43]
	v_mfma_f32_16x16x32_bf16 v[32:35], v[166:169], v[194:197], v[32:35]
	v_mfma_f32_16x16x32_bf16 v[24:27], v[174:177], v[194:197], v[24:27]
	v_mfma_f32_16x16x32_bf16 v[16:19], v[166:169], v[202:205], v[16:19]
	v_mfma_f32_16x16x32_bf16 v[8:11], v[174:177], v[202:205], v[8:11]
	v_mfma_f32_16x16x32_bf16 v[4:7], v[166:169], v[210:213], v[4:7]
	v_mfma_f32_16x16x32_bf16 v[0:3], v[174:177], v[210:213], v[0:3]
	v_mfma_f32_16x16x32_bf16 v[48:51], v[170:173], v[190:193], v[48:51]
	v_mfma_f32_16x16x32_bf16 v[40:43], v[178:181], v[190:193], v[40:43]
	v_mfma_f32_16x16x32_bf16 v[32:35], v[170:173], v[198:201], v[32:35]
	v_mfma_f32_16x16x32_bf16 v[24:27], v[178:181], v[198:201], v[24:27]
	v_mfma_f32_16x16x32_bf16 v[16:19], v[170:173], v[206:209], v[16:19]
	v_mfma_f32_16x16x32_bf16 v[8:11], v[178:181], v[206:209], v[8:11]
	v_mfma_f32_16x16x32_bf16 v[4:7], v[170:173], v[214:217], v[4:7]
	v_mfma_f32_16x16x32_bf16 v[0:3], v[178:181], v[214:217], v[0:3]
	s_setprio 0
	s_barrier
	s_add_i32 s48, s48, 2
	s_add_u32 s46, s46, 0x100
	s_addc_u32 s47, s47, 0
	s_cmp_gt_u32 s48, 3
	s_mov_b64 s[14:15], s[16:17]
	s_cbranch_scc0 .LBB0_515
	s_and_b64 vcc, exec, s[10:11]
	s_cbranch_vccz .LBB0_518
	s_barrier

; #define PG8_STAGE(bufoff, gbase, voff) do { _Pragma("unroll") for (int _i = 0; _i < 2; ++_i) \
;         __builtin_amdgcn_global_load_lds((const unsigned*)((const char*)(gbase) + (voff)[_i]), (PG8_LAS unsigned*)(lds + (bufoff) + ldsw + _i * 8192), 16, 0, 0); } while (0)
; #define PG8_LDA(dst, b, h) do { _Pragma("unroll") for (int m = 0; m < 4; ++m) _Pragma("unroll") for (int k = 0; k < 2; ++k) dst[m][k] = *(const PG8_LAS bf16x8*)(lds + PG8_SA(b, h) + aoff + m * 2048 + k * 1024); } while (0)
; #define PG8_LDB(dst, b, h) do { _Pragma("unroll") for (int n = 0; n < 2; ++n) _Pragma("unroll") for (int k = 0; k < 2; ++k) dst[n][k] = *(const PG8_LAS bf16x8*)(lds + PG8_SB(b, h) + boff + n * 2048 + k * 1024); } while (0)
; #define PG8_MMA(ai, bj, At, Bt) do { __builtin_amdgcn_s_setprio(1); _Pragma("unroll") for (int m = 0; m < 4; ++m) _Pragma("unroll") for (int n = 0; n < 2; ++n) _Pragma("unroll") for (int k = 0; k < 2; ++k) \
;         acc[ai][bj][m][n] = __builtin_amdgcn_mfma_f32_16x16x32_bf16(Bt[n][k], At[m][k], acc[ai][bj][m][n], 0, 0, 0); __builtin_amdgcn_s_setprio(0); } while (0)
; #define PG8_WAIT_V(n) asm volatile("s_waitcnt vmcnt(" #n ")" ::: "memory")
; #define PG8_WAIT_L(n) asm volatile("s_waitcnt lgkmcnt(" #n ")" ::: "memory")
; #define PG8_BAR __builtin_amdgcn_s_barrier()
; #define PG8_SCHED __builtin_amdgcn_sched_barrier(0)
; template <class Epi, class Sched, bool ALIGN_EPI = false, bool SP2 = false>
; __device__ __forceinline__ void gemm_phase(PG8_LAS unsigned char* lds, const Gemm g, const Sched& S, const Epi& E) {
;     ...
;         for (int t = 0; t < nt; t += 2) {
;             const bool last = (t == nt - 2);
;             const char* a1 = cA + (size_t)(t + 1) * kstep;
;             const char* a2 = last ? nA : cA + (size_t)(t + 2) * kstep; const char* b2 = last ? nB : cB + (size_t)(t + 2) * kstep;
;             const char* a3 = a2 + kstep; const char* b3 = b2 + kstep;
;             if (last && has_next) S.a_ready(nxt);
;             if constexpr (SP2) {
;             PG8_LDB(B0, 0, 0); PG8_LDB(B1, 0, 1); PG8_SCHED; PG8_LDA(At, 0, 0); PG8_STAGE(PG8_SA(1, 1), a1 + hstep, voffA);
;             PG8_WAIT_V(8); PG8_WAIT_L(0); PG8_BAR; PG8_MMA(0, 0, At, B0); PG8_MMA(0, 1, At, B1); PG8_BAR; PG8_SCHED;
;             PG8_LDA(At, 0, 1); PG8_STAGE(PG8_SB(0, 0), b2, voffB); PG8_STAGE(PG8_SB(0, 1), b2 + hstep, voffB); PG8_STAGE(PG8_SA(0, 0), a2, voffA);
.LBB0_539:
	s_add_u32 s39, s30, s38
	s_addc_u32 s44, s31, 0
	s_add_u32 s42, s39, 0x100
	s_addc_u32 s43, s44, 0
	s_and_b64 s[40:41], s[36:37], exec
	s_cselect_b32 s41, s21, s43
	s_cselect_b32 s40, s68, s42
	s_add_u32 s38, s28, s38
	s_addc_u32 s42, s29, 0
	s_add_u32 s38, s38, 0x100
	s_addc_u32 s42, s42, 0
	s_and_b64 s[36:37], s[36:37], exec
	s_cselect_b32 s43, s19, s42
	s_cselect_b32 s42, s69, s38
	s_add_u32 s46, s39, 0x10080
	ds_read_b128 v[148:151], v145
	ds_read_b128 v[152:155], v145 offset:1024
	ds_read_b128 v[156:159], v145 offset:2048
	ds_read_b128 v[160:163], v145 offset:3072
	ds_read_b128 v[164:167], v146
	ds_read_b128 v[168:171], v146 offset:1024
	ds_read_b128 v[172:175], v146 offset:2048
	ds_read_b128 v[176:179], v146 offset:3072
	s_addc_u32 s47, s44, 0
	s_add_i32 s77, s61, s52
	s_add_i32 m0, s27, 0xc000
	s_add_i32 s80, s27, 0xe000
	s_add_i32 s74, s77, 0x2000
	s_add_u32 s44, s42, 0x10000
	s_addc_u32 s45, s43, 0
	s_add_i32 s76, s62, s52
	s_add_i32 s75, s76, 0x2000
	s_add_i32 s73, 0, 0x18000
	s_add_i32 s72, 0, 0x1c000
	s_add_u32 s38, s40, 0x10000
	s_addc_u32 s39, s41, 0
	s_add_i32 s71, s73, s52
	s_add_i32 s70, s71, 0x2000
	s_add_u32 s36, s42, 0x10080
	s_addc_u32 s37, s43, 0
	s_add_i32 s79, s72, s52
	s_add_i32 s78, s79, 0x2000
	v_lshl_add_u64 v[140:141], s[46:47], 0, v[128:129]
	ds_read_b128 v[180:183], v147
	ds_read_b128 v[186:189], v147 offset:1024
	ds_read_b128 v[190:193], v147 offset:2048
	ds_read_b128 v[194:197], v147 offset:3072
	ds_read_b128 v[198:201], v147 offset:4096
	ds_read_b128 v[202:205], v147 offset:5120
	ds_read_b128 v[206:209], v147 offset:6144
	ds_read_b128 v[210:213], v147 offset:7168
	global_load_lds_dwordx4 v[140:141], off
	s_mov_b32 m0, s80
	v_lshl_add_u64 v[140:141], s[46:47], 0, v[132:133]
	global_load_lds_dwordx4 v[140:141], off
	s_waitcnt vmcnt(8)
	s_waitcnt lgkmcnt(0)
	s_barrier
	s_setprio 1
	s_waitcnt lgkmcnt(0)
	v_mfma_f32_16x16x32_bf16 v[124:127], v[148:151], v[180:183], v[124:127]
	v_mfma_f32_16x16x32_bf16 v[120:123], v[156:159], v[180:183], v[120:123]
	v_mfma_f32_16x16x32_bf16 v[116:119], v[148:151], v[190:193], v[116:119]
	v_mfma_f32_16x16x32_bf16 v[108:111], v[156:159], v[190:193], v[108:111]
	v_mfma_f32_16x16x32_bf16 v[100:103], v[148:151], v[198:201], v[100:103]
	v_mfma_f32_16x16x32_bf16 v[92:95], v[156:159], v[198:201], v[92:95]
	v_mfma_f32_16x16x32_bf16 v[84:87], v[148:151], v[206:209], v[84:87]
	v_mfma_f32_16x16x32_bf16 v[76:79], v[156:159], v[206:209], v[76:79]
	v_mfma_f32_16x16x32_bf16 v[124:127], v[152:155], v[186:189], v[124:127]
	v_mfma_f32_16x16x32_bf16 v[120:123], v[160:163], v[186:189], v[120:123]
	v_mfma_f32_16x16x32_bf16 v[116:119], v[152:155], v[194:197], v[116:119]
	v_mfma_f32_16x16x32_bf16 v[108:111], v[160:163], v[194:197], v[108:111]
	v_mfma_f32_16x16x32_bf16 v[100:103], v[152:155], v[202:205], v[100:103]
	v_mfma_f32_16x16x32_bf16 v[92:95], v[160:163], v[202:205], v[92:95]
	v_mfma_f32_16x16x32_bf16 v[84:87], v[152:155], v[210:213], v[84:87]
	v_mfma_f32_16x16x32_bf16 v[76:79], v[160:163], v[210:213], v[76:79]
	s_setprio 0
	s_setprio 1
	v_mfma_f32_16x16x32_bf16 v[112:115], v[164:167], v[180:183], v[112:115]
	v_mfma_f32_16x16x32_bf16 v[104:107], v[172:175], v[180:183], v[104:107]
	v_mfma_f32_16x16x32_bf16 v[96:99], v[164:167], v[190:193], v[96:99]
	v_mfma_f32_16x16x32_bf16 v[88:91], v[172:175], v[190:193], v[88:91]
	v_mfma_f32_16x16x32_bf16 v[80:83], v[164:167], v[198:201], v[80:83]
	v_mfma_f32_16x16x32_bf16 v[72:75], v[172:175], v[198:201], v[72:75]
	v_mfma_f32_16x16x32_bf16 v[68:71], v[164:167], v[206:209], v[68:71]
	v_mfma_f32_16x16x32_bf16 v[64:67], v[172:175], v[206:209], v[64:67]
	v_mfma_f32_16x16x32_bf16 v[112:115], v[168:171], v[186:189], v[112:115]
	v_mfma_f32_16x16x32_bf16 v[104:107], v[176:179], v[186:189], v[104:107]
	v_mfma_f32_16x16x32_bf16 v[96:99], v[168:171], v[194:197], v[96:99]
	v_mfma_f32_16x16x32_bf16 v[88:91], v[176:179], v[194:197], v[88:91]
	v_mfma_f32_16x16x32_bf16 v[80:83], v[168:171], v[202:205], v[80:83]
	v_mfma_f32_16x16x32_bf16 v[72:75], v[176:179], v[202:205], v[72:75]
	v_mfma_f32_16x16x32_bf16 v[68:71], v[168:171], v[210:213], v[68:71]
	v_mfma_f32_16x16x32_bf16 v[64:67], v[176:179], v[210:213], v[64:67]
	s_setprio 0
	s_barrier
	s_mov_b32 m0, s77
	v_lshl_add_u64 v[140:141], s[42:43], 0, v[130:131]
	ds_read_b128 v[180:183], v147 offset:16384
	ds_read_b128 v[186:189], v147 offset:17408
	ds_read_b128 v[190:193], v147 offset:18432
	ds_read_b128 v[194:197], v147 offset:19456
	ds_read_b128 v[198:201], v147 offset:20480
	ds_read_b128 v[202:205], v147 offset:21504
	ds_read_b128 v[206:209], v147 offset:22528
	ds_read_b128 v[210:213], v147 offset:23552
	global_load_lds_dwordx4 v[140:141], off
	v_lshl_add_u64 v[214:215], s[42:43], 0, v[134:135]
	s_mov_b32 m0, s74
	v_lshl_add_u64 v[216:217], s[44:45], 0, v[130:131]
	global_load_lds_dwordx4 v[214:215], off
	s_mov_b32 m0, s76
	v_lshl_add_u64 v[218:219], s[40:41], 0, v[132:133]
	global_load_lds_dwordx4 v[216:217], off
	s_mov_b32 m0, s75
	v_lshl_add_u64 v[216:217], s[44:45], 0, v[134:135]
	global_load_lds_dwordx4 v[216:217], off
	s_mov_b32 m0, s27
	v_lshl_add_u64 v[216:217], s[40:41], 0, v[128:129]
	global_load_lds_dwordx4 v[216:217], off
	s_mov_b32 m0, s53
	s_nop 0
	global_load_lds_dwordx4 v[218:219], off
	s_waitcnt vmcnt(8)
	s_waitcnt lgkmcnt(0)
	s_barrier
; #define PG8_STAGE(bufoff, gbase, voff) do { _Pragma("unroll") for (int _i = 0; _i < 2; ++_i) \
;         __builtin_amdgcn_global_load_lds((const unsigned*)((const char*)(gbase) + (voff)[_i]), (PG8_LAS unsigned*)(lds + (bufoff) + ldsw + _i * 8192), 16, 0, 0); } while (0)
; #define PG8_LDA(dst, b, h) do { _Pragma("unroll") for (int m = 0; m < 4; ++m) _Pragma("unroll") for (int k = 0; k < 2; ++k) dst[m][k] = *(const PG8_LAS bf16x8*)(lds + PG8_SA(b, h) + aoff + m * 2048 + k * 1024); } while (0)
; #define PG8_LDB(dst, b, h) do { _Pragma("unroll") for (int n = 0; n < 2; ++n) _Pragma("unroll") for (int k = 0; k < 2; ++k) dst[n][k] = *(const PG8_LAS bf16x8*)(lds + PG8_SB(b, h) + boff + n * 2048 + k * 1024); } while (0)
; #define PG8_MMA(ai, bj, At, Bt) do { __builtin_amdgcn_s_setprio(1); _Pragma("unroll") for (int m = 0; m < 4; ++m) _Pragma("unroll") for (int n = 0; n < 2; ++n) _Pragma("unroll") for (int k = 0; k < 2; ++k) \
;         acc[ai][bj][m][n] = __builtin_amdgcn_mfma_f32_16x16x32_bf16(Bt[n][k], At[m][k], acc[ai][bj][m][n], 0, 0, 0); __builtin_amdgcn_s_setprio(0); } while (0)
; #define PG8_WAIT_V(n) asm volatile("s_waitcnt vmcnt(" #n ")" ::: "memory")
; #define PG8_WAIT_L(n) asm volatile("s_waitcnt lgkmcnt(" #n ")" ::: "memory")
; #define PG8_BAR __builtin_amdgcn_s_barrier()
; #define PG8_SCHED __builtin_amdgcn_sched_barrier(0)
; template <class Epi, class Sched, bool ALIGN_EPI = false, bool SP2 = false>
; __device__ __forceinline__ void gemm_phase(PG8_LAS unsigned char* lds, const Gemm g, const Sched& S, const Epi& E) {
;     ...
;             PG8_WAIT_V(8); PG8_WAIT_L(0); PG8_BAR; PG8_MMA(1, 0, At, B0); PG8_MMA(1, 1, At, B1); PG8_BAR; PG8_SCHED;
;             PG8_LDB(B0, 1, 0); PG8_LDB(B1, 1, 1); PG8_SCHED; PG8_LDA(At, 1, 0); PG8_STAGE(PG8_SA(0, 1), a2 + hstep, voffA);
;             PG8_WAIT_V(8); PG8_WAIT_L(0); PG8_BAR; PG8_MMA(0, 0, At, B0); PG8_MMA(0, 1, At, B1); PG8_BAR; PG8_SCHED;
	s_setprio 1
	s_waitcnt lgkmcnt(0)
	v_mfma_f32_16x16x32_bf16 v[60:63], v[148:151], v[180:183], v[60:63]
	v_mfma_f32_16x16x32_bf16 v[56:59], v[156:159], v[180:183], v[56:59]
	v_mfma_f32_16x16x32_bf16 v[52:55], v[148:151], v[190:193], v[52:55]
	v_mfma_f32_16x16x32_bf16 v[44:47], v[156:159], v[190:193], v[44:47]
	v_mfma_f32_16x16x32_bf16 v[36:39], v[148:151], v[198:201], v[36:39]
	v_mfma_f32_16x16x32_bf16 v[28:31], v[156:159], v[198:201], v[28:31]
	v_mfma_f32_16x16x32_bf16 v[20:23], v[148:151], v[206:209], v[20:23]
	v_mfma_f32_16x16x32_bf16 v[12:15], v[156:159], v[206:209], v[12:15]
	v_mfma_f32_16x16x32_bf16 v[60:63], v[152:155], v[186:189], v[60:63]
	v_mfma_f32_16x16x32_bf16 v[56:59], v[160:163], v[186:189], v[56:59]
	v_mfma_f32_16x16x32_bf16 v[52:55], v[152:155], v[194:197], v[52:55]
	v_mfma_f32_16x16x32_bf16 v[44:47], v[160:163], v[194:197], v[44:47]
	v_mfma_f32_16x16x32_bf16 v[36:39], v[152:155], v[202:205], v[36:39]
	v_mfma_f32_16x16x32_bf16 v[28:31], v[160:163], v[202:205], v[28:31]
	v_mfma_f32_16x16x32_bf16 v[20:23], v[152:155], v[210:213], v[20:23]
	v_mfma_f32_16x16x32_bf16 v[12:15], v[160:163], v[210:213], v[12:15]
	s_setprio 0
	s_setprio 1
	v_mfma_f32_16x16x32_bf16 v[48:51], v[164:167], v[180:183], v[48:51]
	v_mfma_f32_16x16x32_bf16 v[40:43], v[172:175], v[180:183], v[40:43]
	v_mfma_f32_16x16x32_bf16 v[32:35], v[164:167], v[190:193], v[32:35]
	v_mfma_f32_16x16x32_bf16 v[24:27], v[172:175], v[190:193], v[24:27]
	v_mfma_f32_16x16x32_bf16 v[16:19], v[164:167], v[198:201], v[16:19]
	v_mfma_f32_16x16x32_bf16 v[8:11], v[172:175], v[198:201], v[8:11]
	v_mfma_f32_16x16x32_bf16 v[4:7], v[164:167], v[206:209], v[4:7]
	v_mfma_f32_16x16x32_bf16 v[0:3], v[172:175], v[206:209], v[0:3]
	v_mfma_f32_16x16x32_bf16 v[48:51], v[168:171], v[186:189], v[48:51]
	v_mfma_f32_16x16x32_bf16 v[40:43], v[176:179], v[186:189], v[40:43]
	v_mfma_f32_16x16x32_bf16 v[32:35], v[168:171], v[194:197], v[32:35]
	v_mfma_f32_16x16x32_bf16 v[24:27], v[176:179], v[194:197], v[24:27]
	v_mfma_f32_16x16x32_bf16 v[16:19], v[168:171], v[202:205], v[16:19]
	v_mfma_f32_16x16x32_bf16 v[8:11], v[176:179], v[202:205], v[8:11]
	v_mfma_f32_16x16x32_bf16 v[4:7], v[168:171], v[210:213], v[4:7]
	v_mfma_f32_16x16x32_bf16 v[0:3], v[176:179], v[210:213], v[0:3]
	s_setprio 0
	s_barrier
	v_add_u32_e32 v160, s73, v143
	v_add_u32_e32 v176, s72, v143
	ds_read_b128 v[148:151], v160
	ds_read_b128 v[152:155], v160 offset:1024
	ds_read_b128 v[156:159], v160 offset:2048
	ds_read_b128 v[160:163], v160 offset:3072
	ds_read_b128 v[164:167], v176
	ds_read_b128 v[168:171], v176 offset:1024
	ds_read_b128 v[172:175], v176 offset:2048
	ds_read_b128 v[176:179], v176 offset:3072
	s_mov_b32 m0, s54
	v_lshl_add_u64 v[220:221], s[38:39], 0, v[128:129]
	ds_read_b128 v[180:183], v147 offset:32768
	ds_read_b128 v[186:189], v147 offset:33792
	ds_read_b128 v[190:193], v147 offset:34816
	ds_read_b128 v[194:197], v147 offset:35840
	ds_read_b128 v[198:201], v147 offset:36864
	ds_read_b128 v[202:205], v147 offset:37888
	ds_read_b128 v[206:209], v147 offset:38912
	ds_read_b128 v[210:213], v147 offset:39936
	global_load_lds_dwordx4 v[220:221], off
	s_mov_b32 m0, s55
	v_lshl_add_u64 v[220:221], s[38:39], 0, v[132:133]
	global_load_lds_dwordx4 v[220:221], off
	s_waitcnt vmcnt(8)
	s_waitcnt lgkmcnt(0)
	s_barrier
	s_setprio 1
	s_waitcnt lgkmcnt(0)
	v_mfma_f32_16x16x32_bf16 v[124:127], v[148:151], v[180:183], v[124:127]
	v_mfma_f32_16x16x32_bf16 v[120:123], v[156:159], v[180:183], v[120:123]
	v_mfma_f32_16x16x32_bf16 v[116:119], v[148:151], v[190:193], v[116:119]
	v_mfma_f32_16x16x32_bf16 v[108:111], v[156:159], v[190:193], v[108:111]
	v_mfma_f32_16x16x32_bf16 v[100:103], v[148:151], v[198:201], v[100:103]
	v_mfma_f32_16x16x32_bf16 v[92:95], v[156:159], v[198:201], v[92:95]
	v_mfma_f32_16x16x32_bf16 v[84:87], v[148:151], v[206:209], v[84:87]
	v_mfma_f32_16x16x32_bf16 v[76:79], v[156:159], v[206:209], v[76:79]
	v_mfma_f32_16x16x32_bf16 v[124:127], v[152:155], v[186:189], v[124:127]
	v_mfma_f32_16x16x32_bf16 v[120:123], v[160:163], v[186:189], v[120:123]
	v_mfma_f32_16x16x32_bf16 v[116:119], v[152:155], v[194:197], v[116:119]
	v_mfma_f32_16x16x32_bf16 v[108:111], v[160:163], v[194:197], v[108:111]
	v_mfma_f32_16x16x32_bf16 v[100:103], v[152:155], v[202:205], v[100:103]
	v_mfma_f32_16x16x32_bf16 v[92:95], v[160:163], v[202:205], v[92:95]
	v_mfma_f32_16x16x32_bf16 v[84:87], v[152:155], v[210:213], v[84:87]
	v_mfma_f32_16x16x32_bf16 v[76:79], v[160:163], v[210:213], v[76:79]
	s_setprio 0
	s_setprio 1
	v_mfma_f32_16x16x32_bf16 v[112:115], v[164:167], v[180:183], v[112:115]
	v_mfma_f32_16x16x32_bf16 v[104:107], v[172:175], v[180:183], v[104:107]
	v_mfma_f32_16x16x32_bf16 v[96:99], v[164:167], v[190:193], v[96:99]
	v_mfma_f32_16x16x32_bf16 v[88:91], v[172:175], v[190:193], v[88:91]
	v_mfma_f32_16x16x32_bf16 v[80:83], v[164:167], v[198:201], v[80:83]
	v_mfma_f32_16x16x32_bf16 v[72:75], v[172:175], v[198:201], v[72:75]
	v_mfma_f32_16x16x32_bf16 v[68:71], v[164:167], v[206:209], v[68:71]
	v_mfma_f32_16x16x32_bf16 v[64:67], v[172:175], v[206:209], v[64:67]
	v_mfma_f32_16x16x32_bf16 v[112:115], v[168:171], v[186:189], v[112:115]
	v_mfma_f32_16x16x32_bf16 v[104:107], v[176:179], v[186:189], v[104:107]
	v_mfma_f32_16x16x32_bf16 v[96:99], v[168:171], v[194:197], v[96:99]
	v_mfma_f32_16x16x32_bf16 v[88:91], v[176:179], v[194:197], v[88:91]
	v_mfma_f32_16x16x32_bf16 v[80:83], v[168:171], v[202:205], v[80:83]
	v_mfma_f32_16x16x32_bf16 v[72:75], v[176:179], v[202:205], v[72:75]
	v_mfma_f32_16x16x32_bf16 v[68:71], v[168:171], v[210:213], v[68:71]
	v_mfma_f32_16x16x32_bf16 v[64:67], v[176:179], v[210:213], v[64:67]
	s_setprio 0
	s_barrier
; #define PG8_STAGE(bufoff, gbase, voff) do { _Pragma("unroll") for (int _i = 0; _i < 2; ++_i) \
;         __builtin_amdgcn_global_load_lds((const unsigned*)((const char*)(gbase) + (voff)[_i]), (PG8_LAS unsigned*)(lds + (bufoff) + ldsw + _i * 8192), 16, 0, 0); } while (0)
; #define PG8_LDA(dst, b, h) do { _Pragma("unroll") for (int m = 0; m < 4; ++m) _Pragma("unroll") for (int k = 0; k < 2; ++k) dst[m][k] = *(const PG8_LAS bf16x8*)(lds + PG8_SA(b, h) + aoff + m * 2048 + k * 1024); } while (0)
; #define PG8_MMA(ai, bj, At, Bt) do { __builtin_amdgcn_s_setprio(1); _Pragma("unroll") for (int m = 0; m < 4; ++m) _Pragma("unroll") for (int n = 0; n < 2; ++n) _Pragma("unroll") for (int k = 0; k < 2; ++k) \
;         acc[ai][bj][m][n] = __builtin_amdgcn_mfma_f32_16x16x32_bf16(Bt[n][k], At[m][k], acc[ai][bj][m][n], 0, 0, 0); __builtin_amdgcn_s_setprio(0); } while (0)
; #define PG8_WAIT_V(n) asm volatile("s_waitcnt vmcnt(" #n ")" ::: "memory")
; #define PG8_WAIT_L(n) asm volatile("s_waitcnt lgkmcnt(" #n ")" ::: "memory")
; #define PG8_BAR __builtin_amdgcn_s_barrier()
; #define PG8_SCHED __builtin_amdgcn_sched_barrier(0)
; template <class Epi, class Sched, bool ALIGN_EPI = false, bool SP2 = false>
; __device__ __forceinline__ void gemm_phase(PG8_LAS unsigned char* lds, const Gemm g, const Sched& S, const Epi& E) {
;     ...
;         for (int t = 0; t < nt; t += 2) {
;             const bool last = (t == nt - 2);
;             const char* a1 = cA + (size_t)(t + 1) * kstep;
;             const char* a2 = last ? nA : cA + (size_t)(t + 2) * kstep; const char* b2 = last ? nB : cB + (size_t)(t + 2) * kstep;
;             const char* a3 = a2 + kstep; const char* b3 = b2 + kstep;
;     ...
;             PG8_LDA(At, 1, 1); PG8_STAGE(PG8_SB(1, 0), b3, voffB); PG8_STAGE(PG8_SB(1, 1), b3 + hstep, voffB); PG8_STAGE(PG8_SA(1, 0), a3, voffA);
;             PG8_WAIT_V(8); PG8_WAIT_L(0); PG8_BAR; PG8_MMA(1, 0, At, B0); PG8_MMA(1, 1, At, B1); PG8_BAR; PG8_SCHED;
	s_mov_b32 m0, s71
	v_lshl_add_u64 v[140:141], v[140:141], 0, s[6:7]
	ds_read_b128 v[180:183], v147 offset:49152
	ds_read_b128 v[186:189], v147 offset:50176
	ds_read_b128 v[190:193], v147 offset:51200
	ds_read_b128 v[194:197], v147 offset:52224
	ds_read_b128 v[198:201], v147 offset:53248
	ds_read_b128 v[202:205], v147 offset:54272
	ds_read_b128 v[206:209], v147 offset:55296
	ds_read_b128 v[210:213], v147 offset:56320
	global_load_lds_dwordx4 v[140:141], off
	s_mov_b32 m0, s70
	v_lshl_add_u64 v[140:141], v[214:215], 0, s[6:7]
	global_load_lds_dwordx4 v[140:141], off
	s_mov_b32 m0, s79
	v_lshl_add_u64 v[140:141], s[36:37], 0, v[130:131]
	global_load_lds_dwordx4 v[140:141], off
	s_mov_b32 m0, s78
	v_lshl_add_u64 v[140:141], s[36:37], 0, v[134:135]
	global_load_lds_dwordx4 v[140:141], off
	s_mov_b32 m0, s57
	v_lshl_add_u64 v[140:141], v[216:217], 0, s[6:7]
	global_load_lds_dwordx4 v[140:141], off
	s_mov_b32 m0, s58
	v_lshl_add_u64 v[140:141], v[218:219], 0, s[6:7]
	global_load_lds_dwordx4 v[140:141], off
	s_waitcnt vmcnt(8)
	s_waitcnt lgkmcnt(0)
	s_barrier
	s_setprio 1
	s_waitcnt lgkmcnt(0)
	v_mfma_f32_16x16x32_bf16 v[60:63], v[148:151], v[180:183], v[60:63]
	v_mfma_f32_16x16x32_bf16 v[56:59], v[156:159], v[180:183], v[56:59]
	v_mfma_f32_16x16x32_bf16 v[52:55], v[148:151], v[190:193], v[52:55]
	v_mfma_f32_16x16x32_bf16 v[44:47], v[156:159], v[190:193], v[44:47]
	v_mfma_f32_16x16x32_bf16 v[36:39], v[148:151], v[198:201], v[36:39]
	v_mfma_f32_16x16x32_bf16 v[28:31], v[156:159], v[198:201], v[28:31]
	v_mfma_f32_16x16x32_bf16 v[20:23], v[148:151], v[206:209], v[20:23]
	v_mfma_f32_16x16x32_bf16 v[12:15], v[156:159], v[206:209], v[12:15]
	v_mfma_f32_16x16x32_bf16 v[60:63], v[152:155], v[186:189], v[60:63]
	v_mfma_f32_16x16x32_bf16 v[56:59], v[160:163], v[186:189], v[56:59]
	v_mfma_f32_16x16x32_bf16 v[52:55], v[152:155], v[194:197], v[52:55]
	v_mfma_f32_16x16x32_bf16 v[44:47], v[160:163], v[194:197], v[44:47]
	v_mfma_f32_16x16x32_bf16 v[36:39], v[152:155], v[202:205], v[36:39]
	v_mfma_f32_16x16x32_bf16 v[28:31], v[160:163], v[202:205], v[28:31]
	v_mfma_f32_16x16x32_bf16 v[20:23], v[152:155], v[210:213], v[20:23]
	v_mfma_f32_16x16x32_bf16 v[12:15], v[160:163], v[210:213], v[12:15]
	s_setprio 0
	s_setprio 1
	v_mfma_f32_16x16x32_bf16 v[48:51], v[164:167], v[180:183], v[48:51]
	v_mfma_f32_16x16x32_bf16 v[40:43], v[172:175], v[180:183], v[40:43]
	v_mfma_f32_16x16x32_bf16 v[32:35], v[164:167], v[190:193], v[32:35]
	v_mfma_f32_16x16x32_bf16 v[24:27], v[172:175], v[190:193], v[24:27]
	v_mfma_f32_16x16x32_bf16 v[16:19], v[164:167], v[198:201], v[16:19]
	v_mfma_f32_16x16x32_bf16 v[8:11], v[172:175], v[198:201], v[8:11]
	v_mfma_f32_16x16x32_bf16 v[4:7], v[164:167], v[206:209], v[4:7]
	v_mfma_f32_16x16x32_bf16 v[0:3], v[172:175], v[206:209], v[0:3]
	v_mfma_f32_16x16x32_bf16 v[48:51], v[168:171], v[186:189], v[48:51]
	v_mfma_f32_16x16x32_bf16 v[40:43], v[176:179], v[186:189], v[40:43]
	v_mfma_f32_16x16x32_bf16 v[32:35], v[168:171], v[194:197], v[32:35]
	v_mfma_f32_16x16x32_bf16 v[24:27], v[176:179], v[194:197], v[24:27]
	v_mfma_f32_16x16x32_bf16 v[16:19], v[168:171], v[202:205], v[16:19]
	v_mfma_f32_16x16x32_bf16 v[8:11], v[176:179], v[202:205], v[8:11]
	v_mfma_f32_16x16x32_bf16 v[4:7], v[168:171], v[210:213], v[4:7]
	v_mfma_f32_16x16x32_bf16 v[0:3], v[176:179], v[210:213], v[0:3]
	s_setprio 0
	s_barrier
	s_movk_i32 s38, 0x100
	s_andn2_b64 vcc, exec, s[34:35]
	s_mov_b64 s[36:37], -1
	s_mov_b64 s[34:35], 0
	s_cbranch_vccz .LBB0_539
	s_and_b64 vcc, exec, s[8:9]
	s_cbranch_vccz .LBB0_542
	s_barrier

; #define PG8_STAGE(bufoff, gbase, voff) do { _Pragma("unroll") for (int _i = 0; _i < 2; ++_i) \
;         __builtin_amdgcn_global_load_lds((const unsigned*)((const char*)(gbase) + (voff)[_i]), (PG8_LAS unsigned*)(lds + (bufoff) + ldsw + _i * 8192), 16, 0, 0); } while (0)
; #define PG8_LDA(dst, b, h) do { _Pragma("unroll") for (int m = 0; m < 4; ++m) _Pragma("unroll") for (int k = 0; k < 2; ++k) dst[m][k] = *(const PG8_LAS bf16x8*)(lds + PG8_SA(b, h) + aoff + m * 2048 + k * 1024); } while (0)
; #define PG8_LDB(dst, b, h) do { _Pragma("unroll") for (int n = 0; n < 2; ++n) _Pragma("unroll") for (int k = 0; k < 2; ++k) dst[n][k] = *(const PG8_LAS bf16x8*)(lds + PG8_SB(b, h) + boff + n * 2048 + k * 1024); } while (0)
; #define PG8_MMA(ai, bj, At, Bt) do { __builtin_amdgcn_s_setprio(1); _Pragma("unroll") for (int m = 0; m < 4; ++m) _Pragma("unroll") for (int n = 0; n < 2; ++n) _Pragma("unroll") for (int k = 0; k < 2; ++k) \
;         acc[ai][bj][m][n] = __builtin_amdgcn_mfma_f32_16x16x32_bf16(Bt[n][k], At[m][k], acc[ai][bj][m][n], 0, 0, 0); __builtin_amdgcn_s_setprio(0); } while (0)
; #define PG8_WAIT_V(n) asm volatile("s_waitcnt vmcnt(" #n ")" ::: "memory")
; #define PG8_WAIT_L(n) asm volatile("s_waitcnt lgkmcnt(" #n ")" ::: "memory")
; #define PG8_BAR __builtin_amdgcn_s_barrier()
; #define PG8_SCHED __builtin_amdgcn_sched_barrier(0)
; template <class Epi, class Sched, bool ALIGN_EPI = false, bool SP2 = false>
; __device__ __forceinline__ void gemm_phase(PG8_LAS unsigned char* lds, const Gemm g, const Sched& S, const Epi& E) {
;     ...
;         for (int t = 0; t < nt; t += 2) {
;             const bool last = (t == nt - 2);
;             const char* a1 = cA + (size_t)(t + 1) * kstep;
;             const char* a2 = last ? nA : cA + (size_t)(t + 2) * kstep; const char* b2 = last ? nB : cB + (size_t)(t + 2) * kstep;
;             const char* a3 = a2 + kstep; const char* b3 = b2 + kstep;
;             if (last && has_next) S.a_ready(nxt);
;             if constexpr (SP2) {
;             PG8_LDB(B0, 0, 0); PG8_LDB(B1, 0, 1); PG8_SCHED; PG8_LDA(At, 0, 0); PG8_STAGE(PG8_SA(1, 1), a1 + hstep, voffA);
;             PG8_WAIT_V(8); PG8_WAIT_L(0); PG8_BAR; PG8_MMA(0, 0, At, B0); PG8_MMA(0, 1, At, B1); PG8_BAR; PG8_SCHED;
;             PG8_LDA(At, 0, 1); PG8_STAGE(PG8_SB(0, 0), b2, voffB); PG8_STAGE(PG8_SB(0, 1), b2 + hstep, voffB); PG8_STAGE(PG8_SA(0, 0), a2, voffA);
.LBB0_868:
	ds_read_b128 v[152:155], v149
	ds_read_b128 v[156:159], v149 offset:1024
	ds_read_b128 v[160:163], v149 offset:2048
	ds_read_b128 v[164:167], v149 offset:3072
	ds_read_b128 v[168:171], v150
	ds_read_b128 v[172:175], v150 offset:1024
	ds_read_b128 v[176:179], v150 offset:2048
	ds_read_b128 v[180:183], v150 offset:3072
	s_add_u32 s34, s30, 0xfffc0080
	s_addc_u32 s35, s31, -1
	s_cmp_eq_u32 s61, 12
	s_cselect_b32 s37, s23, s35
	s_cselect_b32 s36, s57, s34
	s_cselect_b32 s35, s21, s60
	s_cselect_b32 s34, s58, s59
	v_lshl_add_u64 v[144:145], s[30:31], 0, v[138:139]
	s_add_i32 m0, s29, 0xc000
	ds_read_b128 v[186:189], v151
	ds_read_b128 v[190:193], v151 offset:1024
	ds_read_b128 v[194:197], v151 offset:2048
	ds_read_b128 v[198:201], v151 offset:3072
	ds_read_b128 v[202:205], v151 offset:4096
	ds_read_b128 v[206:209], v151 offset:5120
	ds_read_b128 v[210:213], v151 offset:6144
	ds_read_b128 v[214:217], v151 offset:7168
	global_load_lds_dwordx4 v[144:145], off
	s_add_i32 m0, s29, 0xe000
	v_lshl_add_u64 v[144:145], s[30:31], 0, v[136:137]
	global_load_lds_dwordx4 v[144:145], off
	s_waitcnt vmcnt(8)
	s_waitcnt lgkmcnt(0)
	s_barrier
	s_setprio 1
	s_waitcnt lgkmcnt(0)
	v_mfma_f32_16x16x32_bf16 v[124:127], v[152:155], v[186:189], v[124:127]
	v_mfma_f32_16x16x32_bf16 v[120:123], v[160:163], v[186:189], v[120:123]
	v_mfma_f32_16x16x32_bf16 v[116:119], v[152:155], v[194:197], v[116:119]
	v_mfma_f32_16x16x32_bf16 v[108:111], v[160:163], v[194:197], v[108:111]
	v_mfma_f32_16x16x32_bf16 v[100:103], v[152:155], v[202:205], v[100:103]
	v_mfma_f32_16x16x32_bf16 v[92:95], v[160:163], v[202:205], v[92:95]
	v_mfma_f32_16x16x32_bf16 v[84:87], v[152:155], v[210:213], v[84:87]
	v_mfma_f32_16x16x32_bf16 v[76:79], v[160:163], v[210:213], v[76:79]
	v_mfma_f32_16x16x32_bf16 v[124:127], v[156:159], v[190:193], v[124:127]
	v_mfma_f32_16x16x32_bf16 v[120:123], v[164:167], v[190:193], v[120:123]
	v_mfma_f32_16x16x32_bf16 v[116:119], v[156:159], v[198:201], v[116:119]
	v_mfma_f32_16x16x32_bf16 v[108:111], v[164:167], v[198:201], v[108:111]
	v_mfma_f32_16x16x32_bf16 v[100:103], v[156:159], v[206:209], v[100:103]
	v_mfma_f32_16x16x32_bf16 v[92:95], v[164:167], v[206:209], v[92:95]
	v_mfma_f32_16x16x32_bf16 v[84:87], v[156:159], v[214:217], v[84:87]
	v_mfma_f32_16x16x32_bf16 v[76:79], v[164:167], v[214:217], v[76:79]
	s_setprio 0
	s_setprio 1
	v_mfma_f32_16x16x32_bf16 v[112:115], v[168:171], v[186:189], v[112:115]
	v_mfma_f32_16x16x32_bf16 v[104:107], v[176:179], v[186:189], v[104:107]
	v_mfma_f32_16x16x32_bf16 v[96:99], v[168:171], v[194:197], v[96:99]
	v_mfma_f32_16x16x32_bf16 v[88:91], v[176:179], v[194:197], v[88:91]
	v_mfma_f32_16x16x32_bf16 v[80:83], v[168:171], v[202:205], v[80:83]
	v_mfma_f32_16x16x32_bf16 v[72:75], v[176:179], v[202:205], v[72:75]
	v_mfma_f32_16x16x32_bf16 v[68:71], v[168:171], v[210:213], v[68:71]
	v_mfma_f32_16x16x32_bf16 v[64:67], v[176:179], v[210:213], v[64:67]
	v_mfma_f32_16x16x32_bf16 v[112:115], v[172:175], v[190:193], v[112:115]
	v_mfma_f32_16x16x32_bf16 v[104:107], v[180:183], v[190:193], v[104:107]
	v_mfma_f32_16x16x32_bf16 v[96:99], v[172:175], v[198:201], v[96:99]
	v_mfma_f32_16x16x32_bf16 v[88:91], v[180:183], v[198:201], v[88:91]
	v_mfma_f32_16x16x32_bf16 v[80:83], v[172:175], v[206:209], v[80:83]
	v_mfma_f32_16x16x32_bf16 v[72:75], v[180:183], v[206:209], v[72:75]
	v_mfma_f32_16x16x32_bf16 v[68:71], v[172:175], v[214:217], v[68:71]
	v_mfma_f32_16x16x32_bf16 v[64:67], v[180:183], v[214:217], v[64:67]
	s_setprio 0
	s_barrier
	s_add_i32 s62, s51, s42
	v_lshl_add_u64 v[144:145], s[34:35], 0, v[130:131]
	s_mov_b32 m0, s62
	ds_read_b128 v[186:189], v151 offset:16384
	ds_read_b128 v[190:193], v151 offset:17408
	ds_read_b128 v[194:197], v151 offset:18432
	ds_read_b128 v[198:201], v151 offset:19456
	ds_read_b128 v[202:205], v151 offset:20480
	ds_read_b128 v[206:209], v151 offset:21504
	ds_read_b128 v[210:213], v151 offset:22528
	ds_read_b128 v[214:217], v151 offset:23552
	global_load_lds_dwordx4 v[144:145], off
	s_add_i32 m0, s62, 0x2000
	s_add_u32 s62, s34, 0x40000
	v_lshl_add_u64 v[218:219], s[34:35], 0, v[134:135]
	s_addc_u32 s63, s35, 0
	s_add_i32 s64, s93, s42
	global_load_lds_dwordx4 v[218:219], off
	v_lshl_add_u64 v[220:221], s[62:63], 0, v[130:131]
	s_mov_b32 m0, s64
	v_lshl_add_u64 v[222:223], s[36:37], 0, v[132:133]
	global_load_lds_dwordx4 v[220:221], off
	s_add_i32 m0, s64, 0x2000
	v_lshl_add_u64 v[220:221], s[62:63], 0, v[134:135]
	global_load_lds_dwordx4 v[220:221], off
	s_mov_b32 m0, s29
	v_lshl_add_u64 v[220:221], s[36:37], 0, v[128:129]
	global_load_lds_dwordx4 v[220:221], off
	s_mov_b32 m0, s43
	s_nop 0
	global_load_lds_dwordx4 v[222:223], off
	s_waitcnt vmcnt(8)
	s_waitcnt lgkmcnt(0)
	s_barrier
; #define PG8_STAGE(bufoff, gbase, voff) do { _Pragma("unroll") for (int _i = 0; _i < 2; ++_i) \
;         __builtin_amdgcn_global_load_lds((const unsigned*)((const char*)(gbase) + (voff)[_i]), (PG8_LAS unsigned*)(lds + (bufoff) + ldsw + _i * 8192), 16, 0, 0); } while (0)
; #define PG8_LDA(dst, b, h) do { _Pragma("unroll") for (int m = 0; m < 4; ++m) _Pragma("unroll") for (int k = 0; k < 2; ++k) dst[m][k] = *(const PG8_LAS bf16x8*)(lds + PG8_SA(b, h) + aoff + m * 2048 + k * 1024); } while (0)
; #define PG8_LDB(dst, b, h) do { _Pragma("unroll") for (int n = 0; n < 2; ++n) _Pragma("unroll") for (int k = 0; k < 2; ++k) dst[n][k] = *(const PG8_LAS bf16x8*)(lds + PG8_SB(b, h) + boff + n * 2048 + k * 1024); } while (0)
; #define PG8_MMA(ai, bj, At, Bt) do { __builtin_amdgcn_s_setprio(1); _Pragma("unroll") for (int m = 0; m < 4; ++m) _Pragma("unroll") for (int n = 0; n < 2; ++n) _Pragma("unroll") for (int k = 0; k < 2; ++k) \
;         acc[ai][bj][m][n] = __builtin_amdgcn_mfma_f32_16x16x32_bf16(Bt[n][k], At[m][k], acc[ai][bj][m][n], 0, 0, 0); __builtin_amdgcn_s_setprio(0); } while (0)
; #define PG8_WAIT_V(n) asm volatile("s_waitcnt vmcnt(" #n ")" ::: "memory")
; #define PG8_WAIT_L(n) asm volatile("s_waitcnt lgkmcnt(" #n ")" ::: "memory")
; #define PG8_BAR __builtin_amdgcn_s_barrier()
; #define PG8_SCHED __builtin_amdgcn_sched_barrier(0)
; template <class Epi, class Sched, bool ALIGN_EPI = false, bool SP2 = false>
; __device__ __forceinline__ void gemm_phase(PG8_LAS unsigned char* lds, const Gemm g, const Sched& S, const Epi& E) {
;     ...
;             PG8_WAIT_V(8); PG8_WAIT_L(0); PG8_BAR; PG8_MMA(1, 0, At, B0); PG8_MMA(1, 1, At, B1); PG8_BAR; PG8_SCHED;
;             PG8_LDB(B0, 1, 0); PG8_LDB(B1, 1, 1); PG8_SCHED; PG8_LDA(At, 1, 0); PG8_STAGE(PG8_SA(0, 1), a2 + hstep, voffA);
;             PG8_WAIT_V(8); PG8_WAIT_L(0); PG8_BAR; PG8_MMA(0, 0, At, B0); PG8_MMA(0, 1, At, B1); PG8_BAR; PG8_SCHED;
	s_setprio 1
	s_waitcnt lgkmcnt(0)
	v_mfma_f32_16x16x32_bf16 v[60:63], v[152:155], v[186:189], v[60:63]
	v_mfma_f32_16x16x32_bf16 v[56:59], v[160:163], v[186:189], v[56:59]
	v_mfma_f32_16x16x32_bf16 v[52:55], v[152:155], v[194:197], v[52:55]
	v_mfma_f32_16x16x32_bf16 v[44:47], v[160:163], v[194:197], v[44:47]
	v_mfma_f32_16x16x32_bf16 v[36:39], v[152:155], v[202:205], v[36:39]
	v_mfma_f32_16x16x32_bf16 v[28:31], v[160:163], v[202:205], v[28:31]
	v_mfma_f32_16x16x32_bf16 v[20:23], v[152:155], v[210:213], v[20:23]
	v_mfma_f32_16x16x32_bf16 v[12:15], v[160:163], v[210:213], v[12:15]
	v_mfma_f32_16x16x32_bf16 v[60:63], v[156:159], v[190:193], v[60:63]
	v_mfma_f32_16x16x32_bf16 v[56:59], v[164:167], v[190:193], v[56:59]
	v_mfma_f32_16x16x32_bf16 v[52:55], v[156:159], v[198:201], v[52:55]
	v_mfma_f32_16x16x32_bf16 v[44:47], v[164:167], v[198:201], v[44:47]
	v_mfma_f32_16x16x32_bf16 v[36:39], v[156:159], v[206:209], v[36:39]
	v_mfma_f32_16x16x32_bf16 v[28:31], v[164:167], v[206:209], v[28:31]
	v_mfma_f32_16x16x32_bf16 v[20:23], v[156:159], v[214:217], v[20:23]
	v_mfma_f32_16x16x32_bf16 v[12:15], v[164:167], v[214:217], v[12:15]
	s_setprio 0
	s_setprio 1
	v_mfma_f32_16x16x32_bf16 v[48:51], v[168:171], v[186:189], v[48:51]
	v_mfma_f32_16x16x32_bf16 v[40:43], v[176:179], v[186:189], v[40:43]
	v_mfma_f32_16x16x32_bf16 v[32:35], v[168:171], v[194:197], v[32:35]
	v_mfma_f32_16x16x32_bf16 v[24:27], v[176:179], v[194:197], v[24:27]
	v_mfma_f32_16x16x32_bf16 v[16:19], v[168:171], v[202:205], v[16:19]
	v_mfma_f32_16x16x32_bf16 v[8:11], v[176:179], v[202:205], v[8:11]
	v_mfma_f32_16x16x32_bf16 v[4:7], v[168:171], v[210:213], v[4:7]
	v_mfma_f32_16x16x32_bf16 v[0:3], v[176:179], v[210:213], v[0:3]
	v_mfma_f32_16x16x32_bf16 v[48:51], v[172:175], v[190:193], v[48:51]
	v_mfma_f32_16x16x32_bf16 v[40:43], v[180:183], v[190:193], v[40:43]
	v_mfma_f32_16x16x32_bf16 v[32:35], v[172:175], v[198:201], v[32:35]
	v_mfma_f32_16x16x32_bf16 v[24:27], v[180:183], v[198:201], v[24:27]
	v_mfma_f32_16x16x32_bf16 v[16:19], v[172:175], v[206:209], v[16:19]
	v_mfma_f32_16x16x32_bf16 v[8:11], v[180:183], v[206:209], v[8:11]
	v_mfma_f32_16x16x32_bf16 v[4:7], v[172:175], v[214:217], v[4:7]
	v_mfma_f32_16x16x32_bf16 v[0:3], v[180:183], v[214:217], v[0:3]
	s_setprio 0
	s_barrier
	s_add_i32 s62, 0, 0x18000
	s_add_i32 s63, 0, 0x1c000
	v_add_u32_e32 v164, s62, v147
	v_add_u32_e32 v180, s63, v147
	ds_read_b128 v[152:155], v164
	ds_read_b128 v[156:159], v164 offset:1024
	ds_read_b128 v[160:163], v164 offset:2048
	ds_read_b128 v[164:167], v164 offset:3072
	ds_read_b128 v[168:171], v180
	ds_read_b128 v[172:175], v180 offset:1024
	ds_read_b128 v[176:179], v180 offset:2048
	ds_read_b128 v[180:183], v180 offset:3072
	s_add_u32 s36, s36, 0x40000
	s_addc_u32 s37, s37, 0
	s_mov_b32 m0, s44
	v_lshl_add_u64 v[224:225], s[36:37], 0, v[128:129]
	ds_read_b128 v[186:189], v151 offset:32768
	ds_read_b128 v[190:193], v151 offset:33792
	ds_read_b128 v[194:197], v151 offset:34816
	ds_read_b128 v[198:201], v151 offset:35840
	ds_read_b128 v[202:205], v151 offset:36864
	ds_read_b128 v[206:209], v151 offset:37888
	ds_read_b128 v[210:213], v151 offset:38912
	ds_read_b128 v[214:217], v151 offset:39936
	global_load_lds_dwordx4 v[224:225], off
	s_mov_b32 m0, s45
	v_lshl_add_u64 v[224:225], s[36:37], 0, v[132:133]
	global_load_lds_dwordx4 v[224:225], off
	s_waitcnt vmcnt(8)
	s_waitcnt lgkmcnt(0)
	s_barrier
	s_setprio 1
	s_waitcnt lgkmcnt(0)
	v_mfma_f32_16x16x32_bf16 v[124:127], v[152:155], v[186:189], v[124:127]
	v_mfma_f32_16x16x32_bf16 v[120:123], v[160:163], v[186:189], v[120:123]
	v_mfma_f32_16x16x32_bf16 v[116:119], v[152:155], v[194:197], v[116:119]
	v_mfma_f32_16x16x32_bf16 v[108:111], v[160:163], v[194:197], v[108:111]
	v_mfma_f32_16x16x32_bf16 v[100:103], v[152:155], v[202:205], v[100:103]
	v_mfma_f32_16x16x32_bf16 v[92:95], v[160:163], v[202:205], v[92:95]
	v_mfma_f32_16x16x32_bf16 v[84:87], v[152:155], v[210:213], v[84:87]
	v_mfma_f32_16x16x32_bf16 v[76:79], v[160:163], v[210:213], v[76:79]
	v_mfma_f32_16x16x32_bf16 v[124:127], v[156:159], v[190:193], v[124:127]
	v_mfma_f32_16x16x32_bf16 v[120:123], v[164:167], v[190:193], v[120:123]
	v_mfma_f32_16x16x32_bf16 v[116:119], v[156:159], v[198:201], v[116:119]
	v_mfma_f32_16x16x32_bf16 v[108:111], v[164:167], v[198:201], v[108:111]
	v_mfma_f32_16x16x32_bf16 v[100:103], v[156:159], v[206:209], v[100:103]
	v_mfma_f32_16x16x32_bf16 v[92:95], v[164:167], v[206:209], v[92:95]
	v_mfma_f32_16x16x32_bf16 v[84:87], v[156:159], v[214:217], v[84:87]
	v_mfma_f32_16x16x32_bf16 v[76:79], v[164:167], v[214:217], v[76:79]
	s_setprio 0
	s_setprio 1
	v_mfma_f32_16x16x32_bf16 v[112:115], v[168:171], v[186:189], v[112:115]
	v_mfma_f32_16x16x32_bf16 v[104:107], v[176:179], v[186:189], v[104:107]
	v_mfma_f32_16x16x32_bf16 v[96:99], v[168:171], v[194:197], v[96:99]
	v_mfma_f32_16x16x32_bf16 v[88:91], v[176:179], v[194:197], v[88:91]
	v_mfma_f32_16x16x32_bf16 v[80:83], v[168:171], v[202:205], v[80:83]
	v_mfma_f32_16x16x32_bf16 v[72:75], v[176:179], v[202:205], v[72:75]
	v_mfma_f32_16x16x32_bf16 v[68:71], v[168:171], v[210:213], v[68:71]
	v_mfma_f32_16x16x32_bf16 v[64:67], v[176:179], v[210:213], v[64:67]
	v_mfma_f32_16x16x32_bf16 v[112:115], v[172:175], v[190:193], v[112:115]
	v_mfma_f32_16x16x32_bf16 v[104:107], v[180:183], v[190:193], v[104:107]
	v_mfma_f32_16x16x32_bf16 v[96:99], v[172:175], v[198:201], v[96:99]
	v_mfma_f32_16x16x32_bf16 v[88:91], v[180:183], v[198:201], v[88:91]
	v_mfma_f32_16x16x32_bf16 v[80:83], v[172:175], v[206:209], v[80:83]
	v_mfma_f32_16x16x32_bf16 v[72:75], v[180:183], v[206:209], v[72:75]
	v_mfma_f32_16x16x32_bf16 v[68:71], v[172:175], v[214:217], v[68:71]
	v_mfma_f32_16x16x32_bf16 v[64:67], v[180:183], v[214:217], v[64:67]
	s_setprio 0
	s_barrier
; #define PG8_STAGE(bufoff, gbase, voff) do { _Pragma("unroll") for (int _i = 0; _i < 2; ++_i) \
;         __builtin_amdgcn_global_load_lds((const unsigned*)((const char*)(gbase) + (voff)[_i]), (PG8_LAS unsigned*)(lds + (bufoff) + ldsw + _i * 8192), 16, 0, 0); } while (0)
; #define PG8_LDA(dst, b, h) do { _Pragma("unroll") for (int m = 0; m < 4; ++m) _Pragma("unroll") for (int k = 0; k < 2; ++k) dst[m][k] = *(const PG8_LAS bf16x8*)(lds + PG8_SA(b, h) + aoff + m * 2048 + k * 1024); } while (0)
; #define PG8_MMA(ai, bj, At, Bt) do { __builtin_amdgcn_s_setprio(1); _Pragma("unroll") for (int m = 0; m < 4; ++m) _Pragma("unroll") for (int n = 0; n < 2; ++n) _Pragma("unroll") for (int k = 0; k < 2; ++k) \
;         acc[ai][bj][m][n] = __builtin_amdgcn_mfma_f32_16x16x32_bf16(Bt[n][k], At[m][k], acc[ai][bj][m][n], 0, 0, 0); __builtin_amdgcn_s_setprio(0); } while (0)
; #define PG8_WAIT_V(n) asm volatile("s_waitcnt vmcnt(" #n ")" ::: "memory")
; #define PG8_WAIT_L(n) asm volatile("s_waitcnt lgkmcnt(" #n ")" ::: "memory")
; #define PG8_BAR __builtin_amdgcn_s_barrier()
; #define PG8_SCHED __builtin_amdgcn_sched_barrier(0)
; template <class Epi, class Sched, bool ALIGN_EPI = false, bool SP2 = false>
; __device__ __forceinline__ void gemm_phase(PG8_LAS unsigned char* lds, const Gemm g, const Sched& S, const Epi& E) {
;     ...
;         for (int t = 0; t < nt; t += 2) {
;             const bool last = (t == nt - 2);
;             const char* a1 = cA + (size_t)(t + 1) * kstep;
;             const char* a2 = last ? nA : cA + (size_t)(t + 2) * kstep; const char* b2 = last ? nB : cB + (size_t)(t + 2) * kstep;
;             const char* a3 = a2 + kstep; const char* b3 = b2 + kstep;
;     ...
;             PG8_LDA(At, 1, 1); PG8_STAGE(PG8_SB(1, 0), b3, voffB); PG8_STAGE(PG8_SB(1, 1), b3 + hstep, voffB); PG8_STAGE(PG8_SA(1, 0), a3, voffA);
;             PG8_WAIT_V(8); PG8_WAIT_L(0); PG8_BAR; PG8_MMA(1, 0, At, B0); PG8_MMA(1, 1, At, B1); PG8_BAR; PG8_SCHED;
	s_add_i32 s36, s62, s42
	v_lshl_add_u64 v[144:145], v[144:145], 0, s[10:11]
	s_mov_b32 m0, s36
	ds_read_b128 v[186:189], v151 offset:49152
	ds_read_b128 v[190:193], v151 offset:50176
	ds_read_b128 v[194:197], v151 offset:51200
	ds_read_b128 v[198:201], v151 offset:52224
	ds_read_b128 v[202:205], v151 offset:53248
	ds_read_b128 v[206:209], v151 offset:54272
	ds_read_b128 v[210:213], v151 offset:55296
	ds_read_b128 v[214:217], v151 offset:56320
	global_load_lds_dwordx4 v[144:145], off
	s_add_i32 m0, s36, 0x2000
	s_add_u32 s34, s34, 0x40080
	v_lshl_add_u64 v[144:145], v[218:219], 0, s[10:11]
	s_addc_u32 s35, s35, 0
	s_add_i32 s36, s63, s42
	global_load_lds_dwordx4 v[144:145], off
	s_mov_b32 m0, s36
	v_lshl_add_u64 v[144:145], s[34:35], 0, v[130:131]
	global_load_lds_dwordx4 v[144:145], off
	s_add_i32 m0, s36, 0x2000
	v_lshl_add_u64 v[144:145], s[34:35], 0, v[134:135]
	global_load_lds_dwordx4 v[144:145], off
	s_mov_b32 m0, s47
	v_lshl_add_u64 v[144:145], v[220:221], 0, s[10:11]
	global_load_lds_dwordx4 v[144:145], off
	s_mov_b32 m0, s48
	v_lshl_add_u64 v[144:145], v[222:223], 0, s[10:11]
	global_load_lds_dwordx4 v[144:145], off
	s_waitcnt vmcnt(8)
	s_waitcnt lgkmcnt(0)
	s_barrier
	s_setprio 1
	s_waitcnt lgkmcnt(0)
	v_mfma_f32_16x16x32_bf16 v[60:63], v[152:155], v[186:189], v[60:63]
	v_mfma_f32_16x16x32_bf16 v[56:59], v[160:163], v[186:189], v[56:59]
	v_mfma_f32_16x16x32_bf16 v[52:55], v[152:155], v[194:197], v[52:55]
	v_mfma_f32_16x16x32_bf16 v[44:47], v[160:163], v[194:197], v[44:47]
	v_mfma_f32_16x16x32_bf16 v[36:39], v[152:155], v[202:205], v[36:39]
	v_mfma_f32_16x16x32_bf16 v[28:31], v[160:163], v[202:205], v[28:31]
	v_mfma_f32_16x16x32_bf16 v[20:23], v[152:155], v[210:213], v[20:23]
	v_mfma_f32_16x16x32_bf16 v[12:15], v[160:163], v[210:213], v[12:15]
	v_mfma_f32_16x16x32_bf16 v[60:63], v[156:159], v[190:193], v[60:63]
	v_mfma_f32_16x16x32_bf16 v[56:59], v[164:167], v[190:193], v[56:59]
	v_mfma_f32_16x16x32_bf16 v[52:55], v[156:159], v[198:201], v[52:55]
	v_mfma_f32_16x16x32_bf16 v[44:47], v[164:167], v[198:201], v[44:47]
	v_mfma_f32_16x16x32_bf16 v[36:39], v[156:159], v[206:209], v[36:39]
	v_mfma_f32_16x16x32_bf16 v[28:31], v[164:167], v[206:209], v[28:31]
	v_mfma_f32_16x16x32_bf16 v[20:23], v[156:159], v[214:217], v[20:23]
	v_mfma_f32_16x16x32_bf16 v[12:15], v[164:167], v[214:217], v[12:15]
	s_setprio 0
	s_setprio 1
	v_mfma_f32_16x16x32_bf16 v[48:51], v[168:171], v[186:189], v[48:51]
	v_mfma_f32_16x16x32_bf16 v[40:43], v[176:179], v[186:189], v[40:43]
	v_mfma_f32_16x16x32_bf16 v[32:35], v[168:171], v[194:197], v[32:35]
	v_mfma_f32_16x16x32_bf16 v[24:27], v[176:179], v[194:197], v[24:27]
	v_mfma_f32_16x16x32_bf16 v[16:19], v[168:171], v[202:205], v[16:19]
	v_mfma_f32_16x16x32_bf16 v[8:11], v[176:179], v[202:205], v[8:11]
	v_mfma_f32_16x16x32_bf16 v[4:7], v[168:171], v[210:213], v[4:7]
	v_mfma_f32_16x16x32_bf16 v[0:3], v[176:179], v[210:213], v[0:3]
	v_mfma_f32_16x16x32_bf16 v[48:51], v[172:175], v[190:193], v[48:51]
	v_mfma_f32_16x16x32_bf16 v[40:43], v[180:183], v[190:193], v[40:43]
	v_mfma_f32_16x16x32_bf16 v[32:35], v[172:175], v[198:201], v[32:35]
	v_mfma_f32_16x16x32_bf16 v[24:27], v[180:183], v[198:201], v[24:27]
	v_mfma_f32_16x16x32_bf16 v[16:19], v[172:175], v[206:209], v[16:19]
	v_mfma_f32_16x16x32_bf16 v[8:11], v[180:183], v[206:209], v[8:11]
	v_mfma_f32_16x16x32_bf16 v[4:7], v[172:175], v[214:217], v[4:7]
	v_mfma_f32_16x16x32_bf16 v[0:3], v[180:183], v[214:217], v[0:3]
	s_setprio 0
	s_barrier
	s_add_i32 s61, s61, 2
	s_add_u32 s59, s59, 0x100
	s_addc_u32 s60, s60, 0
	s_add_u32 s30, s30, 0x100
	s_addc_u32 s31, s31, 0
	s_cmp_gt_u32 s61, 13
	s_cbranch_scc0 .LBB0_868
	s_and_b64 vcc, exec, s[12:13]
	s_cbranch_vccz .LBB0_871
	s_barrier

; #define PG8_STAGE(bufoff, gbase, voff) do { _Pragma("unroll") for (int _i = 0; _i < 2; ++_i) \
;         __builtin_amdgcn_global_load_lds((const unsigned*)((const char*)(gbase) + (voff)[_i]), (PG8_LAS unsigned*)(lds + (bufoff) + ldsw + _i * 8192), 16, 0, 0); } while (0)
; #define PG8_LDA(dst, b, h) do { _Pragma("unroll") for (int m = 0; m < 4; ++m) _Pragma("unroll") for (int k = 0; k < 2; ++k) dst[m][k] = *(const PG8_LAS bf16x8*)(lds + PG8_SA(b, h) + aoff + m * 2048 + k * 1024); } while (0)
; #define PG8_LDB(dst, b, h) do { _Pragma("unroll") for (int n = 0; n < 2; ++n) _Pragma("unroll") for (int k = 0; k < 2; ++k) dst[n][k] = *(const PG8_LAS bf16x8*)(lds + PG8_SB(b, h) + boff + n * 2048 + k * 1024); } while (0)
; #define PG8_MMA(ai, bj, At, Bt) do { __builtin_amdgcn_s_setprio(1); _Pragma("unroll") for (int m = 0; m < 4; ++m) _Pragma("unroll") for (int n = 0; n < 2; ++n) _Pragma("unroll") for (int k = 0; k < 2; ++k) \
;         acc[ai][bj][m][n] = __builtin_amdgcn_mfma_f32_16x16x32_bf16(Bt[n][k], At[m][k], acc[ai][bj][m][n], 0, 0, 0); __builtin_amdgcn_s_setprio(0); } while (0)
; #define PG8_WAIT_V(n) asm volatile("s_waitcnt vmcnt(" #n ")" ::: "memory")
; #define PG8_WAIT_L(n) asm volatile("s_waitcnt lgkmcnt(" #n ")" ::: "memory")
; #define PG8_BAR __builtin_amdgcn_s_barrier()
; #define PG8_SCHED __builtin_amdgcn_sched_barrier(0)
; template <class Epi, class Sched, bool ALIGN_EPI = false, bool SP2 = false>
; __device__ __forceinline__ void gemm_phase(PG8_LAS unsigned char* lds, const Gemm g, const Sched& S, const Epi& E) {
;     ...
;         for (int t = 0; t < nt; t += 2) {
;             const bool last = (t == nt - 2);
;             const char* a1 = cA + (size_t)(t + 1) * kstep;
;             const char* a2 = last ? nA : cA + (size_t)(t + 2) * kstep; const char* b2 = last ? nB : cB + (size_t)(t + 2) * kstep;
;             const char* a3 = a2 + kstep; const char* b3 = b2 + kstep;
;             if (last && has_next) S.a_ready(nxt);
;             if constexpr (SP2) {
;             PG8_LDB(B0, 0, 0); PG8_LDB(B1, 0, 1); PG8_SCHED; PG8_LDA(At, 0, 0); PG8_STAGE(PG8_SA(1, 1), a1 + hstep, voffA);
;             PG8_WAIT_V(8); PG8_WAIT_L(0); PG8_BAR; PG8_MMA(0, 0, At, B0); PG8_MMA(0, 1, At, B1); PG8_BAR; PG8_SCHED;
;             PG8_LDA(At, 0, 1); PG8_STAGE(PG8_SB(0, 0), b2, voffB); PG8_STAGE(PG8_SB(0, 1), b2 + hstep, voffB); PG8_STAGE(PG8_SA(0, 0), a2, voffA);
.LBB0_937:
	ds_read_b128 v[148:151], v145
	ds_read_b128 v[152:155], v145 offset:1024
	ds_read_b128 v[156:159], v145 offset:2048
	ds_read_b128 v[160:163], v145 offset:3072
	ds_read_b128 v[164:167], v146
	ds_read_b128 v[168:171], v146 offset:1024
	ds_read_b128 v[172:175], v146 offset:2048
	ds_read_b128 v[176:179], v146 offset:3072
	s_add_u32 s34, s30, 0xfffc0080
	s_addc_u32 s35, s31, -1
	s_cmp_eq_u32 s60, 12
	s_cselect_b32 s37, s23, s35
	s_cselect_b32 s36, s56, s34
	s_cselect_b32 s35, s21, s59
	s_cselect_b32 s34, s57, s58
	v_lshl_add_u64 v[140:141], s[30:31], 0, v[138:139]
	s_add_i32 m0, s40, 0xc000
	ds_read_b128 v[180:183], v147
	ds_read_b128 v[186:189], v147 offset:1024
	ds_read_b128 v[190:193], v147 offset:2048
	ds_read_b128 v[194:197], v147 offset:3072
	ds_read_b128 v[198:201], v147 offset:4096
	ds_read_b128 v[202:205], v147 offset:5120
	ds_read_b128 v[206:209], v147 offset:6144
	ds_read_b128 v[210:213], v147 offset:7168
	global_load_lds_dwordx4 v[140:141], off
	s_add_i32 m0, s40, 0xe000
	v_lshl_add_u64 v[140:141], s[30:31], 0, v[136:137]
	global_load_lds_dwordx4 v[140:141], off
	s_waitcnt vmcnt(8)
	s_waitcnt lgkmcnt(0)
	s_barrier
	s_setprio 1
	s_waitcnt lgkmcnt(0)
	v_mfma_f32_16x16x32_bf16 v[124:127], v[148:151], v[180:183], v[124:127]
	v_mfma_f32_16x16x32_bf16 v[120:123], v[156:159], v[180:183], v[120:123]
	v_mfma_f32_16x16x32_bf16 v[116:119], v[148:151], v[190:193], v[116:119]
	v_mfma_f32_16x16x32_bf16 v[108:111], v[156:159], v[190:193], v[108:111]
	v_mfma_f32_16x16x32_bf16 v[100:103], v[148:151], v[198:201], v[100:103]
	v_mfma_f32_16x16x32_bf16 v[92:95], v[156:159], v[198:201], v[92:95]
	v_mfma_f32_16x16x32_bf16 v[84:87], v[148:151], v[206:209], v[84:87]
	v_mfma_f32_16x16x32_bf16 v[76:79], v[156:159], v[206:209], v[76:79]
	v_mfma_f32_16x16x32_bf16 v[124:127], v[152:155], v[186:189], v[124:127]
	v_mfma_f32_16x16x32_bf16 v[120:123], v[160:163], v[186:189], v[120:123]
	v_mfma_f32_16x16x32_bf16 v[116:119], v[152:155], v[194:197], v[116:119]
	v_mfma_f32_16x16x32_bf16 v[108:111], v[160:163], v[194:197], v[108:111]
	v_mfma_f32_16x16x32_bf16 v[100:103], v[152:155], v[202:205], v[100:103]
	v_mfma_f32_16x16x32_bf16 v[92:95], v[160:163], v[202:205], v[92:95]
	v_mfma_f32_16x16x32_bf16 v[84:87], v[152:155], v[210:213], v[84:87]
	v_mfma_f32_16x16x32_bf16 v[76:79], v[160:163], v[210:213], v[76:79]
	s_setprio 0
	s_setprio 1
	v_mfma_f32_16x16x32_bf16 v[112:115], v[164:167], v[180:183], v[112:115]
	v_mfma_f32_16x16x32_bf16 v[104:107], v[172:175], v[180:183], v[104:107]
	v_mfma_f32_16x16x32_bf16 v[96:99], v[164:167], v[190:193], v[96:99]
	v_mfma_f32_16x16x32_bf16 v[88:91], v[172:175], v[190:193], v[88:91]
	v_mfma_f32_16x16x32_bf16 v[80:83], v[164:167], v[198:201], v[80:83]
	v_mfma_f32_16x16x32_bf16 v[72:75], v[172:175], v[198:201], v[72:75]
	v_mfma_f32_16x16x32_bf16 v[68:71], v[164:167], v[206:209], v[68:71]
	v_mfma_f32_16x16x32_bf16 v[64:67], v[172:175], v[206:209], v[64:67]
	v_mfma_f32_16x16x32_bf16 v[112:115], v[168:171], v[186:189], v[112:115]
	v_mfma_f32_16x16x32_bf16 v[104:107], v[176:179], v[186:189], v[104:107]
	v_mfma_f32_16x16x32_bf16 v[96:99], v[168:171], v[194:197], v[96:99]
	v_mfma_f32_16x16x32_bf16 v[88:91], v[176:179], v[194:197], v[88:91]
	v_mfma_f32_16x16x32_bf16 v[80:83], v[168:171], v[202:205], v[80:83]
	v_mfma_f32_16x16x32_bf16 v[72:75], v[176:179], v[202:205], v[72:75]
	v_mfma_f32_16x16x32_bf16 v[68:71], v[168:171], v[210:213], v[68:71]
	v_mfma_f32_16x16x32_bf16 v[64:67], v[176:179], v[210:213], v[64:67]
	s_setprio 0
	s_barrier
	s_add_i32 s61, s48, s39
	v_lshl_add_u64 v[140:141], s[34:35], 0, v[130:131]
	s_mov_b32 m0, s61
	ds_read_b128 v[180:183], v147 offset:16384
	ds_read_b128 v[186:189], v147 offset:17408
	ds_read_b128 v[190:193], v147 offset:18432
	ds_read_b128 v[194:197], v147 offset:19456
	ds_read_b128 v[198:201], v147 offset:20480
	ds_read_b128 v[202:205], v147 offset:21504
	ds_read_b128 v[206:209], v147 offset:22528
	ds_read_b128 v[210:213], v147 offset:23552
	global_load_lds_dwordx4 v[140:141], off
	s_add_i32 m0, s61, 0x2000
	s_add_u32 s62, s34, 0x40000
	v_lshl_add_u64 v[214:215], s[34:35], 0, v[134:135]
	s_addc_u32 s63, s35, 0
	s_add_i32 s61, s93, s39
	global_load_lds_dwordx4 v[214:215], off
	v_lshl_add_u64 v[216:217], s[62:63], 0, v[130:131]
	s_mov_b32 m0, s61
	v_lshl_add_u64 v[218:219], s[36:37], 0, v[132:133]
	global_load_lds_dwordx4 v[216:217], off
	s_add_i32 m0, s61, 0x2000
	v_lshl_add_u64 v[216:217], s[62:63], 0, v[134:135]
	global_load_lds_dwordx4 v[216:217], off
	s_mov_b32 m0, s40
	v_lshl_add_u64 v[216:217], s[36:37], 0, v[128:129]
	global_load_lds_dwordx4 v[216:217], off
	s_mov_b32 m0, s41
	s_nop 0
	global_load_lds_dwordx4 v[218:219], off
	s_waitcnt vmcnt(8)
	s_waitcnt lgkmcnt(0)
	s_barrier
; #define PG8_STAGE(bufoff, gbase, voff) do { _Pragma("unroll") for (int _i = 0; _i < 2; ++_i) \
;         __builtin_amdgcn_global_load_lds((const unsigned*)((const char*)(gbase) + (voff)[_i]), (PG8_LAS unsigned*)(lds + (bufoff) + ldsw + _i * 8192), 16, 0, 0); } while (0)
; #define PG8_LDA(dst, b, h) do { _Pragma("unroll") for (int m = 0; m < 4; ++m) _Pragma("unroll") for (int k = 0; k < 2; ++k) dst[m][k] = *(const PG8_LAS bf16x8*)(lds + PG8_SA(b, h) + aoff + m * 2048 + k * 1024); } while (0)
; #define PG8_LDB(dst, b, h) do { _Pragma("unroll") for (int n = 0; n < 2; ++n) _Pragma("unroll") for (int k = 0; k < 2; ++k) dst[n][k] = *(const PG8_LAS bf16x8*)(lds + PG8_SB(b, h) + boff + n * 2048 + k * 1024); } while (0)
; #define PG8_MMA(ai, bj, At, Bt) do { __builtin_amdgcn_s_setprio(1); _Pragma("unroll") for (int m = 0; m < 4; ++m) _Pragma("unroll") for (int n = 0; n < 2; ++n) _Pragma("unroll") for (int k = 0; k < 2; ++k) \
;         acc[ai][bj][m][n] = __builtin_amdgcn_mfma_f32_16x16x32_bf16(Bt[n][k], At[m][k], acc[ai][bj][m][n], 0, 0, 0); __builtin_amdgcn_s_setprio(0); } while (0)
; #define PG8_WAIT_V(n) asm volatile("s_waitcnt vmcnt(" #n ")" ::: "memory")
; #define PG8_WAIT_L(n) asm volatile("s_waitcnt lgkmcnt(" #n ")" ::: "memory")
; #define PG8_BAR __builtin_amdgcn_s_barrier()
; #define PG8_SCHED __builtin_amdgcn_sched_barrier(0)
; template <class Epi, class Sched, bool ALIGN_EPI = false, bool SP2 = false>
; __device__ __forceinline__ void gemm_phase(PG8_LAS unsigned char* lds, const Gemm g, const Sched& S, const Epi& E) {
;     ...
;             PG8_WAIT_V(8); PG8_WAIT_L(0); PG8_BAR; PG8_MMA(1, 0, At, B0); PG8_MMA(1, 1, At, B1); PG8_BAR; PG8_SCHED;
;             PG8_LDB(B0, 1, 0); PG8_LDB(B1, 1, 1); PG8_SCHED; PG8_LDA(At, 1, 0); PG8_STAGE(PG8_SA(0, 1), a2 + hstep, voffA);
;             PG8_WAIT_V(8); PG8_WAIT_L(0); PG8_BAR; PG8_MMA(0, 0, At, B0); PG8_MMA(0, 1, At, B1); PG8_BAR; PG8_SCHED;
	s_setprio 1
	s_waitcnt lgkmcnt(0)
	v_mfma_f32_16x16x32_bf16 v[60:63], v[148:151], v[180:183], v[60:63]
	v_mfma_f32_16x16x32_bf16 v[56:59], v[156:159], v[180:183], v[56:59]
	v_mfma_f32_16x16x32_bf16 v[52:55], v[148:151], v[190:193], v[52:55]
	v_mfma_f32_16x16x32_bf16 v[44:47], v[156:159], v[190:193], v[44:47]
	v_mfma_f32_16x16x32_bf16 v[36:39], v[148:151], v[198:201], v[36:39]
	v_mfma_f32_16x16x32_bf16 v[28:31], v[156:159], v[198:201], v[28:31]
	v_mfma_f32_16x16x32_bf16 v[20:23], v[148:151], v[206:209], v[20:23]
	v_mfma_f32_16x16x32_bf16 v[12:15], v[156:159], v[206:209], v[12:15]
	v_mfma_f32_16x16x32_bf16 v[60:63], v[152:155], v[186:189], v[60:63]
	v_mfma_f32_16x16x32_bf16 v[56:59], v[160:163], v[186:189], v[56:59]
	v_mfma_f32_16x16x32_bf16 v[52:55], v[152:155], v[194:197], v[52:55]
	v_mfma_f32_16x16x32_bf16 v[44:47], v[160:163], v[194:197], v[44:47]
	v_mfma_f32_16x16x32_bf16 v[36:39], v[152:155], v[202:205], v[36:39]
	v_mfma_f32_16x16x32_bf16 v[28:31], v[160:163], v[202:205], v[28:31]
	v_mfma_f32_16x16x32_bf16 v[20:23], v[152:155], v[210:213], v[20:23]
	v_mfma_f32_16x16x32_bf16 v[12:15], v[160:163], v[210:213], v[12:15]
	s_setprio 0
	s_setprio 1
	v_mfma_f32_16x16x32_bf16 v[48:51], v[164:167], v[180:183], v[48:51]
	v_mfma_f32_16x16x32_bf16 v[40:43], v[172:175], v[180:183], v[40:43]
	v_mfma_f32_16x16x32_bf16 v[32:35], v[164:167], v[190:193], v[32:35]
	v_mfma_f32_16x16x32_bf16 v[24:27], v[172:175], v[190:193], v[24:27]
	v_mfma_f32_16x16x32_bf16 v[16:19], v[164:167], v[198:201], v[16:19]
	v_mfma_f32_16x16x32_bf16 v[8:11], v[172:175], v[198:201], v[8:11]
	v_mfma_f32_16x16x32_bf16 v[4:7], v[164:167], v[206:209], v[4:7]
	v_mfma_f32_16x16x32_bf16 v[0:3], v[172:175], v[206:209], v[0:3]
	v_mfma_f32_16x16x32_bf16 v[48:51], v[168:171], v[186:189], v[48:51]
	v_mfma_f32_16x16x32_bf16 v[40:43], v[176:179], v[186:189], v[40:43]
	v_mfma_f32_16x16x32_bf16 v[32:35], v[168:171], v[194:197], v[32:35]
	v_mfma_f32_16x16x32_bf16 v[24:27], v[176:179], v[194:197], v[24:27]
	v_mfma_f32_16x16x32_bf16 v[16:19], v[168:171], v[202:205], v[16:19]
	v_mfma_f32_16x16x32_bf16 v[8:11], v[176:179], v[202:205], v[8:11]
	v_mfma_f32_16x16x32_bf16 v[4:7], v[168:171], v[210:213], v[4:7]
	v_mfma_f32_16x16x32_bf16 v[0:3], v[176:179], v[210:213], v[0:3]
	s_setprio 0
	s_barrier
	s_add_i32 s61, 0, 0x18000
	s_add_i32 s62, 0, 0x1c000
	v_add_u32_e32 v160, s61, v143
	v_add_u32_e32 v176, s62, v143
	ds_read_b128 v[148:151], v160
	ds_read_b128 v[152:155], v160 offset:1024
	ds_read_b128 v[156:159], v160 offset:2048
	ds_read_b128 v[160:163], v160 offset:3072
	ds_read_b128 v[164:167], v176
	ds_read_b128 v[168:171], v176 offset:1024
	ds_read_b128 v[172:175], v176 offset:2048
	ds_read_b128 v[176:179], v176 offset:3072
	s_add_u32 s36, s36, 0x40000
	s_addc_u32 s37, s37, 0
	s_mov_b32 m0, s42
	v_lshl_add_u64 v[220:221], s[36:37], 0, v[128:129]
	ds_read_b128 v[180:183], v147 offset:32768
	ds_read_b128 v[186:189], v147 offset:33792
	ds_read_b128 v[190:193], v147 offset:34816
	ds_read_b128 v[194:197], v147 offset:35840
	ds_read_b128 v[198:201], v147 offset:36864
	ds_read_b128 v[202:205], v147 offset:37888
	ds_read_b128 v[206:209], v147 offset:38912
	ds_read_b128 v[210:213], v147 offset:39936
	global_load_lds_dwordx4 v[220:221], off
	s_mov_b32 m0, s43
	v_lshl_add_u64 v[220:221], s[36:37], 0, v[132:133]
	global_load_lds_dwordx4 v[220:221], off
	s_waitcnt vmcnt(8)
	s_waitcnt lgkmcnt(0)
	s_barrier
	s_setprio 1
	s_waitcnt lgkmcnt(0)
	v_mfma_f32_16x16x32_bf16 v[124:127], v[148:151], v[180:183], v[124:127]
	v_mfma_f32_16x16x32_bf16 v[120:123], v[156:159], v[180:183], v[120:123]
	v_mfma_f32_16x16x32_bf16 v[116:119], v[148:151], v[190:193], v[116:119]
	v_mfma_f32_16x16x32_bf16 v[108:111], v[156:159], v[190:193], v[108:111]
	v_mfma_f32_16x16x32_bf16 v[100:103], v[148:151], v[198:201], v[100:103]
	v_mfma_f32_16x16x32_bf16 v[92:95], v[156:159], v[198:201], v[92:95]
	v_mfma_f32_16x16x32_bf16 v[84:87], v[148:151], v[206:209], v[84:87]
	v_mfma_f32_16x16x32_bf16 v[76:79], v[156:159], v[206:209], v[76:79]
	v_mfma_f32_16x16x32_bf16 v[124:127], v[152:155], v[186:189], v[124:127]
	v_mfma_f32_16x16x32_bf16 v[120:123], v[160:163], v[186:189], v[120:123]
	v_mfma_f32_16x16x32_bf16 v[116:119], v[152:155], v[194:197], v[116:119]
	v_mfma_f32_16x16x32_bf16 v[108:111], v[160:163], v[194:197], v[108:111]
	v_mfma_f32_16x16x32_bf16 v[100:103], v[152:155], v[202:205], v[100:103]
	v_mfma_f32_16x16x32_bf16 v[92:95], v[160:163], v[202:205], v[92:95]
	v_mfma_f32_16x16x32_bf16 v[84:87], v[152:155], v[210:213], v[84:87]
	v_mfma_f32_16x16x32_bf16 v[76:79], v[160:163], v[210:213], v[76:79]
	s_setprio 0
	s_setprio 1
	v_mfma_f32_16x16x32_bf16 v[112:115], v[164:167], v[180:183], v[112:115]
	v_mfma_f32_16x16x32_bf16 v[104:107], v[172:175], v[180:183], v[104:107]
	v_mfma_f32_16x16x32_bf16 v[96:99], v[164:167], v[190:193], v[96:99]
	v_mfma_f32_16x16x32_bf16 v[88:91], v[172:175], v[190:193], v[88:91]
	v_mfma_f32_16x16x32_bf16 v[80:83], v[164:167], v[198:201], v[80:83]
	v_mfma_f32_16x16x32_bf16 v[72:75], v[172:175], v[198:201], v[72:75]
	v_mfma_f32_16x16x32_bf16 v[68:71], v[164:167], v[206:209], v[68:71]
	v_mfma_f32_16x16x32_bf16 v[64:67], v[172:175], v[206:209], v[64:67]
	v_mfma_f32_16x16x32_bf16 v[112:115], v[168:171], v[186:189], v[112:115]
	v_mfma_f32_16x16x32_bf16 v[104:107], v[176:179], v[186:189], v[104:107]
	v_mfma_f32_16x16x32_bf16 v[96:99], v[168:171], v[194:197], v[96:99]
	v_mfma_f32_16x16x32_bf16 v[88:91], v[176:179], v[194:197], v[88:91]
	v_mfma_f32_16x16x32_bf16 v[80:83], v[168:171], v[202:205], v[80:83]
	v_mfma_f32_16x16x32_bf16 v[72:75], v[176:179], v[202:205], v[72:75]
	v_mfma_f32_16x16x32_bf16 v[68:71], v[168:171], v[210:213], v[68:71]
	v_mfma_f32_16x16x32_bf16 v[64:67], v[176:179], v[210:213], v[64:67]
	s_setprio 0
	s_barrier
; #define PG8_STAGE(bufoff, gbase, voff) do { _Pragma("unroll") for (int _i = 0; _i < 2; ++_i) \
;         __builtin_amdgcn_global_load_lds((const unsigned*)((const char*)(gbase) + (voff)[_i]), (PG8_LAS unsigned*)(lds + (bufoff) + ldsw + _i * 8192), 16, 0, 0); } while (0)
; #define PG8_LDA(dst, b, h) do { _Pragma("unroll") for (int m = 0; m < 4; ++m) _Pragma("unroll") for (int k = 0; k < 2; ++k) dst[m][k] = *(const PG8_LAS bf16x8*)(lds + PG8_SA(b, h) + aoff + m * 2048 + k * 1024); } while (0)
; #define PG8_MMA(ai, bj, At, Bt) do { __builtin_amdgcn_s_setprio(1); _Pragma("unroll") for (int m = 0; m < 4; ++m) _Pragma("unroll") for (int n = 0; n < 2; ++n) _Pragma("unroll") for (int k = 0; k < 2; ++k) \
;         acc[ai][bj][m][n] = __builtin_amdgcn_mfma_f32_16x16x32_bf16(Bt[n][k], At[m][k], acc[ai][bj][m][n], 0, 0, 0); __builtin_amdgcn_s_setprio(0); } while (0)
; #define PG8_WAIT_V(n) asm volatile("s_waitcnt vmcnt(" #n ")" ::: "memory")
; #define PG8_WAIT_L(n) asm volatile("s_waitcnt lgkmcnt(" #n ")" ::: "memory")
; #define PG8_BAR __builtin_amdgcn_s_barrier()
; #define PG8_SCHED __builtin_amdgcn_sched_barrier(0)
; template <class Epi, class Sched, bool ALIGN_EPI = false, bool SP2 = false>
; __device__ __forceinline__ void gemm_phase(PG8_LAS unsigned char* lds, const Gemm g, const Sched& S, const Epi& E) {
;     ...
;             PG8_LDA(At, 1, 1); PG8_STAGE(PG8_SB(1, 0), b3, voffB); PG8_STAGE(PG8_SB(1, 1), b3 + hstep, voffB); PG8_STAGE(PG8_SA(1, 0), a3, voffA);
;             PG8_WAIT_V(8); PG8_WAIT_L(0); PG8_BAR; PG8_MMA(1, 0, At, B0); PG8_MMA(1, 1, At, B1); PG8_BAR; PG8_SCHED;
;     ...
;         if constexpr (ALIGN_EPI) { if (wr == 0) PG8_BAR; }
	s_add_i32 s36, s61, s39
	v_lshl_add_u64 v[140:141], v[140:141], 0, s[10:11]
	s_mov_b32 m0, s36
	ds_read_b128 v[180:183], v147 offset:49152
	ds_read_b128 v[186:189], v147 offset:50176
	ds_read_b128 v[190:193], v147 offset:51200
	ds_read_b128 v[194:197], v147 offset:52224
	ds_read_b128 v[198:201], v147 offset:53248
	ds_read_b128 v[202:205], v147 offset:54272
	ds_read_b128 v[206:209], v147 offset:55296
	ds_read_b128 v[210:213], v147 offset:56320
	global_load_lds_dwordx4 v[140:141], off
	s_add_i32 m0, s36, 0x2000
	s_add_u32 s34, s34, 0x40080
	v_lshl_add_u64 v[140:141], v[214:215], 0, s[10:11]
	s_addc_u32 s35, s35, 0
	s_add_i32 s36, s62, s39
	global_load_lds_dwordx4 v[140:141], off
	s_mov_b32 m0, s36
	v_lshl_add_u64 v[140:141], s[34:35], 0, v[130:131]
	global_load_lds_dwordx4 v[140:141], off
	s_add_i32 m0, s36, 0x2000
	v_lshl_add_u64 v[140:141], s[34:35], 0, v[134:135]
	global_load_lds_dwordx4 v[140:141], off
	s_mov_b32 m0, s44
	v_lshl_add_u64 v[140:141], v[216:217], 0, s[10:11]
	global_load_lds_dwordx4 v[140:141], off
	s_mov_b32 m0, s45
	v_lshl_add_u64 v[140:141], v[218:219], 0, s[10:11]
	global_load_lds_dwordx4 v[140:141], off
	s_waitcnt vmcnt(8)
	s_waitcnt lgkmcnt(0)
	s_barrier
	s_setprio 1
	s_waitcnt lgkmcnt(0)
	v_mfma_f32_16x16x32_bf16 v[60:63], v[148:151], v[180:183], v[60:63]
	v_mfma_f32_16x16x32_bf16 v[56:59], v[156:159], v[180:183], v[56:59]
	v_mfma_f32_16x16x32_bf16 v[52:55], v[148:151], v[190:193], v[52:55]
	v_mfma_f32_16x16x32_bf16 v[44:47], v[156:159], v[190:193], v[44:47]
	v_mfma_f32_16x16x32_bf16 v[36:39], v[148:151], v[198:201], v[36:39]
	v_mfma_f32_16x16x32_bf16 v[28:31], v[156:159], v[198:201], v[28:31]
	v_mfma_f32_16x16x32_bf16 v[20:23], v[148:151], v[206:209], v[20:23]
	v_mfma_f32_16x16x32_bf16 v[12:15], v[156:159], v[206:209], v[12:15]
	v_mfma_f32_16x16x32_bf16 v[60:63], v[152:155], v[186:189], v[60:63]
	v_mfma_f32_16x16x32_bf16 v[56:59], v[160:163], v[186:189], v[56:59]
	v_mfma_f32_16x16x32_bf16 v[52:55], v[152:155], v[194:197], v[52:55]
	v_mfma_f32_16x16x32_bf16 v[44:47], v[160:163], v[194:197], v[44:47]
	v_mfma_f32_16x16x32_bf16 v[36:39], v[152:155], v[202:205], v[36:39]
	v_mfma_f32_16x16x32_bf16 v[28:31], v[160:163], v[202:205], v[28:31]
	v_mfma_f32_16x16x32_bf16 v[20:23], v[152:155], v[210:213], v[20:23]
	v_mfma_f32_16x16x32_bf16 v[12:15], v[160:163], v[210:213], v[12:15]
	s_setprio 0
	s_setprio 1
	v_mfma_f32_16x16x32_bf16 v[48:51], v[164:167], v[180:183], v[48:51]
	v_mfma_f32_16x16x32_bf16 v[40:43], v[172:175], v[180:183], v[40:43]
	v_mfma_f32_16x16x32_bf16 v[32:35], v[164:167], v[190:193], v[32:35]
	v_mfma_f32_16x16x32_bf16 v[24:27], v[172:175], v[190:193], v[24:27]
	v_mfma_f32_16x16x32_bf16 v[16:19], v[164:167], v[198:201], v[16:19]
	v_mfma_f32_16x16x32_bf16 v[8:11], v[172:175], v[198:201], v[8:11]
	v_mfma_f32_16x16x32_bf16 v[4:7], v[164:167], v[206:209], v[4:7]
	v_mfma_f32_16x16x32_bf16 v[0:3], v[172:175], v[206:209], v[0:3]
	v_mfma_f32_16x16x32_bf16 v[48:51], v[168:171], v[186:189], v[48:51]
	v_mfma_f32_16x16x32_bf16 v[40:43], v[176:179], v[186:189], v[40:43]
	v_mfma_f32_16x16x32_bf16 v[32:35], v[168:171], v[194:197], v[32:35]
	v_mfma_f32_16x16x32_bf16 v[24:27], v[176:179], v[194:197], v[24:27]
	v_mfma_f32_16x16x32_bf16 v[16:19], v[168:171], v[202:205], v[16:19]
	v_mfma_f32_16x16x32_bf16 v[8:11], v[176:179], v[202:205], v[8:11]
	v_mfma_f32_16x16x32_bf16 v[4:7], v[168:171], v[210:213], v[4:7]
	v_mfma_f32_16x16x32_bf16 v[0:3], v[176:179], v[210:213], v[0:3]
	s_setprio 0
	s_barrier
	s_add_i32 s60, s60, 2
	s_add_u32 s58, s58, 0x100
	s_addc_u32 s59, s59, 0
	s_add_u32 s30, s30, 0x100
	s_addc_u32 s31, s31, 0
	s_cmp_gt_u32 s60, 13
	s_cbranch_scc0 .LBB0_937
	s_and_b64 vcc, exec, s[12:13]
	s_cbranch_vccz .LBB0_940
	s_barrier

; #define PG8_STAGE(bufoff, gbase, voff) do { _Pragma("unroll") for (int _i = 0; _i < 2; ++_i) \
;         __builtin_amdgcn_global_load_lds((const unsigned*)((const char*)(gbase) + (voff)[_i]), (PG8_LAS unsigned*)(lds + (bufoff) + ldsw + _i * 8192), 16, 0, 0); } while (0)
; #define PG8_LDA(dst, b, h) do { _Pragma("unroll") for (int m = 0; m < 4; ++m) _Pragma("unroll") for (int k = 0; k < 2; ++k) dst[m][k] = *(const PG8_LAS bf16x8*)(lds + PG8_SA(b, h) + aoff + m * 2048 + k * 1024); } while (0)
; #define PG8_LDB(dst, b, h) do { _Pragma("unroll") for (int n = 0; n < 2; ++n) _Pragma("unroll") for (int k = 0; k < 2; ++k) dst[n][k] = *(const PG8_LAS bf16x8*)(lds + PG8_SB(b, h) + boff + n * 2048 + k * 1024); } while (0)
; #define PG8_MMA(ai, bj, At, Bt) do { __builtin_amdgcn_s_setprio(1); _Pragma("unroll") for (int m = 0; m < 4; ++m) _Pragma("unroll") for (int n = 0; n < 2; ++n) _Pragma("unroll") for (int k = 0; k < 2; ++k) \
;         acc[ai][bj][m][n] = __builtin_amdgcn_mfma_f32_16x16x32_bf16(Bt[n][k], At[m][k], acc[ai][bj][m][n], 0, 0, 0); __builtin_amdgcn_s_setprio(0); } while (0)
; #define PG8_WAIT_V(n) asm volatile("s_waitcnt vmcnt(" #n ")" ::: "memory")
; #define PG8_BAR __builtin_amdgcn_s_barrier()
; template <class Epi, class Sched, bool ALIGN_EPI = false, bool SP2 = false>
; __device__ __forceinline__ void gemm_phase(PG8_LAS unsigned char* lds, const Gemm g, const Sched& S, const Epi& E) {
;     ...
;         for (int t = 0; t < nt; t += 2) {
;             const bool last = (t == nt - 2);
;             const char* a1 = cA + (size_t)(t + 1) * kstep;
;             const char* a2 = last ? nA : cA + (size_t)(t + 2) * kstep; const char* b2 = last ? nB : cB + (size_t)(t + 2) * kstep;
;             const char* a3 = a2 + kstep; const char* b3 = b2 + kstep;
;             if (last && has_next) S.a_ready(nxt);
;             if constexpr (SP2) {
;             PG8_LDB(B0, 0, 0); PG8_LDB(B1, 0, 1); PG8_SCHED; PG8_LDA(At, 0, 0); PG8_STAGE(PG8_SA(1, 1), a1 + hstep, voffA);
;             PG8_WAIT_V(8); PG8_WAIT_L(0); PG8_BAR; PG8_MMA(0, 0, At, B0); PG8_MMA(0, 1, At, B1); PG8_BAR; PG8_SCHED;
;             PG8_LDA(At, 0, 1); PG8_STAGE(PG8_SB(0, 0), b2, voffB); PG8_STAGE(PG8_SB(0, 1), b2 + hstep, voffB); PG8_STAGE(PG8_SA(0, 0), a2, voffA);
;             PG8_WAIT_V(8); PG8_WAIT_L(0); PG8_BAR; PG8_MMA(1, 0, At, B0); PG8_MMA(1, 1, At, B1); PG8_BAR; PG8_SCHED;
.LBB0_1017:
	ds_read_b128 v[144:147], v151
	ds_read_b128 v[154:157], v151 offset:1024
	ds_read_b128 v[158:161], v151 offset:2048
	ds_read_b128 v[162:165], v151 offset:3072
	ds_read_b128 v[166:169], v152
	ds_read_b128 v[170:173], v152 offset:1024
	ds_read_b128 v[174:177], v152 offset:2048
	ds_read_b128 v[178:181], v152 offset:3072
	s_add_u32 s24, s22, 0xfffc0080
	s_addc_u32 s25, s23, -1
	s_cmp_eq_u32 s50, 12
	s_cselect_b32 s27, s15, s25
	s_cselect_b32 s26, s46, s24
	s_cselect_b32 s25, s13, s49
	s_cselect_b32 s24, s47, s48
	v_lshl_add_u64 v[182:183], s[22:23], 0, v[138:139]
	s_add_i32 m0, s21, 0xc000
	ds_read_b128 v[186:189], v153
	ds_read_b128 v[190:193], v153 offset:1024
	ds_read_b128 v[194:197], v153 offset:2048
	ds_read_b128 v[198:201], v153 offset:3072
	ds_read_b128 v[202:205], v153 offset:4096
	ds_read_b128 v[206:209], v153 offset:5120
	ds_read_b128 v[210:213], v153 offset:6144
	ds_read_b128 v[214:217], v153 offset:7168
	global_load_lds_dwordx4 v[182:183], off
	s_add_i32 m0, s21, 0xe000
	v_lshl_add_u64 v[182:183], s[22:23], 0, v[136:137]
	global_load_lds_dwordx4 v[182:183], off
	s_waitcnt vmcnt(8)
	s_waitcnt lgkmcnt(0)
	s_barrier
	s_setprio 1
	s_waitcnt lgkmcnt(0)
	v_mfma_f32_16x16x32_bf16 v[124:127], v[144:147], v[186:189], v[124:127]
	v_mfma_f32_16x16x32_bf16 v[116:119], v[158:161], v[186:189], v[116:119]
	v_mfma_f32_16x16x32_bf16 v[108:111], v[144:147], v[194:197], v[108:111]
	v_mfma_f32_16x16x32_bf16 v[100:103], v[158:161], v[194:197], v[100:103]
	v_mfma_f32_16x16x32_bf16 v[92:95], v[144:147], v[202:205], v[92:95]
	v_mfma_f32_16x16x32_bf16 v[84:87], v[158:161], v[202:205], v[84:87]
	v_mfma_f32_16x16x32_bf16 v[76:79], v[144:147], v[210:213], v[76:79]
	v_mfma_f32_16x16x32_bf16 v[68:71], v[158:161], v[210:213], v[68:71]
	v_mfma_f32_16x16x32_bf16 v[124:127], v[154:157], v[190:193], v[124:127]
	v_mfma_f32_16x16x32_bf16 v[116:119], v[162:165], v[190:193], v[116:119]
	v_mfma_f32_16x16x32_bf16 v[108:111], v[154:157], v[198:201], v[108:111]
	v_mfma_f32_16x16x32_bf16 v[100:103], v[162:165], v[198:201], v[100:103]
	v_mfma_f32_16x16x32_bf16 v[92:95], v[154:157], v[206:209], v[92:95]
	v_mfma_f32_16x16x32_bf16 v[84:87], v[162:165], v[206:209], v[84:87]
	v_mfma_f32_16x16x32_bf16 v[76:79], v[154:157], v[214:217], v[76:79]
	v_mfma_f32_16x16x32_bf16 v[68:71], v[162:165], v[214:217], v[68:71]
	s_setprio 0
	s_setprio 1
	v_mfma_f32_16x16x32_bf16 v[120:123], v[166:169], v[186:189], v[120:123]
	v_mfma_f32_16x16x32_bf16 v[112:115], v[174:177], v[186:189], v[112:115]
	v_mfma_f32_16x16x32_bf16 v[104:107], v[166:169], v[194:197], v[104:107]
	v_mfma_f32_16x16x32_bf16 v[96:99], v[174:177], v[194:197], v[96:99]
	v_mfma_f32_16x16x32_bf16 v[88:91], v[166:169], v[202:205], v[88:91]
	v_mfma_f32_16x16x32_bf16 v[80:83], v[174:177], v[202:205], v[80:83]
	v_mfma_f32_16x16x32_bf16 v[72:75], v[166:169], v[210:213], v[72:75]
	v_mfma_f32_16x16x32_bf16 v[64:67], v[174:177], v[210:213], v[64:67]
	v_mfma_f32_16x16x32_bf16 v[120:123], v[170:173], v[190:193], v[120:123]
	v_mfma_f32_16x16x32_bf16 v[112:115], v[178:181], v[190:193], v[112:115]
	v_mfma_f32_16x16x32_bf16 v[104:107], v[170:173], v[198:201], v[104:107]
	v_mfma_f32_16x16x32_bf16 v[96:99], v[178:181], v[198:201], v[96:99]
	v_mfma_f32_16x16x32_bf16 v[88:91], v[170:173], v[206:209], v[88:91]
	v_mfma_f32_16x16x32_bf16 v[80:83], v[178:181], v[206:209], v[80:83]
	v_mfma_f32_16x16x32_bf16 v[72:75], v[170:173], v[214:217], v[72:75]
	v_mfma_f32_16x16x32_bf16 v[64:67], v[178:181], v[214:217], v[64:67]
	s_setprio 0
	s_barrier
	s_add_i32 s51, s43, s34
	v_lshl_add_u64 v[182:183], s[24:25], 0, v[130:131]
	s_mov_b32 m0, s51
	ds_read_b128 v[186:189], v153 offset:16384
	ds_read_b128 v[190:193], v153 offset:17408
	ds_read_b128 v[194:197], v153 offset:18432
	ds_read_b128 v[198:201], v153 offset:19456
	ds_read_b128 v[202:205], v153 offset:20480
	ds_read_b128 v[206:209], v153 offset:21504
	ds_read_b128 v[210:213], v153 offset:22528
	ds_read_b128 v[214:217], v153 offset:23552
	global_load_lds_dwordx4 v[182:183], off
	s_add_i32 m0, s51, 0x2000
	s_add_u32 s52, s24, 0x40000
	v_lshl_add_u64 v[218:219], s[24:25], 0, v[134:135]
	s_addc_u32 s53, s25, 0
	s_add_i32 s51, s93, s34
	global_load_lds_dwordx4 v[218:219], off
	v_lshl_add_u64 v[220:221], s[52:53], 0, v[130:131]
	s_mov_b32 m0, s51
	v_lshl_add_u64 v[222:223], s[26:27], 0, v[132:133]
	global_load_lds_dwordx4 v[220:221], off
	s_add_i32 m0, s51, 0x2000
	v_lshl_add_u64 v[220:221], s[52:53], 0, v[134:135]
	global_load_lds_dwordx4 v[220:221], off
	s_mov_b32 m0, s21
	v_lshl_add_u64 v[220:221], s[26:27], 0, v[128:129]
	global_load_lds_dwordx4 v[220:221], off
	s_mov_b32 m0, s35
	s_nop 0
	global_load_lds_dwordx4 v[222:223], off
	s_waitcnt vmcnt(8)
	s_waitcnt lgkmcnt(0)
	s_barrier
; #define PG8_STAGE(bufoff, gbase, voff) do { _Pragma("unroll") for (int _i = 0; _i < 2; ++_i) \
;         __builtin_amdgcn_global_load_lds((const unsigned*)((const char*)(gbase) + (voff)[_i]), (PG8_LAS unsigned*)(lds + (bufoff) + ldsw + _i * 8192), 16, 0, 0); } while (0)
; #define PG8_LDA(dst, b, h) do { _Pragma("unroll") for (int m = 0; m < 4; ++m) _Pragma("unroll") for (int k = 0; k < 2; ++k) dst[m][k] = *(const PG8_LAS bf16x8*)(lds + PG8_SA(b, h) + aoff + m * 2048 + k * 1024); } while (0)
; #define PG8_LDB(dst, b, h) do { _Pragma("unroll") for (int n = 0; n < 2; ++n) _Pragma("unroll") for (int k = 0; k < 2; ++k) dst[n][k] = *(const PG8_LAS bf16x8*)(lds + PG8_SB(b, h) + boff + n * 2048 + k * 1024); } while (0)
; #define PG8_MMA(ai, bj, At, Bt) do { __builtin_amdgcn_s_setprio(1); _Pragma("unroll") for (int m = 0; m < 4; ++m) _Pragma("unroll") for (int n = 0; n < 2; ++n) _Pragma("unroll") for (int k = 0; k < 2; ++k) \
;         acc[ai][bj][m][n] = __builtin_amdgcn_mfma_f32_16x16x32_bf16(Bt[n][k], At[m][k], acc[ai][bj][m][n], 0, 0, 0); __builtin_amdgcn_s_setprio(0); } while (0)
; #define PG8_WAIT_V(n) asm volatile("s_waitcnt vmcnt(" #n ")" ::: "memory")
; #define PG8_WAIT_L(n) asm volatile("s_waitcnt lgkmcnt(" #n ")" ::: "memory")
; #define PG8_BAR __builtin_amdgcn_s_barrier()
; #define PG8_SCHED __builtin_amdgcn_sched_barrier(0)
; template <class Epi, class Sched, bool ALIGN_EPI = false, bool SP2 = false>
; __device__ __forceinline__ void gemm_phase(PG8_LAS unsigned char* lds, const Gemm g, const Sched& S, const Epi& E) {
;     ...
;             PG8_WAIT_V(8); PG8_WAIT_L(0); PG8_BAR; PG8_MMA(1, 0, At, B0); PG8_MMA(1, 1, At, B1); PG8_BAR; PG8_SCHED;
;             PG8_LDB(B0, 1, 0); PG8_LDB(B1, 1, 1); PG8_SCHED; PG8_LDA(At, 1, 0); PG8_STAGE(PG8_SA(0, 1), a2 + hstep, voffA);
;             PG8_WAIT_V(8); PG8_WAIT_L(0); PG8_BAR; PG8_MMA(0, 0, At, B0); PG8_MMA(0, 1, At, B1); PG8_BAR; PG8_SCHED;
	s_setprio 1
	s_waitcnt lgkmcnt(0)
	v_mfma_f32_16x16x32_bf16 v[60:63], v[144:147], v[186:189], v[60:63]
	v_mfma_f32_16x16x32_bf16 v[52:55], v[158:161], v[186:189], v[52:55]
	v_mfma_f32_16x16x32_bf16 v[44:47], v[144:147], v[194:197], v[44:47]
	v_mfma_f32_16x16x32_bf16 v[36:39], v[158:161], v[194:197], v[36:39]
	v_mfma_f32_16x16x32_bf16 v[28:31], v[144:147], v[202:205], v[28:31]
	v_mfma_f32_16x16x32_bf16 v[20:23], v[158:161], v[202:205], v[20:23]
	v_mfma_f32_16x16x32_bf16 v[12:15], v[144:147], v[210:213], v[12:15]
	v_mfma_f32_16x16x32_bf16 v[4:7], v[158:161], v[210:213], v[4:7]
	v_mfma_f32_16x16x32_bf16 v[60:63], v[154:157], v[190:193], v[60:63]
	v_mfma_f32_16x16x32_bf16 v[52:55], v[162:165], v[190:193], v[52:55]
	v_mfma_f32_16x16x32_bf16 v[44:47], v[154:157], v[198:201], v[44:47]
	v_mfma_f32_16x16x32_bf16 v[36:39], v[162:165], v[198:201], v[36:39]
	v_mfma_f32_16x16x32_bf16 v[28:31], v[154:157], v[206:209], v[28:31]
	v_mfma_f32_16x16x32_bf16 v[20:23], v[162:165], v[206:209], v[20:23]
	v_mfma_f32_16x16x32_bf16 v[12:15], v[154:157], v[214:217], v[12:15]
	v_mfma_f32_16x16x32_bf16 v[4:7], v[162:165], v[214:217], v[4:7]
	s_setprio 0
	s_setprio 1
	v_mfma_f32_16x16x32_bf16 v[56:59], v[166:169], v[186:189], v[56:59]
	v_mfma_f32_16x16x32_bf16 v[48:51], v[174:177], v[186:189], v[48:51]
	v_mfma_f32_16x16x32_bf16 v[40:43], v[166:169], v[194:197], v[40:43]
	v_mfma_f32_16x16x32_bf16 v[32:35], v[174:177], v[194:197], v[32:35]
	v_mfma_f32_16x16x32_bf16 v[24:27], v[166:169], v[202:205], v[24:27]
	v_mfma_f32_16x16x32_bf16 v[16:19], v[174:177], v[202:205], v[16:19]
	v_mfma_f32_16x16x32_bf16 v[8:11], v[166:169], v[210:213], v[8:11]
	v_mfma_f32_16x16x32_bf16 v[0:3], v[174:177], v[210:213], v[0:3]
	v_mfma_f32_16x16x32_bf16 v[56:59], v[170:173], v[190:193], v[56:59]
	v_mfma_f32_16x16x32_bf16 v[48:51], v[178:181], v[190:193], v[48:51]
	v_mfma_f32_16x16x32_bf16 v[40:43], v[170:173], v[198:201], v[40:43]
	v_mfma_f32_16x16x32_bf16 v[32:35], v[178:181], v[198:201], v[32:35]
	v_mfma_f32_16x16x32_bf16 v[24:27], v[170:173], v[206:209], v[24:27]
	v_mfma_f32_16x16x32_bf16 v[16:19], v[178:181], v[206:209], v[16:19]
	v_mfma_f32_16x16x32_bf16 v[8:11], v[170:173], v[214:217], v[8:11]
	v_mfma_f32_16x16x32_bf16 v[0:3], v[178:181], v[214:217], v[0:3]
	s_setprio 0
	s_barrier
	s_add_i32 s51, 0, 0x18000
	s_add_i32 s52, 0, 0x1c000
	v_add_u32_e32 v162, s51, v149
	v_add_u32_e32 v178, s52, v149
	ds_read_b128 v[144:147], v162
	ds_read_b128 v[154:157], v162 offset:1024
	ds_read_b128 v[158:161], v162 offset:2048
	ds_read_b128 v[162:165], v162 offset:3072
	ds_read_b128 v[166:169], v178
	ds_read_b128 v[170:173], v178 offset:1024
	ds_read_b128 v[174:177], v178 offset:2048
	ds_read_b128 v[178:181], v178 offset:3072
	s_add_u32 s26, s26, 0x40000
	s_addc_u32 s27, s27, 0
	s_mov_b32 m0, s36
	v_lshl_add_u64 v[224:225], s[26:27], 0, v[128:129]
	ds_read_b128 v[186:189], v153 offset:32768
	ds_read_b128 v[190:193], v153 offset:33792
	ds_read_b128 v[194:197], v153 offset:34816
	ds_read_b128 v[198:201], v153 offset:35840
	ds_read_b128 v[202:205], v153 offset:36864
	ds_read_b128 v[206:209], v153 offset:37888
	ds_read_b128 v[210:213], v153 offset:38912
	ds_read_b128 v[214:217], v153 offset:39936
	global_load_lds_dwordx4 v[224:225], off
	s_mov_b32 m0, s37
	v_lshl_add_u64 v[224:225], s[26:27], 0, v[132:133]
	global_load_lds_dwordx4 v[224:225], off
	s_waitcnt vmcnt(8)
	s_waitcnt lgkmcnt(0)
	s_barrier
	s_setprio 1
	s_waitcnt lgkmcnt(0)
	v_mfma_f32_16x16x32_bf16 v[124:127], v[144:147], v[186:189], v[124:127]
	v_mfma_f32_16x16x32_bf16 v[116:119], v[158:161], v[186:189], v[116:119]
	v_mfma_f32_16x16x32_bf16 v[108:111], v[144:147], v[194:197], v[108:111]
	v_mfma_f32_16x16x32_bf16 v[100:103], v[158:161], v[194:197], v[100:103]
	v_mfma_f32_16x16x32_bf16 v[92:95], v[144:147], v[202:205], v[92:95]
	v_mfma_f32_16x16x32_bf16 v[84:87], v[158:161], v[202:205], v[84:87]
	v_mfma_f32_16x16x32_bf16 v[76:79], v[144:147], v[210:213], v[76:79]
	v_mfma_f32_16x16x32_bf16 v[68:71], v[158:161], v[210:213], v[68:71]
	v_mfma_f32_16x16x32_bf16 v[124:127], v[154:157], v[190:193], v[124:127]
	v_mfma_f32_16x16x32_bf16 v[116:119], v[162:165], v[190:193], v[116:119]
	v_mfma_f32_16x16x32_bf16 v[108:111], v[154:157], v[198:201], v[108:111]
	v_mfma_f32_16x16x32_bf16 v[100:103], v[162:165], v[198:201], v[100:103]
	v_mfma_f32_16x16x32_bf16 v[92:95], v[154:157], v[206:209], v[92:95]
	v_mfma_f32_16x16x32_bf16 v[84:87], v[162:165], v[206:209], v[84:87]
	v_mfma_f32_16x16x32_bf16 v[76:79], v[154:157], v[214:217], v[76:79]
	v_mfma_f32_16x16x32_bf16 v[68:71], v[162:165], v[214:217], v[68:71]
	s_setprio 0
	s_setprio 1
	v_mfma_f32_16x16x32_bf16 v[120:123], v[166:169], v[186:189], v[120:123]
	v_mfma_f32_16x16x32_bf16 v[112:115], v[174:177], v[186:189], v[112:115]
	v_mfma_f32_16x16x32_bf16 v[104:107], v[166:169], v[194:197], v[104:107]
	v_mfma_f32_16x16x32_bf16 v[96:99], v[174:177], v[194:197], v[96:99]
	v_mfma_f32_16x16x32_bf16 v[88:91], v[166:169], v[202:205], v[88:91]
	v_mfma_f32_16x16x32_bf16 v[80:83], v[174:177], v[202:205], v[80:83]
	v_mfma_f32_16x16x32_bf16 v[72:75], v[166:169], v[210:213], v[72:75]
	v_mfma_f32_16x16x32_bf16 v[64:67], v[174:177], v[210:213], v[64:67]
	v_mfma_f32_16x16x32_bf16 v[120:123], v[170:173], v[190:193], v[120:123]
	v_mfma_f32_16x16x32_bf16 v[112:115], v[178:181], v[190:193], v[112:115]
	v_mfma_f32_16x16x32_bf16 v[104:107], v[170:173], v[198:201], v[104:107]
	v_mfma_f32_16x16x32_bf16 v[96:99], v[178:181], v[198:201], v[96:99]
	v_mfma_f32_16x16x32_bf16 v[88:91], v[170:173], v[206:209], v[88:91]
	v_mfma_f32_16x16x32_bf16 v[80:83], v[178:181], v[206:209], v[80:83]
	v_mfma_f32_16x16x32_bf16 v[72:75], v[170:173], v[214:217], v[72:75]
	v_mfma_f32_16x16x32_bf16 v[64:67], v[178:181], v[214:217], v[64:67]
	s_setprio 0
	s_barrier
; #define PG8_STAGE(bufoff, gbase, voff) do { _Pragma("unroll") for (int _i = 0; _i < 2; ++_i) \
;         __builtin_amdgcn_global_load_lds((const unsigned*)((const char*)(gbase) + (voff)[_i]), (PG8_LAS unsigned*)(lds + (bufoff) + ldsw + _i * 8192), 16, 0, 0); } while (0)
; #define PG8_LDA(dst, b, h) do { _Pragma("unroll") for (int m = 0; m < 4; ++m) _Pragma("unroll") for (int k = 0; k < 2; ++k) dst[m][k] = *(const PG8_LAS bf16x8*)(lds + PG8_SA(b, h) + aoff + m * 2048 + k * 1024); } while (0)
; #define PG8_MMA(ai, bj, At, Bt) do { __builtin_amdgcn_s_setprio(1); _Pragma("unroll") for (int m = 0; m < 4; ++m) _Pragma("unroll") for (int n = 0; n < 2; ++n) _Pragma("unroll") for (int k = 0; k < 2; ++k) \
;         acc[ai][bj][m][n] = __builtin_amdgcn_mfma_f32_16x16x32_bf16(Bt[n][k], At[m][k], acc[ai][bj][m][n], 0, 0, 0); __builtin_amdgcn_s_setprio(0); } while (0)
; #define PG8_WAIT_V(n) asm volatile("s_waitcnt vmcnt(" #n ")" ::: "memory")
; #define PG8_WAIT_L(n) asm volatile("s_waitcnt lgkmcnt(" #n ")" ::: "memory")
; #define PG8_BAR __builtin_amdgcn_s_barrier()
; #define PG8_SCHED __builtin_amdgcn_sched_barrier(0)
; template <class Epi, class Sched, bool ALIGN_EPI = false, bool SP2 = false>
; __device__ __forceinline__ void gemm_phase(PG8_LAS unsigned char* lds, const Gemm g, const Sched& S, const Epi& E) {
;     ...
;             PG8_LDA(At, 1, 1); PG8_STAGE(PG8_SB(1, 0), b3, voffB); PG8_STAGE(PG8_SB(1, 1), b3 + hstep, voffB); PG8_STAGE(PG8_SA(1, 0), a3, voffA);
;             PG8_WAIT_V(8); PG8_WAIT_L(0); PG8_BAR; PG8_MMA(1, 0, At, B0); PG8_MMA(1, 1, At, B1); PG8_BAR; PG8_SCHED;
;     ...
;         if constexpr (ALIGN_EPI) { if (wr == 0) PG8_BAR; }
	s_add_i32 s26, s51, s34
	v_lshl_add_u64 v[182:183], v[182:183], 0, s[8:9]
	s_mov_b32 m0, s26
	ds_read_b128 v[186:189], v153 offset:49152
	ds_read_b128 v[190:193], v153 offset:50176
	ds_read_b128 v[194:197], v153 offset:51200
	ds_read_b128 v[198:201], v153 offset:52224
	ds_read_b128 v[202:205], v153 offset:53248
	ds_read_b128 v[206:209], v153 offset:54272
	ds_read_b128 v[210:213], v153 offset:55296
	ds_read_b128 v[214:217], v153 offset:56320
	global_load_lds_dwordx4 v[182:183], off
	s_add_i32 m0, s26, 0x2000
	s_add_u32 s24, s24, 0x40080
	v_lshl_add_u64 v[182:183], v[218:219], 0, s[8:9]
	s_addc_u32 s25, s25, 0
	s_add_i32 s26, s52, s34
	global_load_lds_dwordx4 v[182:183], off
	s_mov_b32 m0, s26
	v_lshl_add_u64 v[182:183], s[24:25], 0, v[130:131]
	global_load_lds_dwordx4 v[182:183], off
	s_add_i32 m0, s26, 0x2000
	v_lshl_add_u64 v[182:183], s[24:25], 0, v[134:135]
	global_load_lds_dwordx4 v[182:183], off
	s_mov_b32 m0, s39
	v_lshl_add_u64 v[182:183], v[220:221], 0, s[8:9]
	global_load_lds_dwordx4 v[182:183], off
	s_mov_b32 m0, s40
	v_lshl_add_u64 v[182:183], v[222:223], 0, s[8:9]
	global_load_lds_dwordx4 v[182:183], off
	s_waitcnt vmcnt(8)
	s_waitcnt lgkmcnt(0)
	s_barrier
	s_setprio 1
	s_waitcnt lgkmcnt(0)
	v_mfma_f32_16x16x32_bf16 v[60:63], v[144:147], v[186:189], v[60:63]
	v_mfma_f32_16x16x32_bf16 v[52:55], v[158:161], v[186:189], v[52:55]
	v_mfma_f32_16x16x32_bf16 v[44:47], v[144:147], v[194:197], v[44:47]
	v_mfma_f32_16x16x32_bf16 v[36:39], v[158:161], v[194:197], v[36:39]
	v_mfma_f32_16x16x32_bf16 v[28:31], v[144:147], v[202:205], v[28:31]
	v_mfma_f32_16x16x32_bf16 v[20:23], v[158:161], v[202:205], v[20:23]
	v_mfma_f32_16x16x32_bf16 v[12:15], v[144:147], v[210:213], v[12:15]
	v_mfma_f32_16x16x32_bf16 v[4:7], v[158:161], v[210:213], v[4:7]
	v_mfma_f32_16x16x32_bf16 v[60:63], v[154:157], v[190:193], v[60:63]
	v_mfma_f32_16x16x32_bf16 v[52:55], v[162:165], v[190:193], v[52:55]
	v_mfma_f32_16x16x32_bf16 v[44:47], v[154:157], v[198:201], v[44:47]
	v_mfma_f32_16x16x32_bf16 v[36:39], v[162:165], v[198:201], v[36:39]
	v_mfma_f32_16x16x32_bf16 v[28:31], v[154:157], v[206:209], v[28:31]
	v_mfma_f32_16x16x32_bf16 v[20:23], v[162:165], v[206:209], v[20:23]
	v_mfma_f32_16x16x32_bf16 v[12:15], v[154:157], v[214:217], v[12:15]
	v_mfma_f32_16x16x32_bf16 v[4:7], v[162:165], v[214:217], v[4:7]
	s_setprio 0
	s_setprio 1
	v_mfma_f32_16x16x32_bf16 v[56:59], v[166:169], v[186:189], v[56:59]
	v_mfma_f32_16x16x32_bf16 v[48:51], v[174:177], v[186:189], v[48:51]
	v_mfma_f32_16x16x32_bf16 v[40:43], v[166:169], v[194:197], v[40:43]
	v_mfma_f32_16x16x32_bf16 v[32:35], v[174:177], v[194:197], v[32:35]
	v_mfma_f32_16x16x32_bf16 v[24:27], v[166:169], v[202:205], v[24:27]
	v_mfma_f32_16x16x32_bf16 v[16:19], v[174:177], v[202:205], v[16:19]
	v_mfma_f32_16x16x32_bf16 v[8:11], v[166:169], v[210:213], v[8:11]
	v_mfma_f32_16x16x32_bf16 v[0:3], v[174:177], v[210:213], v[0:3]
	v_mfma_f32_16x16x32_bf16 v[56:59], v[170:173], v[190:193], v[56:59]
	v_mfma_f32_16x16x32_bf16 v[48:51], v[178:181], v[190:193], v[48:51]
	v_mfma_f32_16x16x32_bf16 v[40:43], v[170:173], v[198:201], v[40:43]
	v_mfma_f32_16x16x32_bf16 v[32:35], v[178:181], v[198:201], v[32:35]
	v_mfma_f32_16x16x32_bf16 v[24:27], v[170:173], v[206:209], v[24:27]
	v_mfma_f32_16x16x32_bf16 v[16:19], v[178:181], v[206:209], v[16:19]
	v_mfma_f32_16x16x32_bf16 v[8:11], v[170:173], v[214:217], v[8:11]
	v_mfma_f32_16x16x32_bf16 v[0:3], v[178:181], v[214:217], v[0:3]
	s_setprio 0
	s_barrier
	s_add_i32 s50, s50, 2
	s_add_u32 s48, s48, 0x100
	s_addc_u32 s49, s49, 0
	s_add_u32 s22, s22, 0x100
	s_addc_u32 s23, s23, 0
	s_cmp_gt_u32 s50, 13
	s_cbranch_scc0 .LBB0_1017
	s_and_b64 vcc, exec, s[10:11]
	s_cbranch_vccz .LBB0_1020
	s_barrier

; #define PG8_STAGE(bufoff, gbase, voff) do { _Pragma("unroll") for (int _i = 0; _i < 2; ++_i) \
;         __builtin_amdgcn_global_load_lds((const unsigned*)((const char*)(gbase) + (voff)[_i]), (PG8_LAS unsigned*)(lds + (bufoff) + ldsw + _i * 8192), 16, 0, 0); } while (0)
; #define PG8_LDA(dst, b, h) do { _Pragma("unroll") for (int m = 0; m < 4; ++m) _Pragma("unroll") for (int k = 0; k < 2; ++k) dst[m][k] = *(const PG8_LAS bf16x8*)(lds + PG8_SA(b, h) + aoff + m * 2048 + k * 1024); } while (0)
; #define PG8_LDB(dst, b, h) do { _Pragma("unroll") for (int n = 0; n < 2; ++n) _Pragma("unroll") for (int k = 0; k < 2; ++k) dst[n][k] = *(const PG8_LAS bf16x8*)(lds + PG8_SB(b, h) + boff + n * 2048 + k * 1024); } while (0)
; #define PG8_MMA(ai, bj, At, Bt) do { __builtin_amdgcn_s_setprio(1); _Pragma("unroll") for (int m = 0; m < 4; ++m) _Pragma("unroll") for (int n = 0; n < 2; ++n) _Pragma("unroll") for (int k = 0; k < 2; ++k) \
;         acc[ai][bj][m][n] = __builtin_amdgcn_mfma_f32_16x16x32_bf16(Bt[n][k], At[m][k], acc[ai][bj][m][n], 0, 0, 0); __builtin_amdgcn_s_setprio(0); } while (0)
; #define PG8_WAIT_V(n) asm volatile("s_waitcnt vmcnt(" #n ")" ::: "memory")
; #define PG8_BAR __builtin_amdgcn_s_barrier()
; template <class Epi, class Sched, bool ALIGN_EPI = false, bool SP2 = false>
; __device__ __forceinline__ void gemm_phase(PG8_LAS unsigned char* lds, const Gemm g, const Sched& S, const Epi& E) {
;     ...
;         for (int t = 0; t < nt; t += 2) {
;             const bool last = (t == nt - 2);
;             const char* a1 = cA + (size_t)(t + 1) * kstep;
;             const char* a2 = last ? nA : cA + (size_t)(t + 2) * kstep; const char* b2 = last ? nB : cB + (size_t)(t + 2) * kstep;
;             const char* a3 = a2 + kstep; const char* b3 = b2 + kstep;
;             if (last && has_next) S.a_ready(nxt);
;             if constexpr (SP2) {
;             PG8_LDB(B0, 0, 0); PG8_LDB(B1, 0, 1); PG8_SCHED; PG8_LDA(At, 0, 0); PG8_STAGE(PG8_SA(1, 1), a1 + hstep, voffA);
;             PG8_WAIT_V(8); PG8_WAIT_L(0); PG8_BAR; PG8_MMA(0, 0, At, B0); PG8_MMA(0, 1, At, B1); PG8_BAR; PG8_SCHED;
;             PG8_LDA(At, 0, 1); PG8_STAGE(PG8_SB(0, 0), b2, voffB); PG8_STAGE(PG8_SB(0, 1), b2 + hstep, voffB); PG8_STAGE(PG8_SA(0, 0), a2, voffA);
;             PG8_WAIT_V(8); PG8_WAIT_L(0); PG8_BAR; PG8_MMA(1, 0, At, B0); PG8_MMA(1, 1, At, B1); PG8_BAR; PG8_SCHED;
.LBB0_1089:
	ds_read_b128 v[152:155], v149
	ds_read_b128 v[156:159], v149 offset:1024
	ds_read_b128 v[160:163], v149 offset:2048
	ds_read_b128 v[164:167], v149 offset:3072
	ds_read_b128 v[168:171], v150
	ds_read_b128 v[172:175], v150 offset:1024
	ds_read_b128 v[176:179], v150 offset:2048
	ds_read_b128 v[180:183], v150 offset:3072
	s_add_u32 s24, s22, 0x100
	s_addc_u32 s25, s23, 0
	s_cmp_eq_u32 s57, 40
	s_cselect_b32 s29, s5, s25
	s_cselect_b32 s28, s4, s24
	s_cselect_b32 s27, s21, s56
	s_cselect_b32 s26, s20, s55
	v_lshl_add_u64 v[144:145], s[22:23], 0, v[138:139]
	s_add_i32 m0, s37, 0xc000
	ds_read_b128 v[186:189], v151
	ds_read_b128 v[190:193], v151 offset:1024
	ds_read_b128 v[194:197], v151 offset:2048
	ds_read_b128 v[198:201], v151 offset:3072
	ds_read_b128 v[202:205], v151 offset:4096
	ds_read_b128 v[206:209], v151 offset:5120
	ds_read_b128 v[210:213], v151 offset:6144
	ds_read_b128 v[214:217], v151 offset:7168
	global_load_lds_dwordx4 v[144:145], off
	s_add_i32 m0, s37, 0xe000
	v_lshl_add_u64 v[144:145], s[22:23], 0, v[136:137]
	global_load_lds_dwordx4 v[144:145], off
	s_waitcnt vmcnt(8)
	s_waitcnt lgkmcnt(0)
	s_barrier
	s_setprio 1
	s_waitcnt lgkmcnt(0)
	v_mfma_f32_16x16x32_bf16 v[124:127], v[152:155], v[186:189], v[124:127]
	v_mfma_f32_16x16x32_bf16 v[120:123], v[160:163], v[186:189], v[120:123]
	v_mfma_f32_16x16x32_bf16 v[116:119], v[152:155], v[194:197], v[116:119]
	v_mfma_f32_16x16x32_bf16 v[108:111], v[160:163], v[194:197], v[108:111]
	v_mfma_f32_16x16x32_bf16 v[100:103], v[152:155], v[202:205], v[100:103]
	v_mfma_f32_16x16x32_bf16 v[92:95], v[160:163], v[202:205], v[92:95]
	v_mfma_f32_16x16x32_bf16 v[84:87], v[152:155], v[210:213], v[84:87]
	v_mfma_f32_16x16x32_bf16 v[76:79], v[160:163], v[210:213], v[76:79]
	v_mfma_f32_16x16x32_bf16 v[124:127], v[156:159], v[190:193], v[124:127]
	v_mfma_f32_16x16x32_bf16 v[120:123], v[164:167], v[190:193], v[120:123]
	v_mfma_f32_16x16x32_bf16 v[116:119], v[156:159], v[198:201], v[116:119]
	v_mfma_f32_16x16x32_bf16 v[108:111], v[164:167], v[198:201], v[108:111]
	v_mfma_f32_16x16x32_bf16 v[100:103], v[156:159], v[206:209], v[100:103]
	v_mfma_f32_16x16x32_bf16 v[92:95], v[164:167], v[206:209], v[92:95]
	v_mfma_f32_16x16x32_bf16 v[84:87], v[156:159], v[214:217], v[84:87]
	v_mfma_f32_16x16x32_bf16 v[76:79], v[164:167], v[214:217], v[76:79]
	s_setprio 0
	s_setprio 1
	v_mfma_f32_16x16x32_bf16 v[112:115], v[168:171], v[186:189], v[112:115]
	v_mfma_f32_16x16x32_bf16 v[104:107], v[176:179], v[186:189], v[104:107]
	v_mfma_f32_16x16x32_bf16 v[96:99], v[168:171], v[194:197], v[96:99]
	v_mfma_f32_16x16x32_bf16 v[88:91], v[176:179], v[194:197], v[88:91]
	v_mfma_f32_16x16x32_bf16 v[80:83], v[168:171], v[202:205], v[80:83]
	v_mfma_f32_16x16x32_bf16 v[72:75], v[176:179], v[202:205], v[72:75]
	v_mfma_f32_16x16x32_bf16 v[68:71], v[168:171], v[210:213], v[68:71]
	v_mfma_f32_16x16x32_bf16 v[64:67], v[176:179], v[210:213], v[64:67]
	v_mfma_f32_16x16x32_bf16 v[112:115], v[172:175], v[190:193], v[112:115]
	v_mfma_f32_16x16x32_bf16 v[104:107], v[180:183], v[190:193], v[104:107]
	v_mfma_f32_16x16x32_bf16 v[96:99], v[172:175], v[198:201], v[96:99]
	v_mfma_f32_16x16x32_bf16 v[88:91], v[180:183], v[198:201], v[88:91]
	v_mfma_f32_16x16x32_bf16 v[80:83], v[172:175], v[206:209], v[80:83]
	v_mfma_f32_16x16x32_bf16 v[72:75], v[180:183], v[206:209], v[72:75]
	v_mfma_f32_16x16x32_bf16 v[68:71], v[172:175], v[214:217], v[68:71]
	v_mfma_f32_16x16x32_bf16 v[64:67], v[180:183], v[214:217], v[64:67]
	s_setprio 0
	s_barrier
	s_add_i32 s22, s46, s36
	v_lshl_add_u64 v[144:145], s[26:27], 0, v[130:131]
	s_mov_b32 m0, s22
	ds_read_b128 v[186:189], v151 offset:16384
	ds_read_b128 v[190:193], v151 offset:17408
	ds_read_b128 v[194:197], v151 offset:18432
	ds_read_b128 v[198:201], v151 offset:19456
	ds_read_b128 v[202:205], v151 offset:20480
	ds_read_b128 v[206:209], v151 offset:21504
	ds_read_b128 v[210:213], v151 offset:22528
	ds_read_b128 v[214:217], v151 offset:23552
	global_load_lds_dwordx4 v[144:145], off
	s_add_i32 m0, s22, 0x2000
	s_add_u32 s22, s26, 0xb0000
	v_lshl_add_u64 v[218:219], s[26:27], 0, v[134:135]
	s_addc_u32 s23, s27, 0
	s_add_i32 s58, s93, s36
	global_load_lds_dwordx4 v[218:219], off
	v_lshl_add_u64 v[220:221], s[22:23], 0, v[130:131]
	s_mov_b32 m0, s58
	v_lshl_add_u64 v[222:223], s[28:29], 0, v[132:133]
	global_load_lds_dwordx4 v[220:221], off
	s_add_i32 m0, s58, 0x2000
	v_lshl_add_u64 v[220:221], s[22:23], 0, v[134:135]
	global_load_lds_dwordx4 v[220:221], off
	s_mov_b32 m0, s37
	v_lshl_add_u64 v[220:221], s[28:29], 0, v[128:129]
	global_load_lds_dwordx4 v[220:221], off
	s_mov_b32 m0, s38
	s_nop 0
	global_load_lds_dwordx4 v[222:223], off
	s_waitcnt vmcnt(8)
	s_waitcnt lgkmcnt(0)
	s_barrier
; #define PG8_STAGE(bufoff, gbase, voff) do { _Pragma("unroll") for (int _i = 0; _i < 2; ++_i) \
;         __builtin_amdgcn_global_load_lds((const unsigned*)((const char*)(gbase) + (voff)[_i]), (PG8_LAS unsigned*)(lds + (bufoff) + ldsw + _i * 8192), 16, 0, 0); } while (0)
; #define PG8_LDA(dst, b, h) do { _Pragma("unroll") for (int m = 0; m < 4; ++m) _Pragma("unroll") for (int k = 0; k < 2; ++k) dst[m][k] = *(const PG8_LAS bf16x8*)(lds + PG8_SA(b, h) + aoff + m * 2048 + k * 1024); } while (0)
; #define PG8_LDB(dst, b, h) do { _Pragma("unroll") for (int n = 0; n < 2; ++n) _Pragma("unroll") for (int k = 0; k < 2; ++k) dst[n][k] = *(const PG8_LAS bf16x8*)(lds + PG8_SB(b, h) + boff + n * 2048 + k * 1024); } while (0)
; #define PG8_MMA(ai, bj, At, Bt) do { __builtin_amdgcn_s_setprio(1); _Pragma("unroll") for (int m = 0; m < 4; ++m) _Pragma("unroll") for (int n = 0; n < 2; ++n) _Pragma("unroll") for (int k = 0; k < 2; ++k) \
;         acc[ai][bj][m][n] = __builtin_amdgcn_mfma_f32_16x16x32_bf16(Bt[n][k], At[m][k], acc[ai][bj][m][n], 0, 0, 0); __builtin_amdgcn_s_setprio(0); } while (0)
; #define PG8_WAIT_V(n) asm volatile("s_waitcnt vmcnt(" #n ")" ::: "memory")
; #define PG8_WAIT_L(n) asm volatile("s_waitcnt lgkmcnt(" #n ")" ::: "memory")
; #define PG8_BAR __builtin_amdgcn_s_barrier()
; #define PG8_SCHED __builtin_amdgcn_sched_barrier(0)
; template <class Epi, class Sched, bool ALIGN_EPI = false, bool SP2 = false>
; __device__ __forceinline__ void gemm_phase(PG8_LAS unsigned char* lds, const Gemm g, const Sched& S, const Epi& E) {
;     ...
;             PG8_WAIT_V(8); PG8_WAIT_L(0); PG8_BAR; PG8_MMA(1, 0, At, B0); PG8_MMA(1, 1, At, B1); PG8_BAR; PG8_SCHED;
;             PG8_LDB(B0, 1, 0); PG8_LDB(B1, 1, 1); PG8_SCHED; PG8_LDA(At, 1, 0); PG8_STAGE(PG8_SA(0, 1), a2 + hstep, voffA);
;             PG8_WAIT_V(8); PG8_WAIT_L(0); PG8_BAR; PG8_MMA(0, 0, At, B0); PG8_MMA(0, 1, At, B1); PG8_BAR; PG8_SCHED;
	s_setprio 1
	s_waitcnt lgkmcnt(0)
	v_mfma_f32_16x16x32_bf16 v[60:63], v[152:155], v[186:189], v[60:63]
	v_mfma_f32_16x16x32_bf16 v[56:59], v[160:163], v[186:189], v[56:59]
	v_mfma_f32_16x16x32_bf16 v[52:55], v[152:155], v[194:197], v[52:55]
	v_mfma_f32_16x16x32_bf16 v[44:47], v[160:163], v[194:197], v[44:47]
	v_mfma_f32_16x16x32_bf16 v[36:39], v[152:155], v[202:205], v[36:39]
	v_mfma_f32_16x16x32_bf16 v[28:31], v[160:163], v[202:205], v[28:31]
	v_mfma_f32_16x16x32_bf16 v[20:23], v[152:155], v[210:213], v[20:23]
	v_mfma_f32_16x16x32_bf16 v[12:15], v[160:163], v[210:213], v[12:15]
	v_mfma_f32_16x16x32_bf16 v[60:63], v[156:159], v[190:193], v[60:63]
	v_mfma_f32_16x16x32_bf16 v[56:59], v[164:167], v[190:193], v[56:59]
	v_mfma_f32_16x16x32_bf16 v[52:55], v[156:159], v[198:201], v[52:55]
	v_mfma_f32_16x16x32_bf16 v[44:47], v[164:167], v[198:201], v[44:47]
	v_mfma_f32_16x16x32_bf16 v[36:39], v[156:159], v[206:209], v[36:39]
	v_mfma_f32_16x16x32_bf16 v[28:31], v[164:167], v[206:209], v[28:31]
	v_mfma_f32_16x16x32_bf16 v[20:23], v[156:159], v[214:217], v[20:23]
	v_mfma_f32_16x16x32_bf16 v[12:15], v[164:167], v[214:217], v[12:15]
	s_setprio 0
	s_setprio 1
	v_mfma_f32_16x16x32_bf16 v[48:51], v[168:171], v[186:189], v[48:51]
	v_mfma_f32_16x16x32_bf16 v[40:43], v[176:179], v[186:189], v[40:43]
	v_mfma_f32_16x16x32_bf16 v[32:35], v[168:171], v[194:197], v[32:35]
	v_mfma_f32_16x16x32_bf16 v[24:27], v[176:179], v[194:197], v[24:27]
	v_mfma_f32_16x16x32_bf16 v[16:19], v[168:171], v[202:205], v[16:19]
	v_mfma_f32_16x16x32_bf16 v[8:11], v[176:179], v[202:205], v[8:11]
	v_mfma_f32_16x16x32_bf16 v[4:7], v[168:171], v[210:213], v[4:7]
	v_mfma_f32_16x16x32_bf16 v[0:3], v[176:179], v[210:213], v[0:3]
	v_mfma_f32_16x16x32_bf16 v[48:51], v[172:175], v[190:193], v[48:51]
	v_mfma_f32_16x16x32_bf16 v[40:43], v[180:183], v[190:193], v[40:43]
	v_mfma_f32_16x16x32_bf16 v[32:35], v[172:175], v[198:201], v[32:35]
	v_mfma_f32_16x16x32_bf16 v[24:27], v[180:183], v[198:201], v[24:27]
	v_mfma_f32_16x16x32_bf16 v[16:19], v[172:175], v[206:209], v[16:19]
	v_mfma_f32_16x16x32_bf16 v[8:11], v[180:183], v[206:209], v[8:11]
	v_mfma_f32_16x16x32_bf16 v[4:7], v[172:175], v[214:217], v[4:7]
	v_mfma_f32_16x16x32_bf16 v[0:3], v[180:183], v[214:217], v[0:3]
	s_setprio 0
	s_barrier
	s_add_i32 s58, 0, 0x18000
	s_add_i32 s59, 0, 0x1c000
	v_add_u32_e32 v164, s58, v147
	v_add_u32_e32 v180, s59, v147
	ds_read_b128 v[152:155], v164
	ds_read_b128 v[156:159], v164 offset:1024
	ds_read_b128 v[160:163], v164 offset:2048
	ds_read_b128 v[164:167], v164 offset:3072
	ds_read_b128 v[168:171], v180
	ds_read_b128 v[172:175], v180 offset:1024
	ds_read_b128 v[176:179], v180 offset:2048
	ds_read_b128 v[180:183], v180 offset:3072
	s_add_u32 s22, s28, 0xb0000
	s_addc_u32 s23, s29, 0
	s_mov_b32 m0, s39
	v_lshl_add_u64 v[224:225], s[22:23], 0, v[128:129]
	ds_read_b128 v[186:189], v151 offset:32768
	ds_read_b128 v[190:193], v151 offset:33792
	ds_read_b128 v[194:197], v151 offset:34816
	ds_read_b128 v[198:201], v151 offset:35840
	ds_read_b128 v[202:205], v151 offset:36864
	ds_read_b128 v[206:209], v151 offset:37888
	ds_read_b128 v[210:213], v151 offset:38912
	ds_read_b128 v[214:217], v151 offset:39936
	global_load_lds_dwordx4 v[224:225], off
	s_mov_b32 m0, s40
	v_lshl_add_u64 v[224:225], s[22:23], 0, v[132:133]
	global_load_lds_dwordx4 v[224:225], off
	s_waitcnt vmcnt(8)
	s_waitcnt lgkmcnt(0)
	s_barrier
	s_setprio 1
	s_waitcnt lgkmcnt(0)
	v_mfma_f32_16x16x32_bf16 v[124:127], v[152:155], v[186:189], v[124:127]
	v_mfma_f32_16x16x32_bf16 v[120:123], v[160:163], v[186:189], v[120:123]
	v_mfma_f32_16x16x32_bf16 v[116:119], v[152:155], v[194:197], v[116:119]
	v_mfma_f32_16x16x32_bf16 v[108:111], v[160:163], v[194:197], v[108:111]
	v_mfma_f32_16x16x32_bf16 v[100:103], v[152:155], v[202:205], v[100:103]
	v_mfma_f32_16x16x32_bf16 v[92:95], v[160:163], v[202:205], v[92:95]
	v_mfma_f32_16x16x32_bf16 v[84:87], v[152:155], v[210:213], v[84:87]
	v_mfma_f32_16x16x32_bf16 v[76:79], v[160:163], v[210:213], v[76:79]
	v_mfma_f32_16x16x32_bf16 v[124:127], v[156:159], v[190:193], v[124:127]
	v_mfma_f32_16x16x32_bf16 v[120:123], v[164:167], v[190:193], v[120:123]
	v_mfma_f32_16x16x32_bf16 v[116:119], v[156:159], v[198:201], v[116:119]
	v_mfma_f32_16x16x32_bf16 v[108:111], v[164:167], v[198:201], v[108:111]
	v_mfma_f32_16x16x32_bf16 v[100:103], v[156:159], v[206:209], v[100:103]
	v_mfma_f32_16x16x32_bf16 v[92:95], v[164:167], v[206:209], v[92:95]
	v_mfma_f32_16x16x32_bf16 v[84:87], v[156:159], v[214:217], v[84:87]
	v_mfma_f32_16x16x32_bf16 v[76:79], v[164:167], v[214:217], v[76:79]
	s_setprio 0
	s_setprio 1
	v_mfma_f32_16x16x32_bf16 v[112:115], v[168:171], v[186:189], v[112:115]
	v_mfma_f32_16x16x32_bf16 v[104:107], v[176:179], v[186:189], v[104:107]
	v_mfma_f32_16x16x32_bf16 v[96:99], v[168:171], v[194:197], v[96:99]
	v_mfma_f32_16x16x32_bf16 v[88:91], v[176:179], v[194:197], v[88:91]
	v_mfma_f32_16x16x32_bf16 v[80:83], v[168:171], v[202:205], v[80:83]
	v_mfma_f32_16x16x32_bf16 v[72:75], v[176:179], v[202:205], v[72:75]
	v_mfma_f32_16x16x32_bf16 v[68:71], v[168:171], v[210:213], v[68:71]
	v_mfma_f32_16x16x32_bf16 v[64:67], v[176:179], v[210:213], v[64:67]
	v_mfma_f32_16x16x32_bf16 v[112:115], v[172:175], v[190:193], v[112:115]
	v_mfma_f32_16x16x32_bf16 v[104:107], v[180:183], v[190:193], v[104:107]
	v_mfma_f32_16x16x32_bf16 v[96:99], v[172:175], v[198:201], v[96:99]
	v_mfma_f32_16x16x32_bf16 v[88:91], v[180:183], v[198:201], v[88:91]
	v_mfma_f32_16x16x32_bf16 v[80:83], v[172:175], v[206:209], v[80:83]
	v_mfma_f32_16x16x32_bf16 v[72:75], v[180:183], v[206:209], v[72:75]
	v_mfma_f32_16x16x32_bf16 v[68:71], v[172:175], v[214:217], v[68:71]
	v_mfma_f32_16x16x32_bf16 v[64:67], v[180:183], v[214:217], v[64:67]
	s_setprio 0
	s_barrier
; #define PG8_STAGE(bufoff, gbase, voff) do { _Pragma("unroll") for (int _i = 0; _i < 2; ++_i) \
;         __builtin_amdgcn_global_load_lds((const unsigned*)((const char*)(gbase) + (voff)[_i]), (PG8_LAS unsigned*)(lds + (bufoff) + ldsw + _i * 8192), 16, 0, 0); } while (0)
; #define PG8_LDA(dst, b, h) do { _Pragma("unroll") for (int m = 0; m < 4; ++m) _Pragma("unroll") for (int k = 0; k < 2; ++k) dst[m][k] = *(const PG8_LAS bf16x8*)(lds + PG8_SA(b, h) + aoff + m * 2048 + k * 1024); } while (0)
; #define PG8_MMA(ai, bj, At, Bt) do { __builtin_amdgcn_s_setprio(1); _Pragma("unroll") for (int m = 0; m < 4; ++m) _Pragma("unroll") for (int n = 0; n < 2; ++n) _Pragma("unroll") for (int k = 0; k < 2; ++k) \
;         acc[ai][bj][m][n] = __builtin_amdgcn_mfma_f32_16x16x32_bf16(Bt[n][k], At[m][k], acc[ai][bj][m][n], 0, 0, 0); __builtin_amdgcn_s_setprio(0); } while (0)
; #define PG8_WAIT_V(n) asm volatile("s_waitcnt vmcnt(" #n ")" ::: "memory")
; #define PG8_WAIT_L(n) asm volatile("s_waitcnt lgkmcnt(" #n ")" ::: "memory")
; #define PG8_BAR __builtin_amdgcn_s_barrier()
; #define PG8_SCHED __builtin_amdgcn_sched_barrier(0)
; template <class Epi, class Sched, bool ALIGN_EPI = false, bool SP2 = false>
; __device__ __forceinline__ void gemm_phase(PG8_LAS unsigned char* lds, const Gemm g, const Sched& S, const Epi& E) {
;     ...
;             PG8_LDA(At, 1, 1); PG8_STAGE(PG8_SB(1, 0), b3, voffB); PG8_STAGE(PG8_SB(1, 1), b3 + hstep, voffB); PG8_STAGE(PG8_SA(1, 0), a3, voffA);
;             PG8_WAIT_V(8); PG8_WAIT_L(0); PG8_BAR; PG8_MMA(1, 0, At, B0); PG8_MMA(1, 1, At, B1); PG8_BAR; PG8_SCHED;
;     ...
;         if constexpr (ALIGN_EPI) { if (wr == 0) PG8_BAR; }
	s_add_i32 s22, s58, s36
	v_lshl_add_u64 v[144:145], v[144:145], 0, s[8:9]
	s_mov_b32 m0, s22
	ds_read_b128 v[186:189], v151 offset:49152
	ds_read_b128 v[190:193], v151 offset:50176
	ds_read_b128 v[194:197], v151 offset:51200
	ds_read_b128 v[198:201], v151 offset:52224
	ds_read_b128 v[202:205], v151 offset:53248
	ds_read_b128 v[206:209], v151 offset:54272
	ds_read_b128 v[210:213], v151 offset:55296
	ds_read_b128 v[214:217], v151 offset:56320
	global_load_lds_dwordx4 v[144:145], off
	s_add_i32 m0, s22, 0x2000
	s_add_u32 s22, s26, 0xb0080
	v_lshl_add_u64 v[144:145], v[218:219], 0, s[8:9]
	s_addc_u32 s23, s27, 0
	s_add_i32 s26, s59, s36
	global_load_lds_dwordx4 v[144:145], off
	s_mov_b32 m0, s26
	v_lshl_add_u64 v[144:145], s[22:23], 0, v[130:131]
	global_load_lds_dwordx4 v[144:145], off
	s_add_i32 m0, s26, 0x2000
	v_lshl_add_u64 v[144:145], s[22:23], 0, v[134:135]
	global_load_lds_dwordx4 v[144:145], off
	s_mov_b32 m0, s42
	v_lshl_add_u64 v[144:145], v[220:221], 0, s[8:9]
	global_load_lds_dwordx4 v[144:145], off
	s_mov_b32 m0, s43
	v_lshl_add_u64 v[144:145], v[222:223], 0, s[8:9]
	global_load_lds_dwordx4 v[144:145], off
	s_waitcnt vmcnt(8)
	s_waitcnt lgkmcnt(0)
	s_barrier
	s_setprio 1
	s_waitcnt lgkmcnt(0)
	v_mfma_f32_16x16x32_bf16 v[60:63], v[152:155], v[186:189], v[60:63]
	v_mfma_f32_16x16x32_bf16 v[56:59], v[160:163], v[186:189], v[56:59]
	v_mfma_f32_16x16x32_bf16 v[52:55], v[152:155], v[194:197], v[52:55]
	v_mfma_f32_16x16x32_bf16 v[44:47], v[160:163], v[194:197], v[44:47]
	v_mfma_f32_16x16x32_bf16 v[36:39], v[152:155], v[202:205], v[36:39]
	v_mfma_f32_16x16x32_bf16 v[28:31], v[160:163], v[202:205], v[28:31]
	v_mfma_f32_16x16x32_bf16 v[20:23], v[152:155], v[210:213], v[20:23]
	v_mfma_f32_16x16x32_bf16 v[12:15], v[160:163], v[210:213], v[12:15]
	v_mfma_f32_16x16x32_bf16 v[60:63], v[156:159], v[190:193], v[60:63]
	v_mfma_f32_16x16x32_bf16 v[56:59], v[164:167], v[190:193], v[56:59]
	v_mfma_f32_16x16x32_bf16 v[52:55], v[156:159], v[198:201], v[52:55]
	v_mfma_f32_16x16x32_bf16 v[44:47], v[164:167], v[198:201], v[44:47]
	v_mfma_f32_16x16x32_bf16 v[36:39], v[156:159], v[206:209], v[36:39]
	v_mfma_f32_16x16x32_bf16 v[28:31], v[164:167], v[206:209], v[28:31]
	v_mfma_f32_16x16x32_bf16 v[20:23], v[156:159], v[214:217], v[20:23]
	v_mfma_f32_16x16x32_bf16 v[12:15], v[164:167], v[214:217], v[12:15]
	s_setprio 0
	s_setprio 1
	v_mfma_f32_16x16x32_bf16 v[48:51], v[168:171], v[186:189], v[48:51]
	v_mfma_f32_16x16x32_bf16 v[40:43], v[176:179], v[186:189], v[40:43]
	v_mfma_f32_16x16x32_bf16 v[32:35], v[168:171], v[194:197], v[32:35]
	v_mfma_f32_16x16x32_bf16 v[24:27], v[176:179], v[194:197], v[24:27]
	v_mfma_f32_16x16x32_bf16 v[16:19], v[168:171], v[202:205], v[16:19]
	v_mfma_f32_16x16x32_bf16 v[8:11], v[176:179], v[202:205], v[8:11]
	v_mfma_f32_16x16x32_bf16 v[4:7], v[168:171], v[210:213], v[4:7]
	v_mfma_f32_16x16x32_bf16 v[0:3], v[176:179], v[210:213], v[0:3]
	v_mfma_f32_16x16x32_bf16 v[48:51], v[172:175], v[190:193], v[48:51]
	v_mfma_f32_16x16x32_bf16 v[40:43], v[180:183], v[190:193], v[40:43]
	v_mfma_f32_16x16x32_bf16 v[32:35], v[172:175], v[198:201], v[32:35]
	v_mfma_f32_16x16x32_bf16 v[24:27], v[180:183], v[198:201], v[24:27]
	v_mfma_f32_16x16x32_bf16 v[16:19], v[172:175], v[206:209], v[16:19]
	v_mfma_f32_16x16x32_bf16 v[8:11], v[180:183], v[206:209], v[8:11]
	v_mfma_f32_16x16x32_bf16 v[4:7], v[172:175], v[214:217], v[4:7]
	v_mfma_f32_16x16x32_bf16 v[0:3], v[180:183], v[214:217], v[0:3]
	s_setprio 0
	s_barrier
	s_add_i32 s57, s57, 2
	s_add_u32 s55, s55, 0x100
	s_addc_u32 s56, s56, 0
	s_cmp_gt_u32 s57, 41
	s_mov_b64 s[22:23], s[24:25]
	s_cbranch_scc0 .LBB0_1089
	s_and_b64 vcc, exec, s[10:11]
	s_cbranch_vccz .LBB0_1092
	s_barrier

; #define PG8_STAGE(bufoff, gbase, voff) do { _Pragma("unroll") for (int _i = 0; _i < 2; ++_i) \
;         __builtin_amdgcn_global_load_lds((const unsigned*)((const char*)(gbase) + (voff)[_i]), (PG8_LAS unsigned*)(lds + (bufoff) + ldsw + _i * 8192), 16, 0, 0); } while (0)
; #define PG8_LDA(dst, b, h) do { _Pragma("unroll") for (int m = 0; m < 4; ++m) _Pragma("unroll") for (int k = 0; k < 2; ++k) dst[m][k] = *(const PG8_LAS bf16x8*)(lds + PG8_SA(b, h) + aoff + m * 2048 + k * 1024); } while (0)
; #define PG8_LDB(dst, b, h) do { _Pragma("unroll") for (int n = 0; n < 2; ++n) _Pragma("unroll") for (int k = 0; k < 2; ++k) dst[n][k] = *(const PG8_LAS bf16x8*)(lds + PG8_SB(b, h) + boff + n * 2048 + k * 1024); } while (0)
; #define PG8_MMA(ai, bj, At, Bt) do { __builtin_amdgcn_s_setprio(1); _Pragma("unroll") for (int m = 0; m < 4; ++m) _Pragma("unroll") for (int n = 0; n < 2; ++n) _Pragma("unroll") for (int k = 0; k < 2; ++k) \
;         acc[ai][bj][m][n] = __builtin_amdgcn_mfma_f32_16x16x32_bf16(Bt[n][k], At[m][k], acc[ai][bj][m][n], 0, 0, 0); __builtin_amdgcn_s_setprio(0); } while (0)
; #define PG8_WAIT_V(n) asm volatile("s_waitcnt vmcnt(" #n ")" ::: "memory")
; #define PG8_BAR __builtin_amdgcn_s_barrier()
; template <class Epi, class Sched, bool ALIGN_EPI = false, bool SP2 = false>
; __device__ __forceinline__ void gemm_phase(PG8_LAS unsigned char* lds, const Gemm g, const Sched& S, const Epi& E) {
;     ...
;         for (int t = 0; t < nt; t += 2) {
;             const bool last = (t == nt - 2);
;             const char* a1 = cA + (size_t)(t + 1) * kstep;
;             const char* a2 = last ? nA : cA + (size_t)(t + 2) * kstep; const char* b2 = last ? nB : cB + (size_t)(t + 2) * kstep;
;             const char* a3 = a2 + kstep; const char* b3 = b2 + kstep;
;             if (last && has_next) S.a_ready(nxt);
;             if constexpr (SP2) {
;             PG8_LDB(B0, 0, 0); PG8_LDB(B1, 0, 1); PG8_SCHED; PG8_LDA(At, 0, 0); PG8_STAGE(PG8_SA(1, 1), a1 + hstep, voffA);
;             PG8_WAIT_V(8); PG8_WAIT_L(0); PG8_BAR; PG8_MMA(0, 0, At, B0); PG8_MMA(0, 1, At, B1); PG8_BAR; PG8_SCHED;
;             PG8_LDA(At, 0, 1); PG8_STAGE(PG8_SB(0, 0), b2, voffB); PG8_STAGE(PG8_SB(0, 1), b2 + hstep, voffB); PG8_STAGE(PG8_SA(0, 0), a2, voffA);
;             PG8_WAIT_V(8); PG8_WAIT_L(0); PG8_BAR; PG8_MMA(1, 0, At, B0); PG8_MMA(1, 1, At, B1); PG8_BAR; PG8_SCHED;
.LBB0_1158:
	ds_read_b128 v[148:151], v145
	ds_read_b128 v[152:155], v145 offset:1024
	ds_read_b128 v[156:159], v145 offset:2048
	ds_read_b128 v[160:163], v145 offset:3072
	ds_read_b128 v[164:167], v146
	ds_read_b128 v[168:171], v146 offset:1024
	ds_read_b128 v[172:175], v146 offset:2048
	ds_read_b128 v[176:179], v146 offset:3072
	s_add_u32 s26, s24, 0x100
	s_addc_u32 s27, s25, 0
	s_cmp_eq_u32 s55, 40
	s_cselect_b32 s31, s21, s27
	s_cselect_b32 s30, s20, s26
	s_cselect_b32 s29, s23, s54
	s_cselect_b32 s28, s22, s53
	v_lshl_add_u64 v[140:141], s[24:25], 0, v[138:139]
	s_add_i32 m0, s36, 0xc000
	ds_read_b128 v[180:183], v147
	ds_read_b128 v[186:189], v147 offset:1024
	ds_read_b128 v[190:193], v147 offset:2048
	ds_read_b128 v[194:197], v147 offset:3072
	ds_read_b128 v[198:201], v147 offset:4096
	ds_read_b128 v[202:205], v147 offset:5120
	ds_read_b128 v[206:209], v147 offset:6144
	ds_read_b128 v[210:213], v147 offset:7168
	global_load_lds_dwordx4 v[140:141], off
	s_add_i32 m0, s36, 0xe000
	v_lshl_add_u64 v[140:141], s[24:25], 0, v[136:137]
	global_load_lds_dwordx4 v[140:141], off
	s_waitcnt vmcnt(8)
	s_waitcnt lgkmcnt(0)
	s_barrier
	s_setprio 1
	s_waitcnt lgkmcnt(0)
	v_mfma_f32_16x16x32_bf16 v[124:127], v[148:151], v[180:183], v[124:127]
	v_mfma_f32_16x16x32_bf16 v[120:123], v[156:159], v[180:183], v[120:123]
	v_mfma_f32_16x16x32_bf16 v[116:119], v[148:151], v[190:193], v[116:119]
	v_mfma_f32_16x16x32_bf16 v[108:111], v[156:159], v[190:193], v[108:111]
	v_mfma_f32_16x16x32_bf16 v[100:103], v[148:151], v[198:201], v[100:103]
	v_mfma_f32_16x16x32_bf16 v[92:95], v[156:159], v[198:201], v[92:95]
	v_mfma_f32_16x16x32_bf16 v[84:87], v[148:151], v[206:209], v[84:87]
	v_mfma_f32_16x16x32_bf16 v[76:79], v[156:159], v[206:209], v[76:79]
	v_mfma_f32_16x16x32_bf16 v[124:127], v[152:155], v[186:189], v[124:127]
	v_mfma_f32_16x16x32_bf16 v[120:123], v[160:163], v[186:189], v[120:123]
	v_mfma_f32_16x16x32_bf16 v[116:119], v[152:155], v[194:197], v[116:119]
	v_mfma_f32_16x16x32_bf16 v[108:111], v[160:163], v[194:197], v[108:111]
	v_mfma_f32_16x16x32_bf16 v[100:103], v[152:155], v[202:205], v[100:103]
	v_mfma_f32_16x16x32_bf16 v[92:95], v[160:163], v[202:205], v[92:95]
	v_mfma_f32_16x16x32_bf16 v[84:87], v[152:155], v[210:213], v[84:87]
	v_mfma_f32_16x16x32_bf16 v[76:79], v[160:163], v[210:213], v[76:79]
	s_setprio 0
	s_setprio 1
	v_mfma_f32_16x16x32_bf16 v[112:115], v[164:167], v[180:183], v[112:115]
	v_mfma_f32_16x16x32_bf16 v[104:107], v[172:175], v[180:183], v[104:107]
	v_mfma_f32_16x16x32_bf16 v[96:99], v[164:167], v[190:193], v[96:99]
	v_mfma_f32_16x16x32_bf16 v[88:91], v[172:175], v[190:193], v[88:91]
	v_mfma_f32_16x16x32_bf16 v[80:83], v[164:167], v[198:201], v[80:83]
	v_mfma_f32_16x16x32_bf16 v[72:75], v[172:175], v[198:201], v[72:75]
	v_mfma_f32_16x16x32_bf16 v[68:71], v[164:167], v[206:209], v[68:71]
	v_mfma_f32_16x16x32_bf16 v[64:67], v[172:175], v[206:209], v[64:67]
	v_mfma_f32_16x16x32_bf16 v[112:115], v[168:171], v[186:189], v[112:115]
	v_mfma_f32_16x16x32_bf16 v[104:107], v[176:179], v[186:189], v[104:107]
	v_mfma_f32_16x16x32_bf16 v[96:99], v[168:171], v[194:197], v[96:99]
	v_mfma_f32_16x16x32_bf16 v[88:91], v[176:179], v[194:197], v[88:91]
	v_mfma_f32_16x16x32_bf16 v[80:83], v[168:171], v[202:205], v[80:83]
	v_mfma_f32_16x16x32_bf16 v[72:75], v[176:179], v[202:205], v[72:75]
	v_mfma_f32_16x16x32_bf16 v[68:71], v[168:171], v[210:213], v[68:71]
	v_mfma_f32_16x16x32_bf16 v[64:67], v[176:179], v[210:213], v[64:67]
	s_setprio 0
	s_barrier
	s_add_i32 s24, s43, s35
	v_lshl_add_u64 v[140:141], s[28:29], 0, v[130:131]
	s_mov_b32 m0, s24
	ds_read_b128 v[180:183], v147 offset:16384
	ds_read_b128 v[186:189], v147 offset:17408
	ds_read_b128 v[190:193], v147 offset:18432
	ds_read_b128 v[194:197], v147 offset:19456
	ds_read_b128 v[198:201], v147 offset:20480
	ds_read_b128 v[202:205], v147 offset:21504
	ds_read_b128 v[206:209], v147 offset:22528
	ds_read_b128 v[210:213], v147 offset:23552
	global_load_lds_dwordx4 v[140:141], off
	s_add_i32 m0, s24, 0x2000
	s_add_u32 s24, s28, 0xb0000
	v_lshl_add_u64 v[214:215], s[28:29], 0, v[134:135]
	s_addc_u32 s25, s29, 0
	s_add_i32 s56, s93, s35
	global_load_lds_dwordx4 v[214:215], off
	v_lshl_add_u64 v[216:217], s[24:25], 0, v[130:131]
	s_mov_b32 m0, s56
	v_lshl_add_u64 v[218:219], s[30:31], 0, v[132:133]
	global_load_lds_dwordx4 v[216:217], off
	s_add_i32 m0, s56, 0x2000
	v_lshl_add_u64 v[216:217], s[24:25], 0, v[134:135]
	global_load_lds_dwordx4 v[216:217], off
	s_mov_b32 m0, s36
	v_lshl_add_u64 v[216:217], s[30:31], 0, v[128:129]
	global_load_lds_dwordx4 v[216:217], off
	s_mov_b32 m0, s37
	s_nop 0
	global_load_lds_dwordx4 v[218:219], off
	s_waitcnt vmcnt(8)
	s_waitcnt lgkmcnt(0)
	s_barrier
; #define PG8_STAGE(bufoff, gbase, voff) do { _Pragma("unroll") for (int _i = 0; _i < 2; ++_i) \
;         __builtin_amdgcn_global_load_lds((const unsigned*)((const char*)(gbase) + (voff)[_i]), (PG8_LAS unsigned*)(lds + (bufoff) + ldsw + _i * 8192), 16, 0, 0); } while (0)
; #define PG8_LDA(dst, b, h) do { _Pragma("unroll") for (int m = 0; m < 4; ++m) _Pragma("unroll") for (int k = 0; k < 2; ++k) dst[m][k] = *(const PG8_LAS bf16x8*)(lds + PG8_SA(b, h) + aoff + m * 2048 + k * 1024); } while (0)
; #define PG8_LDB(dst, b, h) do { _Pragma("unroll") for (int n = 0; n < 2; ++n) _Pragma("unroll") for (int k = 0; k < 2; ++k) dst[n][k] = *(const PG8_LAS bf16x8*)(lds + PG8_SB(b, h) + boff + n * 2048 + k * 1024); } while (0)
; #define PG8_MMA(ai, bj, At, Bt) do { __builtin_amdgcn_s_setprio(1); _Pragma("unroll") for (int m = 0; m < 4; ++m) _Pragma("unroll") for (int n = 0; n < 2; ++n) _Pragma("unroll") for (int k = 0; k < 2; ++k) \
;         acc[ai][bj][m][n] = __builtin_amdgcn_mfma_f32_16x16x32_bf16(Bt[n][k], At[m][k], acc[ai][bj][m][n], 0, 0, 0); __builtin_amdgcn_s_setprio(0); } while (0)
; #define PG8_WAIT_V(n) asm volatile("s_waitcnt vmcnt(" #n ")" ::: "memory")
; #define PG8_WAIT_L(n) asm volatile("s_waitcnt lgkmcnt(" #n ")" ::: "memory")
; #define PG8_BAR __builtin_amdgcn_s_barrier()
; #define PG8_SCHED __builtin_amdgcn_sched_barrier(0)
; template <class Epi, class Sched, bool ALIGN_EPI = false, bool SP2 = false>
; __device__ __forceinline__ void gemm_phase(PG8_LAS unsigned char* lds, const Gemm g, const Sched& S, const Epi& E) {
;     ...
;             PG8_WAIT_V(8); PG8_WAIT_L(0); PG8_BAR; PG8_MMA(1, 0, At, B0); PG8_MMA(1, 1, At, B1); PG8_BAR; PG8_SCHED;
;             PG8_LDB(B0, 1, 0); PG8_LDB(B1, 1, 1); PG8_SCHED; PG8_LDA(At, 1, 0); PG8_STAGE(PG8_SA(0, 1), a2 + hstep, voffA);
;             PG8_WAIT_V(8); PG8_WAIT_L(0); PG8_BAR; PG8_MMA(0, 0, At, B0); PG8_MMA(0, 1, At, B1); PG8_BAR; PG8_SCHED;
	s_setprio 1
	s_waitcnt lgkmcnt(0)
	v_mfma_f32_16x16x32_bf16 v[60:63], v[148:151], v[180:183], v[60:63]
	v_mfma_f32_16x16x32_bf16 v[56:59], v[156:159], v[180:183], v[56:59]
	v_mfma_f32_16x16x32_bf16 v[52:55], v[148:151], v[190:193], v[52:55]
	v_mfma_f32_16x16x32_bf16 v[44:47], v[156:159], v[190:193], v[44:47]
	v_mfma_f32_16x16x32_bf16 v[36:39], v[148:151], v[198:201], v[36:39]
	v_mfma_f32_16x16x32_bf16 v[28:31], v[156:159], v[198:201], v[28:31]
	v_mfma_f32_16x16x32_bf16 v[20:23], v[148:151], v[206:209], v[20:23]
	v_mfma_f32_16x16x32_bf16 v[12:15], v[156:159], v[206:209], v[12:15]
	v_mfma_f32_16x16x32_bf16 v[60:63], v[152:155], v[186:189], v[60:63]
	v_mfma_f32_16x16x32_bf16 v[56:59], v[160:163], v[186:189], v[56:59]
	v_mfma_f32_16x16x32_bf16 v[52:55], v[152:155], v[194:197], v[52:55]
	v_mfma_f32_16x16x32_bf16 v[44:47], v[160:163], v[194:197], v[44:47]
	v_mfma_f32_16x16x32_bf16 v[36:39], v[152:155], v[202:205], v[36:39]
	v_mfma_f32_16x16x32_bf16 v[28:31], v[160:163], v[202:205], v[28:31]
	v_mfma_f32_16x16x32_bf16 v[20:23], v[152:155], v[210:213], v[20:23]
	v_mfma_f32_16x16x32_bf16 v[12:15], v[160:163], v[210:213], v[12:15]
	s_setprio 0
	s_setprio 1
	v_mfma_f32_16x16x32_bf16 v[48:51], v[164:167], v[180:183], v[48:51]
	v_mfma_f32_16x16x32_bf16 v[40:43], v[172:175], v[180:183], v[40:43]
	v_mfma_f32_16x16x32_bf16 v[32:35], v[164:167], v[190:193], v[32:35]
	v_mfma_f32_16x16x32_bf16 v[24:27], v[172:175], v[190:193], v[24:27]
	v_mfma_f32_16x16x32_bf16 v[16:19], v[164:167], v[198:201], v[16:19]
	v_mfma_f32_16x16x32_bf16 v[8:11], v[172:175], v[198:201], v[8:11]
	v_mfma_f32_16x16x32_bf16 v[4:7], v[164:167], v[206:209], v[4:7]
	v_mfma_f32_16x16x32_bf16 v[0:3], v[172:175], v[206:209], v[0:3]
	v_mfma_f32_16x16x32_bf16 v[48:51], v[168:171], v[186:189], v[48:51]
	v_mfma_f32_16x16x32_bf16 v[40:43], v[176:179], v[186:189], v[40:43]
	v_mfma_f32_16x16x32_bf16 v[32:35], v[168:171], v[194:197], v[32:35]
	v_mfma_f32_16x16x32_bf16 v[24:27], v[176:179], v[194:197], v[24:27]
	v_mfma_f32_16x16x32_bf16 v[16:19], v[168:171], v[202:205], v[16:19]
	v_mfma_f32_16x16x32_bf16 v[8:11], v[176:179], v[202:205], v[8:11]
	v_mfma_f32_16x16x32_bf16 v[4:7], v[168:171], v[210:213], v[4:7]
	v_mfma_f32_16x16x32_bf16 v[0:3], v[176:179], v[210:213], v[0:3]
	s_setprio 0
	s_barrier
	s_add_i32 s56, 0, 0x18000
	s_add_i32 s57, 0, 0x1c000
	v_add_u32_e32 v160, s56, v143
	v_add_u32_e32 v176, s57, v143
	ds_read_b128 v[148:151], v160
	ds_read_b128 v[152:155], v160 offset:1024
	ds_read_b128 v[156:159], v160 offset:2048
	ds_read_b128 v[160:163], v160 offset:3072
	ds_read_b128 v[164:167], v176
	ds_read_b128 v[168:171], v176 offset:1024
	ds_read_b128 v[172:175], v176 offset:2048
	ds_read_b128 v[176:179], v176 offset:3072
	s_add_u32 s24, s30, 0xb0000
	s_addc_u32 s25, s31, 0
	s_mov_b32 m0, s38
	v_lshl_add_u64 v[220:221], s[24:25], 0, v[128:129]
	ds_read_b128 v[180:183], v147 offset:32768
	ds_read_b128 v[186:189], v147 offset:33792
	ds_read_b128 v[190:193], v147 offset:34816
	ds_read_b128 v[194:197], v147 offset:35840
	ds_read_b128 v[198:201], v147 offset:36864
	ds_read_b128 v[202:205], v147 offset:37888
	ds_read_b128 v[206:209], v147 offset:38912
	ds_read_b128 v[210:213], v147 offset:39936
	global_load_lds_dwordx4 v[220:221], off
	s_mov_b32 m0, s39
	v_lshl_add_u64 v[220:221], s[24:25], 0, v[132:133]
	global_load_lds_dwordx4 v[220:221], off
	s_waitcnt vmcnt(8)
	s_waitcnt lgkmcnt(0)
	s_barrier
	s_setprio 1
	s_waitcnt lgkmcnt(0)
	v_mfma_f32_16x16x32_bf16 v[124:127], v[148:151], v[180:183], v[124:127]
	v_mfma_f32_16x16x32_bf16 v[120:123], v[156:159], v[180:183], v[120:123]
	v_mfma_f32_16x16x32_bf16 v[116:119], v[148:151], v[190:193], v[116:119]
	v_mfma_f32_16x16x32_bf16 v[108:111], v[156:159], v[190:193], v[108:111]
	v_mfma_f32_16x16x32_bf16 v[100:103], v[148:151], v[198:201], v[100:103]
	v_mfma_f32_16x16x32_bf16 v[92:95], v[156:159], v[198:201], v[92:95]
	v_mfma_f32_16x16x32_bf16 v[84:87], v[148:151], v[206:209], v[84:87]
	v_mfma_f32_16x16x32_bf16 v[76:79], v[156:159], v[206:209], v[76:79]
	v_mfma_f32_16x16x32_bf16 v[124:127], v[152:155], v[186:189], v[124:127]
	v_mfma_f32_16x16x32_bf16 v[120:123], v[160:163], v[186:189], v[120:123]
	v_mfma_f32_16x16x32_bf16 v[116:119], v[152:155], v[194:197], v[116:119]
	v_mfma_f32_16x16x32_bf16 v[108:111], v[160:163], v[194:197], v[108:111]
	v_mfma_f32_16x16x32_bf16 v[100:103], v[152:155], v[202:205], v[100:103]
	v_mfma_f32_16x16x32_bf16 v[92:95], v[160:163], v[202:205], v[92:95]
	v_mfma_f32_16x16x32_bf16 v[84:87], v[152:155], v[210:213], v[84:87]
	v_mfma_f32_16x16x32_bf16 v[76:79], v[160:163], v[210:213], v[76:79]
	s_setprio 0
	s_setprio 1
	v_mfma_f32_16x16x32_bf16 v[112:115], v[164:167], v[180:183], v[112:115]
	v_mfma_f32_16x16x32_bf16 v[104:107], v[172:175], v[180:183], v[104:107]
	v_mfma_f32_16x16x32_bf16 v[96:99], v[164:167], v[190:193], v[96:99]
	v_mfma_f32_16x16x32_bf16 v[88:91], v[172:175], v[190:193], v[88:91]
	v_mfma_f32_16x16x32_bf16 v[80:83], v[164:167], v[198:201], v[80:83]
	v_mfma_f32_16x16x32_bf16 v[72:75], v[172:175], v[198:201], v[72:75]
	v_mfma_f32_16x16x32_bf16 v[68:71], v[164:167], v[206:209], v[68:71]
	v_mfma_f32_16x16x32_bf16 v[64:67], v[172:175], v[206:209], v[64:67]
	v_mfma_f32_16x16x32_bf16 v[112:115], v[168:171], v[186:189], v[112:115]
	v_mfma_f32_16x16x32_bf16 v[104:107], v[176:179], v[186:189], v[104:107]
	v_mfma_f32_16x16x32_bf16 v[96:99], v[168:171], v[194:197], v[96:99]
	v_mfma_f32_16x16x32_bf16 v[88:91], v[176:179], v[194:197], v[88:91]
	v_mfma_f32_16x16x32_bf16 v[80:83], v[168:171], v[202:205], v[80:83]
	v_mfma_f32_16x16x32_bf16 v[72:75], v[176:179], v[202:205], v[72:75]
	v_mfma_f32_16x16x32_bf16 v[68:71], v[168:171], v[210:213], v[68:71]
	v_mfma_f32_16x16x32_bf16 v[64:67], v[176:179], v[210:213], v[64:67]
	s_setprio 0
	s_barrier
; #define PG8_STAGE(bufoff, gbase, voff) do { _Pragma("unroll") for (int _i = 0; _i < 2; ++_i) \
;         __builtin_amdgcn_global_load_lds((const unsigned*)((const char*)(gbase) + (voff)[_i]), (PG8_LAS unsigned*)(lds + (bufoff) + ldsw + _i * 8192), 16, 0, 0); } while (0)
; #define PG8_LDA(dst, b, h) do { _Pragma("unroll") for (int m = 0; m < 4; ++m) _Pragma("unroll") for (int k = 0; k < 2; ++k) dst[m][k] = *(const PG8_LAS bf16x8*)(lds + PG8_SA(b, h) + aoff + m * 2048 + k * 1024); } while (0)
; #define PG8_MMA(ai, bj, At, Bt) do { __builtin_amdgcn_s_setprio(1); _Pragma("unroll") for (int m = 0; m < 4; ++m) _Pragma("unroll") for (int n = 0; n < 2; ++n) _Pragma("unroll") for (int k = 0; k < 2; ++k) \
;         acc[ai][bj][m][n] = __builtin_amdgcn_mfma_f32_16x16x32_bf16(Bt[n][k], At[m][k], acc[ai][bj][m][n], 0, 0, 0); __builtin_amdgcn_s_setprio(0); } while (0)
; #define PG8_WAIT_V(n) asm volatile("s_waitcnt vmcnt(" #n ")" ::: "memory")
; #define PG8_WAIT_L(n) asm volatile("s_waitcnt lgkmcnt(" #n ")" ::: "memory")
; #define PG8_BAR __builtin_amdgcn_s_barrier()
; #define PG8_SCHED __builtin_amdgcn_sched_barrier(0)
; template <class Epi, class Sched, bool ALIGN_EPI = false, bool SP2 = false>
; __device__ __forceinline__ void gemm_phase(PG8_LAS unsigned char* lds, const Gemm g, const Sched& S, const Epi& E) {
;     ...
;             PG8_LDA(At, 1, 1); PG8_STAGE(PG8_SB(1, 0), b3, voffB); PG8_STAGE(PG8_SB(1, 1), b3 + hstep, voffB); PG8_STAGE(PG8_SA(1, 0), a3, voffA);
;             PG8_WAIT_V(8); PG8_WAIT_L(0); PG8_BAR; PG8_MMA(1, 0, At, B0); PG8_MMA(1, 1, At, B1); PG8_BAR; PG8_SCHED;
;     ...
;         if constexpr (ALIGN_EPI) { if (wr == 0) PG8_BAR; }
	s_add_i32 s24, s56, s35
	v_lshl_add_u64 v[140:141], v[140:141], 0, s[8:9]
	s_mov_b32 m0, s24
	ds_read_b128 v[180:183], v147 offset:49152
	ds_read_b128 v[186:189], v147 offset:50176
	ds_read_b128 v[190:193], v147 offset:51200
	ds_read_b128 v[194:197], v147 offset:52224
	ds_read_b128 v[198:201], v147 offset:53248
	ds_read_b128 v[202:205], v147 offset:54272
	ds_read_b128 v[206:209], v147 offset:55296
	ds_read_b128 v[210:213], v147 offset:56320
	global_load_lds_dwordx4 v[140:141], off
	s_add_i32 m0, s24, 0x2000
	s_add_u32 s24, s28, 0xb0080
	v_lshl_add_u64 v[140:141], v[214:215], 0, s[8:9]
	s_addc_u32 s25, s29, 0
	s_add_i32 s28, s57, s35
	global_load_lds_dwordx4 v[140:141], off
	s_mov_b32 m0, s28
	v_lshl_add_u64 v[140:141], s[24:25], 0, v[130:131]
	global_load_lds_dwordx4 v[140:141], off
	s_add_i32 m0, s28, 0x2000
	v_lshl_add_u64 v[140:141], s[24:25], 0, v[134:135]
	global_load_lds_dwordx4 v[140:141], off
	s_mov_b32 m0, s40
	v_lshl_add_u64 v[140:141], v[216:217], 0, s[8:9]
	global_load_lds_dwordx4 v[140:141], off
	s_mov_b32 m0, s41
	v_lshl_add_u64 v[140:141], v[218:219], 0, s[8:9]
	global_load_lds_dwordx4 v[140:141], off
	s_waitcnt vmcnt(8)
	s_waitcnt lgkmcnt(0)
	s_barrier
	s_setprio 1
	s_waitcnt lgkmcnt(0)
	v_mfma_f32_16x16x32_bf16 v[60:63], v[148:151], v[180:183], v[60:63]
	v_mfma_f32_16x16x32_bf16 v[56:59], v[156:159], v[180:183], v[56:59]
	v_mfma_f32_16x16x32_bf16 v[52:55], v[148:151], v[190:193], v[52:55]
	v_mfma_f32_16x16x32_bf16 v[44:47], v[156:159], v[190:193], v[44:47]
	v_mfma_f32_16x16x32_bf16 v[36:39], v[148:151], v[198:201], v[36:39]
	v_mfma_f32_16x16x32_bf16 v[28:31], v[156:159], v[198:201], v[28:31]
	v_mfma_f32_16x16x32_bf16 v[20:23], v[148:151], v[206:209], v[20:23]
	v_mfma_f32_16x16x32_bf16 v[12:15], v[156:159], v[206:209], v[12:15]
	v_mfma_f32_16x16x32_bf16 v[60:63], v[152:155], v[186:189], v[60:63]
	v_mfma_f32_16x16x32_bf16 v[56:59], v[160:163], v[186:189], v[56:59]
	v_mfma_f32_16x16x32_bf16 v[52:55], v[152:155], v[194:197], v[52:55]
	v_mfma_f32_16x16x32_bf16 v[44:47], v[160:163], v[194:197], v[44:47]
	v_mfma_f32_16x16x32_bf16 v[36:39], v[152:155], v[202:205], v[36:39]
	v_mfma_f32_16x16x32_bf16 v[28:31], v[160:163], v[202:205], v[28:31]
	v_mfma_f32_16x16x32_bf16 v[20:23], v[152:155], v[210:213], v[20:23]
	v_mfma_f32_16x16x32_bf16 v[12:15], v[160:163], v[210:213], v[12:15]
	s_setprio 0
	s_setprio 1
	v_mfma_f32_16x16x32_bf16 v[48:51], v[164:167], v[180:183], v[48:51]
	v_mfma_f32_16x16x32_bf16 v[40:43], v[172:175], v[180:183], v[40:43]
	v_mfma_f32_16x16x32_bf16 v[32:35], v[164:167], v[190:193], v[32:35]
	v_mfma_f32_16x16x32_bf16 v[24:27], v[172:175], v[190:193], v[24:27]
	v_mfma_f32_16x16x32_bf16 v[16:19], v[164:167], v[198:201], v[16:19]
	v_mfma_f32_16x16x32_bf16 v[8:11], v[172:175], v[198:201], v[8:11]
	v_mfma_f32_16x16x32_bf16 v[4:7], v[164:167], v[206:209], v[4:7]
	v_mfma_f32_16x16x32_bf16 v[0:3], v[172:175], v[206:209], v[0:3]
	v_mfma_f32_16x16x32_bf16 v[48:51], v[168:171], v[186:189], v[48:51]
	v_mfma_f32_16x16x32_bf16 v[40:43], v[176:179], v[186:189], v[40:43]
	v_mfma_f32_16x16x32_bf16 v[32:35], v[168:171], v[194:197], v[32:35]
	v_mfma_f32_16x16x32_bf16 v[24:27], v[176:179], v[194:197], v[24:27]
	v_mfma_f32_16x16x32_bf16 v[16:19], v[168:171], v[202:205], v[16:19]
	v_mfma_f32_16x16x32_bf16 v[8:11], v[176:179], v[202:205], v[8:11]
	v_mfma_f32_16x16x32_bf16 v[4:7], v[168:171], v[210:213], v[4:7]
	v_mfma_f32_16x16x32_bf16 v[0:3], v[176:179], v[210:213], v[0:3]
	s_setprio 0
	s_barrier
	s_add_i32 s55, s55, 2
	s_add_u32 s53, s53, 0x100
	s_addc_u32 s54, s54, 0
	s_cmp_gt_u32 s55, 41
	s_mov_b64 s[24:25], s[26:27]
	s_cbranch_scc0 .LBB0_1158
	s_and_b64 vcc, exec, s[10:11]
	s_cbranch_vccz .LBB0_1161
	s_barrier
